# v69 + GEMM K-loops: LDS-DMA loads in SGPR-base form (vOff, s[base], offset folded out of M0) instead of a v_lshl_add_u64 64-bit VGPR address per load (158 of 160 loads; 16 fewer VALU per K-iteration p
# baseline (speedup 1.0000x reference)
; #define PG8_STAGE(bufoff, gbase, voff) do { _Pragma("unroll") for (int _i = 0; _i < 2; ++_i) \
;         __builtin_amdgcn_global_load_lds((const unsigned*)((const char*)(gbase) + (voff)[_i]), (LAS unsigned*)(lds + (bufoff) + ldsw + _i * 8192), 16, 0, 0); } while (0)
; #define PG8_LDA(dst, b, h) do { _Pragma("unroll") for (int m = 0; m < 4; ++m) _Pragma("unroll") for (int k = 0; k < 2; ++k) dst[m][k] = *(const LAS bf16x8*)(lds + PG8_SA(b, h) + aoff + m * 2048 + k * 1024); } while (0)
; #define PG8_LDB(dst, b, h) do { _Pragma("unroll") for (int n = 0; n < 2; ++n) _Pragma("unroll") for (int k = 0; k < 2; ++k) dst[n][k] = *(const LAS bf16x8*)(lds + PG8_SB(b, h) + boff + n * 2048 + k * 1024); } while (0)
; #define PG8_SCHED __builtin_amdgcn_sched_barrier(0)
; template <class Epi, bool ALIGN_EPI = PG8_ALIGN, bool SP2 = PG8_SP2>
; __device__ __forceinline__ void gemm_phase(LAS uchar* lds, const Gemm g, const StaticOrder& S, const Epi& E) {
;     ...
;         for (int t = tb; t < tb + tblk; t += 2) {
;             const bool last = (t == nt - 2);
;             const char* a1 = cA + (size_t)(t + 1) * kstep;
;             const char* a2 = last ? nA : cA + (size_t)(t + 2) * kstep; const char* b2 = last ? nB : cB + (size_t)(t + 2) * kstep;
;             const char* a3 = a2 + kstep; const char* b3 = b2 + kstep;
;             if constexpr (SP2) {
;             PG8_LDB(B0, 0, 0); PG8_LDB(B1, 0, 1); PG8_SCHED; PG8_LDA(At, 0, 0); PG8_STAGE(PG8_SA(1, 1), a1 + hstepA, voffA);
.LBB0_344:
	s_add_u32 s38, s4, 0x100
	s_addc_u32 s39, s5, 0
	s_mov_b32 s40, -2
	s_add_u32 s18, s16, 0x100
	s_addc_u32 s19, s17, 0
	s_add_i32 s41, 0, 0x10000
	s_cmp_eq_u32 s40, 12
	s_cselect_b32 s21, s7, s19
	s_cselect_b32 s20, s6, s18
	v_add_u32_e32 v168, s41, v139
	s_cselect_b32 s5, s15, s39
	s_cselect_b32 s4, s14, s38
	s_add_i32 s42, 0, 0x14000
	ds_read_b128 v[164:167], v168
	ds_read_b128 v[172:175], v168 offset:1024
	ds_read_b128 v[176:179], v168 offset:2048
	ds_read_b128 v[184:187], v168 offset:3072
	v_add_u32_e32 v168, s42, v139
	ds_read_b128 v[188:191], v168
	ds_read_b128 v[192:195], v168 offset:1024
	ds_read_b128 v[196:199], v168 offset:2048
	ds_read_b128 v[200:203], v168 offset:3072
	s_add_i32 m0, s25, 0xc000
	ds_read_b128 v[204:207], v171
	ds_read_b128 v[208:211], v171 offset:1024
	ds_read_b128 v[212:215], v171 offset:2048
	ds_read_b128 v[216:219], v171 offset:3072
	ds_read_b128 v[220:223], v171 offset:4096
	ds_read_b128 v[224:227], v171 offset:5120
	ds_read_b128 v[228:231], v171 offset:6144
	ds_read_b128 v[232:235], v171 offset:7168
	global_load_lds_dwordx4 v160, s[16:17]
	s_add_i32 m0, s25, 0xe000
	s_nop 0
	global_load_lds_dwordx4 v162, s[16:17]
	s_cmp_eq_u32 s97, 1
	s_cbranch_scc0 .Lrw_std_345_0_pl
	s_waitcnt vmcnt(24)
	s_branch .Lrw_done_345_0_pl

; #define PG8_STAGE(bufoff, gbase, voff) do { _Pragma("unroll") for (int _i = 0; _i < 2; ++_i) \
;         __builtin_amdgcn_global_load_lds((const unsigned*)((const char*)(gbase) + (voff)[_i]), (LAS unsigned*)(lds + (bufoff) + ldsw + _i * 8192), 16, 0, 0); } while (0)
; #define PG8_LDA(dst, b, h) do { _Pragma("unroll") for (int m = 0; m < 4; ++m) _Pragma("unroll") for (int k = 0; k < 2; ++k) dst[m][k] = *(const LAS bf16x8*)(lds + PG8_SA(b, h) + aoff + m * 2048 + k * 1024); } while (0)
; #define PG8_LDB(dst, b, h) do { _Pragma("unroll") for (int n = 0; n < 2; ++n) _Pragma("unroll") for (int k = 0; k < 2; ++k) dst[n][k] = *(const LAS bf16x8*)(lds + PG8_SB(b, h) + boff + n * 2048 + k * 1024); } while (0)
; #define PG8_MMA(ai, bj, At, Bt) do { __builtin_amdgcn_s_setprio(1); _Pragma("unroll") for (int m = 0; m < 4; ++m) _Pragma("unroll") for (int n = 0; n < 2; ++n) _Pragma("unroll") for (int k = 0; k < 2; ++k) \
;         acc[ai][bj][m][n] = __builtin_amdgcn_mfma_f32_16x16x32_bf16(Bt[n][k], At[m][k], acc[ai][bj][m][n], 0, 0, 0); __builtin_amdgcn_s_setprio(0); } while (0)
; #define PG8_WAIT_V(n) asm volatile("s_waitcnt vmcnt(" #n ")" ::: "memory")
; #define PG8_WAIT_L(n) asm volatile("s_waitcnt lgkmcnt(" #n ")" ::: "memory")
; #define PG8_BAR __builtin_amdgcn_s_barrier()
; #define PG8_SCHED __builtin_amdgcn_sched_barrier(0)
; template <class Epi, bool ALIGN_EPI = PG8_ALIGN, bool SP2 = PG8_SP2>
; __device__ __forceinline__ void gemm_phase(LAS uchar* lds, const Gemm g, const StaticOrder& S, const Epi& E) {
;     ...
;             PG8_LDB(B0, 0, 0); PG8_LDB(B1, 0, 1); PG8_SCHED; PG8_LDA(At, 0, 0); PG8_STAGE(PG8_SA(1, 1), a1 + hstepA, voffA);
;             PG8_WAIT_V(8); PG8_WAIT_L(0); PG8_BAR; PG8_MMA(0, 0, At, B0); PG8_MMA(0, 1, At, B1); PG8_BAR; PG8_SCHED;
;             PG8_LDA(At, 0, 1); PG8_STAGE(PG8_SB(0, 0), b2, voffB); PG8_STAGE(PG8_SB(0, 1), b2 + hstepB, voffB); PG8_STAGE(PG8_SA(0, 0), a2, voffA);
.Lrw_done_345_0_pl:
	s_waitcnt lgkmcnt(0)
	s_setprio 1
	s_barrier
	v_mfma_f32_16x16x32_bf16 v[126:129], v[164:167], v[204:207], 0
	v_mfma_f32_16x16x32_bf16 v[122:125], v[176:179], v[204:207], 0
	v_mfma_f32_16x16x32_bf16 v[118:121], v[164:167], v[212:215], 0
	v_mfma_f32_16x16x32_bf16 v[110:113], v[176:179], v[212:215], 0
	v_mfma_f32_16x16x32_bf16 v[102:105], v[164:167], v[220:223], 0
	v_mfma_f32_16x16x32_bf16 v[94:97], v[176:179], v[220:223], 0
	v_mfma_f32_16x16x32_bf16 v[86:89], v[164:167], v[228:231], 0
	v_mfma_f32_16x16x32_bf16 v[78:81], v[176:179], v[228:231], 0
	v_mfma_f32_16x16x32_bf16 v[126:129], v[172:175], v[208:211], v[126:129]
	v_mfma_f32_16x16x32_bf16 v[122:125], v[184:187], v[208:211], v[122:125]
	v_mfma_f32_16x16x32_bf16 v[118:121], v[172:175], v[216:219], v[118:121]
	v_mfma_f32_16x16x32_bf16 v[110:113], v[184:187], v[216:219], v[110:113]
	v_mfma_f32_16x16x32_bf16 v[102:105], v[172:175], v[224:227], v[102:105]
	v_mfma_f32_16x16x32_bf16 v[94:97], v[184:187], v[224:227], v[94:97]
	v_mfma_f32_16x16x32_bf16 v[86:89], v[172:175], v[232:235], v[86:89]
	v_mfma_f32_16x16x32_bf16 v[78:81], v[184:187], v[232:235], v[78:81]
	v_mfma_f32_16x16x32_bf16 v[114:117], v[188:191], v[204:207], 0
	v_mfma_f32_16x16x32_bf16 v[106:109], v[196:199], v[204:207], 0
	v_mfma_f32_16x16x32_bf16 v[98:101], v[188:191], v[212:215], 0
	v_mfma_f32_16x16x32_bf16 v[90:93], v[196:199], v[212:215], 0
	v_mfma_f32_16x16x32_bf16 v[82:85], v[188:191], v[220:223], 0
	v_mfma_f32_16x16x32_bf16 v[74:77], v[196:199], v[220:223], 0
	v_mfma_f32_16x16x32_bf16 v[70:73], v[188:191], v[228:231], 0
	v_mfma_f32_16x16x32_bf16 v[66:69], v[196:199], v[228:231], 0
	v_mfma_f32_16x16x32_bf16 v[114:117], v[192:195], v[208:211], v[114:117]
	v_mfma_f32_16x16x32_bf16 v[106:109], v[200:203], v[208:211], v[106:109]
	v_mfma_f32_16x16x32_bf16 v[98:101], v[192:195], v[216:219], v[98:101]
	v_mfma_f32_16x16x32_bf16 v[90:93], v[200:203], v[216:219], v[90:93]
	v_mfma_f32_16x16x32_bf16 v[82:85], v[192:195], v[224:227], v[82:85]
	v_mfma_f32_16x16x32_bf16 v[74:77], v[200:203], v[224:227], v[74:77]
	v_mfma_f32_16x16x32_bf16 v[70:73], v[192:195], v[232:235], v[70:73]
	v_mfma_f32_16x16x32_bf16 v[66:69], v[200:203], v[232:235], v[66:69]
	s_barrier
	s_setprio 0
	s_add_i32 s16, s41, s23
	s_mov_b32 m0, s16
	ds_read_b128 v[204:207], v171 offset:16384
	ds_read_b128 v[208:211], v171 offset:17408
	ds_read_b128 v[212:215], v171 offset:18432
	ds_read_b128 v[216:219], v171 offset:19456
	ds_read_b128 v[220:223], v171 offset:20480
	ds_read_b128 v[224:227], v171 offset:21504
	ds_read_b128 v[228:231], v171 offset:22528
	ds_read_b128 v[232:235], v171 offset:23552
	global_load_lds_dwordx4 v134, s[4:5]
	s_add_i32 m0, s16, 0x2000
	s_add_u32 s16, s4, 0x44000
	v_lshl_add_u64 v[180:181], s[4:5], 0, v[130:131]
	s_addc_u32 s17, s5, 0
	s_add_i32 s41, s42, s23
	global_load_lds_dwordx4 v130, s[4:5]
	s_mov_b32 m0, s41
	s_nop 0
	global_load_lds_dwordx4 v134, s[16:17]
	s_add_i32 m0, s41, 0x2000
	s_nop 0
	global_load_lds_dwordx4 v130, s[16:17]
	s_mov_b32 m0, s25
	s_nop 0
	global_load_lds_dwordx4 v156, s[20:21]
	s_mov_b32 m0, s26
	s_nop 0
	global_load_lds_dwordx4 v132, s[20:21]
	s_cmp_eq_u32 s97, 1
	s_cbranch_scc0 .Lrw_std_345_1_pl
	s_waitcnt vmcnt(24)
	s_branch .Lrw_done_345_1_pl

; #define PG8_STAGE(bufoff, gbase, voff) do { _Pragma("unroll") for (int _i = 0; _i < 2; ++_i) \
;         __builtin_amdgcn_global_load_lds((const unsigned*)((const char*)(gbase) + (voff)[_i]), (LAS unsigned*)(lds + (bufoff) + ldsw + _i * 8192), 16, 0, 0); } while (0)
; #define PG8_LDA(dst, b, h) do { _Pragma("unroll") for (int m = 0; m < 4; ++m) _Pragma("unroll") for (int k = 0; k < 2; ++k) dst[m][k] = *(const LAS bf16x8*)(lds + PG8_SA(b, h) + aoff + m * 2048 + k * 1024); } while (0)
; #define PG8_LDB(dst, b, h) do { _Pragma("unroll") for (int n = 0; n < 2; ++n) _Pragma("unroll") for (int k = 0; k < 2; ++k) dst[n][k] = *(const LAS bf16x8*)(lds + PG8_SB(b, h) + boff + n * 2048 + k * 1024); } while (0)
; #define PG8_MMA(ai, bj, At, Bt) do { __builtin_amdgcn_s_setprio(1); _Pragma("unroll") for (int m = 0; m < 4; ++m) _Pragma("unroll") for (int n = 0; n < 2; ++n) _Pragma("unroll") for (int k = 0; k < 2; ++k) \
;         acc[ai][bj][m][n] = __builtin_amdgcn_mfma_f32_16x16x32_bf16(Bt[n][k], At[m][k], acc[ai][bj][m][n], 0, 0, 0); __builtin_amdgcn_s_setprio(0); } while (0)
; #define PG8_WAIT_V(n) asm volatile("s_waitcnt vmcnt(" #n ")" ::: "memory")
; #define PG8_WAIT_L(n) asm volatile("s_waitcnt lgkmcnt(" #n ")" ::: "memory")
; #define PG8_BAR __builtin_amdgcn_s_barrier()
; #define PG8_SCHED __builtin_amdgcn_sched_barrier(0)
; template <class Epi, bool ALIGN_EPI = PG8_ALIGN, bool SP2 = PG8_SP2>
; __device__ __forceinline__ void gemm_phase(LAS uchar* lds, const Gemm g, const StaticOrder& S, const Epi& E) {
;     ...
;             PG8_LDA(At, 0, 1); PG8_STAGE(PG8_SB(0, 0), b2, voffB); PG8_STAGE(PG8_SB(0, 1), b2 + hstepB, voffB); PG8_STAGE(PG8_SA(0, 0), a2, voffA);
;             PG8_WAIT_V(8); PG8_WAIT_L(0); PG8_BAR; PG8_MMA(1, 0, At, B0); PG8_MMA(1, 1, At, B1); PG8_BAR; PG8_SCHED;
;             PG8_LDB(B0, 1, 0); PG8_LDB(B1, 1, 1); PG8_SCHED; PG8_LDA(At, 1, 0); PG8_STAGE(PG8_SA(0, 1), a2 + hstepA, voffA);
;             PG8_WAIT_V(8); PG8_WAIT_L(0); PG8_BAR; PG8_MMA(0, 0, At, B0); PG8_MMA(0, 1, At, B1); PG8_BAR; PG8_SCHED;
.Lrw_done_345_1_pl:
	s_waitcnt lgkmcnt(0)
	s_setprio 1
	s_barrier
	v_mfma_f32_16x16x32_bf16 v[62:65], v[164:167], v[204:207], 0
	v_mfma_f32_16x16x32_bf16 v[58:61], v[176:179], v[204:207], 0
	v_mfma_f32_16x16x32_bf16 v[54:57], v[164:167], v[212:215], 0
	v_mfma_f32_16x16x32_bf16 v[46:49], v[176:179], v[212:215], 0
	v_mfma_f32_16x16x32_bf16 v[38:41], v[164:167], v[220:223], 0
	v_mfma_f32_16x16x32_bf16 v[30:33], v[176:179], v[220:223], 0
	v_mfma_f32_16x16x32_bf16 v[22:25], v[164:167], v[228:231], 0
	v_mfma_f32_16x16x32_bf16 v[14:17], v[176:179], v[228:231], 0
	v_mfma_f32_16x16x32_bf16 v[62:65], v[172:175], v[208:211], v[62:65]
	v_mfma_f32_16x16x32_bf16 v[58:61], v[184:187], v[208:211], v[58:61]
	v_mfma_f32_16x16x32_bf16 v[54:57], v[172:175], v[216:219], v[54:57]
	v_mfma_f32_16x16x32_bf16 v[46:49], v[184:187], v[216:219], v[46:49]
	v_mfma_f32_16x16x32_bf16 v[38:41], v[172:175], v[224:227], v[38:41]
	v_mfma_f32_16x16x32_bf16 v[30:33], v[184:187], v[224:227], v[30:33]
	v_mfma_f32_16x16x32_bf16 v[22:25], v[172:175], v[232:235], v[22:25]
	v_mfma_f32_16x16x32_bf16 v[14:17], v[184:187], v[232:235], v[14:17]
	v_mfma_f32_16x16x32_bf16 v[50:53], v[188:191], v[204:207], 0
	v_mfma_f32_16x16x32_bf16 v[42:45], v[196:199], v[204:207], 0
	v_mfma_f32_16x16x32_bf16 v[34:37], v[188:191], v[212:215], 0
	v_mfma_f32_16x16x32_bf16 v[26:29], v[196:199], v[212:215], 0
	v_mfma_f32_16x16x32_bf16 v[18:21], v[188:191], v[220:223], 0
	v_mfma_f32_16x16x32_bf16 v[10:13], v[196:199], v[220:223], 0
	v_mfma_f32_16x16x32_bf16 v[6:9], v[188:191], v[228:231], 0
	v_mfma_f32_16x16x32_bf16 v[2:5], v[196:199], v[228:231], 0
	v_mfma_f32_16x16x32_bf16 v[50:53], v[192:195], v[208:211], v[50:53]
	v_mfma_f32_16x16x32_bf16 v[42:45], v[200:203], v[208:211], v[42:45]
	v_mfma_f32_16x16x32_bf16 v[34:37], v[192:195], v[216:219], v[34:37]
	v_mfma_f32_16x16x32_bf16 v[26:29], v[200:203], v[216:219], v[26:29]
	v_mfma_f32_16x16x32_bf16 v[18:21], v[192:195], v[224:227], v[18:21]
	v_mfma_f32_16x16x32_bf16 v[10:13], v[200:203], v[224:227], v[10:13]
	v_mfma_f32_16x16x32_bf16 v[6:9], v[192:195], v[232:235], v[6:9]
	v_mfma_f32_16x16x32_bf16 v[2:5], v[200:203], v[232:235], v[2:5]
	s_barrier
	s_setprio 0
	s_add_i32 s41, 0, 0x18000
	s_add_i32 s42, 0, 0x1c000
	v_add_u32_e32 v184, s41, v139
	v_add_u32_e32 v200, s42, v139
	ds_read_b128 v[164:167], v184
	ds_read_b128 v[172:175], v184 offset:1024
	ds_read_b128 v[176:179], v184 offset:2048
	ds_read_b128 v[184:187], v184 offset:3072
	ds_read_b128 v[188:191], v200
	ds_read_b128 v[192:195], v200 offset:1024
	ds_read_b128 v[196:199], v200 offset:2048
	ds_read_b128 v[200:203], v200 offset:3072
	s_add_u32 s16, s20, 0x44000
	s_addc_u32 s17, s21, 0
	s_mov_b32 m0, s27
	ds_read_b128 v[204:207], v171 offset:32768
	ds_read_b128 v[208:211], v171 offset:33792
	ds_read_b128 v[212:215], v171 offset:34816
	ds_read_b128 v[216:219], v171 offset:35840
	ds_read_b128 v[220:223], v171 offset:36864
	ds_read_b128 v[224:227], v171 offset:37888
	ds_read_b128 v[228:231], v171 offset:38912
	ds_read_b128 v[232:235], v171 offset:39936
	global_load_lds_dwordx4 v156, s[16:17]
	s_mov_b32 m0, s28
	s_nop 0
	global_load_lds_dwordx4 v132, s[16:17]
	s_waitcnt vmcnt(8)
	s_waitcnt lgkmcnt(0)
	s_setprio 1
	s_barrier
	v_mfma_f32_16x16x32_bf16 v[126:129], v[164:167], v[204:207], v[126:129]
	v_mfma_f32_16x16x32_bf16 v[122:125], v[176:179], v[204:207], v[122:125]
	v_mfma_f32_16x16x32_bf16 v[118:121], v[164:167], v[212:215], v[118:121]
	v_mfma_f32_16x16x32_bf16 v[110:113], v[176:179], v[212:215], v[110:113]
	v_mfma_f32_16x16x32_bf16 v[102:105], v[164:167], v[220:223], v[102:105]
	v_mfma_f32_16x16x32_bf16 v[94:97], v[176:179], v[220:223], v[94:97]
	v_mfma_f32_16x16x32_bf16 v[86:89], v[164:167], v[228:231], v[86:89]
	v_mfma_f32_16x16x32_bf16 v[78:81], v[176:179], v[228:231], v[78:81]
	v_mfma_f32_16x16x32_bf16 v[126:129], v[172:175], v[208:211], v[126:129]
	v_mfma_f32_16x16x32_bf16 v[122:125], v[184:187], v[208:211], v[122:125]
	v_mfma_f32_16x16x32_bf16 v[118:121], v[172:175], v[216:219], v[118:121]
	v_mfma_f32_16x16x32_bf16 v[110:113], v[184:187], v[216:219], v[110:113]
	v_mfma_f32_16x16x32_bf16 v[102:105], v[172:175], v[224:227], v[102:105]
	v_mfma_f32_16x16x32_bf16 v[94:97], v[184:187], v[224:227], v[94:97]
	v_mfma_f32_16x16x32_bf16 v[86:89], v[172:175], v[232:235], v[86:89]
	v_mfma_f32_16x16x32_bf16 v[78:81], v[184:187], v[232:235], v[78:81]
	v_mfma_f32_16x16x32_bf16 v[114:117], v[188:191], v[204:207], v[114:117]
	v_mfma_f32_16x16x32_bf16 v[106:109], v[196:199], v[204:207], v[106:109]
	v_mfma_f32_16x16x32_bf16 v[98:101], v[188:191], v[212:215], v[98:101]
	v_mfma_f32_16x16x32_bf16 v[90:93], v[196:199], v[212:215], v[90:93]
	v_mfma_f32_16x16x32_bf16 v[82:85], v[188:191], v[220:223], v[82:85]
	v_mfma_f32_16x16x32_bf16 v[74:77], v[196:199], v[220:223], v[74:77]
	v_mfma_f32_16x16x32_bf16 v[70:73], v[188:191], v[228:231], v[70:73]
	v_mfma_f32_16x16x32_bf16 v[66:69], v[196:199], v[228:231], v[66:69]
	v_mfma_f32_16x16x32_bf16 v[114:117], v[192:195], v[208:211], v[114:117]
	v_mfma_f32_16x16x32_bf16 v[106:109], v[200:203], v[208:211], v[106:109]
	v_mfma_f32_16x16x32_bf16 v[98:101], v[192:195], v[216:219], v[98:101]
	v_mfma_f32_16x16x32_bf16 v[90:93], v[200:203], v[216:219], v[90:93]
	v_mfma_f32_16x16x32_bf16 v[82:85], v[192:195], v[224:227], v[82:85]
	v_mfma_f32_16x16x32_bf16 v[74:77], v[200:203], v[224:227], v[74:77]
	v_mfma_f32_16x16x32_bf16 v[70:73], v[192:195], v[232:235], v[70:73]
	v_mfma_f32_16x16x32_bf16 v[66:69], v[200:203], v[232:235], v[66:69]
	s_barrier
; #define PG8_STAGE(bufoff, gbase, voff) do { _Pragma("unroll") for (int _i = 0; _i < 2; ++_i) \
;         __builtin_amdgcn_global_load_lds((const unsigned*)((const char*)(gbase) + (voff)[_i]), (LAS unsigned*)(lds + (bufoff) + ldsw + _i * 8192), 16, 0, 0); } while (0)
; #define PG8_LDA(dst, b, h) do { _Pragma("unroll") for (int m = 0; m < 4; ++m) _Pragma("unroll") for (int k = 0; k < 2; ++k) dst[m][k] = *(const LAS bf16x8*)(lds + PG8_SA(b, h) + aoff + m * 2048 + k * 1024); } while (0)
; #define PG8_LDB(dst, b, h) do { _Pragma("unroll") for (int n = 0; n < 2; ++n) _Pragma("unroll") for (int k = 0; k < 2; ++k) dst[n][k] = *(const LAS bf16x8*)(lds + PG8_SB(b, h) + boff + n * 2048 + k * 1024); } while (0)
; #define PG8_BAR __builtin_amdgcn_s_barrier()
; template <class Epi, bool ALIGN_EPI = PG8_ALIGN, bool SP2 = PG8_SP2>
; __device__ __forceinline__ void gemm_phase(LAS uchar* lds, const Gemm g, const StaticOrder& S, const Epi& E) {
;     ...
;         for (int t = tb; t < tb + tblk; t += 2) {
;             const bool last = (t == nt - 2);
;             const char* a1 = cA + (size_t)(t + 1) * kstep;
;             const char* a2 = last ? nA : cA + (size_t)(t + 2) * kstep; const char* b2 = last ? nB : cB + (size_t)(t + 2) * kstep;
;             const char* a3 = a2 + kstep; const char* b3 = b2 + kstep;
;             if constexpr (SP2) {
;             PG8_LDB(B0, 0, 0); PG8_LDB(B1, 0, 1); PG8_SCHED; PG8_LDA(At, 0, 0); PG8_STAGE(PG8_SA(1, 1), a1 + hstepA, voffA);
;             PG8_WAIT_V(8); PG8_WAIT_L(0); PG8_BAR; PG8_MMA(0, 0, At, B0); PG8_MMA(0, 1, At, B1); PG8_BAR; PG8_SCHED;
;             PG8_LDA(At, 0, 1); PG8_STAGE(PG8_SB(0, 0), b2, voffB); PG8_STAGE(PG8_SB(0, 1), b2 + hstepB, voffB); PG8_STAGE(PG8_SA(0, 0), a2, voffA);
;             PG8_WAIT_V(8); PG8_WAIT_L(0); PG8_BAR; PG8_MMA(1, 0, At, B0); PG8_MMA(1, 1, At, B1); PG8_BAR; PG8_SCHED;
;             PG8_LDB(B0, 1, 0); PG8_LDB(B1, 1, 1); PG8_SCHED; PG8_LDA(At, 1, 0); PG8_STAGE(PG8_SA(0, 1), a2 + hstepA, voffA);
;             PG8_WAIT_V(8); PG8_WAIT_L(0); PG8_BAR; PG8_MMA(0, 0, At, B0); PG8_MMA(0, 1, At, B1); PG8_BAR; PG8_SCHED;
;             PG8_LDA(At, 1, 1); PG8_STAGE(PG8_SB(1, 0), b3, voffB); PG8_STAGE(PG8_SB(1, 1), b3 + hstepB, voffB); PG8_STAGE(PG8_SA(1, 0), a3, voffA);
;             PG8_WAIT_V(8); PG8_WAIT_L(0); PG8_BAR; PG8_MMA(1, 0, At, B0); PG8_MMA(1, 1, At, B1); PG8_BAR; PG8_SCHED;
	s_setprio 0
	s_add_i32 s16, s41, s23
	s_add_i32 m0, s16, 0xffffff80
	ds_read_b128 v[204:207], v171 offset:49152
	ds_read_b128 v[208:211], v171 offset:50176
	ds_read_b128 v[212:215], v171 offset:51200
	ds_read_b128 v[216:219], v171 offset:52224
	ds_read_b128 v[220:223], v171 offset:53248
	ds_read_b128 v[224:227], v171 offset:54272
	ds_read_b128 v[228:231], v171 offset:55296
	ds_read_b128 v[232:235], v171 offset:56320
	global_load_lds_dwordx4 v134, s[4:5] offset:128
	s_add_i32 m0, s16, 0x2000
	s_add_u32 s4, s4, 0x44080
	v_lshl_add_u64 v[168:169], v[180:181], 0, s[84:85]
	s_addc_u32 s5, s5, 0
	s_add_i32 s16, s42, s23
	global_load_lds_dwordx4 v[168:169], off
	s_mov_b32 m0, s16
	s_nop 0
	global_load_lds_dwordx4 v134, s[4:5]
	s_add_i32 m0, s16, 0x2000
	s_nop 0
	global_load_lds_dwordx4 v130, s[4:5]
	s_add_i32 m0, s29, 0xffffff80
	s_nop 0
	global_load_lds_dwordx4 v156, s[20:21] offset:128
	s_add_i32 m0, s30, 0xffffff80
	s_nop 0
	global_load_lds_dwordx4 v132, s[20:21] offset:128
	s_waitcnt vmcnt(8)
	s_waitcnt lgkmcnt(0)
	s_setprio 1
	s_barrier
	v_mfma_f32_16x16x32_bf16 v[62:65], v[164:167], v[204:207], v[62:65]
	v_mfma_f32_16x16x32_bf16 v[58:61], v[176:179], v[204:207], v[58:61]
	v_mfma_f32_16x16x32_bf16 v[54:57], v[164:167], v[212:215], v[54:57]
	v_mfma_f32_16x16x32_bf16 v[46:49], v[176:179], v[212:215], v[46:49]
	v_mfma_f32_16x16x32_bf16 v[38:41], v[164:167], v[220:223], v[38:41]
	v_mfma_f32_16x16x32_bf16 v[30:33], v[176:179], v[220:223], v[30:33]
	v_mfma_f32_16x16x32_bf16 v[22:25], v[164:167], v[228:231], v[22:25]
	v_mfma_f32_16x16x32_bf16 v[14:17], v[176:179], v[228:231], v[14:17]
	v_mfma_f32_16x16x32_bf16 v[62:65], v[172:175], v[208:211], v[62:65]
	v_mfma_f32_16x16x32_bf16 v[58:61], v[184:187], v[208:211], v[58:61]
	v_mfma_f32_16x16x32_bf16 v[54:57], v[172:175], v[216:219], v[54:57]
	v_mfma_f32_16x16x32_bf16 v[46:49], v[184:187], v[216:219], v[46:49]
	v_mfma_f32_16x16x32_bf16 v[38:41], v[172:175], v[224:227], v[38:41]
	v_mfma_f32_16x16x32_bf16 v[30:33], v[184:187], v[224:227], v[30:33]
	v_mfma_f32_16x16x32_bf16 v[22:25], v[172:175], v[232:235], v[22:25]
	v_mfma_f32_16x16x32_bf16 v[14:17], v[184:187], v[232:235], v[14:17]
	v_mfma_f32_16x16x32_bf16 v[50:53], v[188:191], v[204:207], v[50:53]
	v_mfma_f32_16x16x32_bf16 v[42:45], v[196:199], v[204:207], v[42:45]
	v_mfma_f32_16x16x32_bf16 v[34:37], v[188:191], v[212:215], v[34:37]
	v_mfma_f32_16x16x32_bf16 v[26:29], v[196:199], v[212:215], v[26:29]
	v_mfma_f32_16x16x32_bf16 v[18:21], v[188:191], v[220:223], v[18:21]
	v_mfma_f32_16x16x32_bf16 v[10:13], v[196:199], v[220:223], v[10:13]
	v_mfma_f32_16x16x32_bf16 v[6:9], v[188:191], v[228:231], v[6:9]
	v_mfma_f32_16x16x32_bf16 v[2:5], v[196:199], v[228:231], v[2:5]
	v_mfma_f32_16x16x32_bf16 v[50:53], v[192:195], v[208:211], v[50:53]
	v_mfma_f32_16x16x32_bf16 v[42:45], v[200:203], v[208:211], v[42:45]
	v_mfma_f32_16x16x32_bf16 v[34:37], v[192:195], v[216:219], v[34:37]
	v_mfma_f32_16x16x32_bf16 v[26:29], v[200:203], v[216:219], v[26:29]
	v_mfma_f32_16x16x32_bf16 v[18:21], v[192:195], v[224:227], v[18:21]
	v_mfma_f32_16x16x32_bf16 v[10:13], v[200:203], v[224:227], v[10:13]
	v_mfma_f32_16x16x32_bf16 v[6:9], v[192:195], v[232:235], v[6:9]
	v_mfma_f32_16x16x32_bf16 v[2:5], v[200:203], v[232:235], v[2:5]
	s_barrier
	s_setprio 0
	s_add_i32 s40, s40, 2
	s_add_u32 s38, s38, 0x100
	s_addc_u32 s39, s39, 0
	s_cmp_gt_u32 s40, 13
	s_mov_b64 s[16:17], s[18:19]
.LBB0_345:
	s_add_u32 s18, s16, 0x100
	s_addc_u32 s19, s17, 0
	s_add_i32 s41, 0, 0x10000
	s_cmp_eq_u32 s40, 12
	s_cselect_b32 s21, s7, s19
	s_cselect_b32 s20, s6, s18
	v_add_u32_e32 v168, s41, v139
	s_cselect_b32 s5, s15, s39
	s_cselect_b32 s4, s14, s38
	s_add_i32 s42, 0, 0x14000
	ds_read_b128 v[164:167], v168
	ds_read_b128 v[172:175], v168 offset:1024
	ds_read_b128 v[176:179], v168 offset:2048
	ds_read_b128 v[184:187], v168 offset:3072
	v_add_u32_e32 v168, s42, v139
	ds_read_b128 v[188:191], v168
	ds_read_b128 v[192:195], v168 offset:1024
	ds_read_b128 v[196:199], v168 offset:2048
	ds_read_b128 v[200:203], v168 offset:3072
	s_add_i32 m0, s25, 0xc000
	ds_read_b128 v[204:207], v171
	ds_read_b128 v[208:211], v171 offset:1024
	ds_read_b128 v[212:215], v171 offset:2048
	ds_read_b128 v[216:219], v171 offset:3072
	ds_read_b128 v[220:223], v171 offset:4096
	ds_read_b128 v[224:227], v171 offset:5120
	ds_read_b128 v[228:231], v171 offset:6144
	ds_read_b128 v[232:235], v171 offset:7168
	global_load_lds_dwordx4 v160, s[16:17]
	s_add_i32 m0, s25, 0xe000
	s_nop 0
	global_load_lds_dwordx4 v162, s[16:17]
	s_waitcnt vmcnt(8)
	s_waitcnt lgkmcnt(0)
	s_setprio 1
	s_barrier
; #define PG8_STAGE(bufoff, gbase, voff) do { _Pragma("unroll") for (int _i = 0; _i < 2; ++_i) \
;         __builtin_amdgcn_global_load_lds((const unsigned*)((const char*)(gbase) + (voff)[_i]), (LAS unsigned*)(lds + (bufoff) + ldsw + _i * 8192), 16, 0, 0); } while (0)
; #define PG8_LDA(dst, b, h) do { _Pragma("unroll") for (int m = 0; m < 4; ++m) _Pragma("unroll") for (int k = 0; k < 2; ++k) dst[m][k] = *(const LAS bf16x8*)(lds + PG8_SA(b, h) + aoff + m * 2048 + k * 1024); } while (0)
; #define PG8_MMA(ai, bj, At, Bt) do { __builtin_amdgcn_s_setprio(1); _Pragma("unroll") for (int m = 0; m < 4; ++m) _Pragma("unroll") for (int n = 0; n < 2; ++n) _Pragma("unroll") for (int k = 0; k < 2; ++k) \
;         acc[ai][bj][m][n] = __builtin_amdgcn_mfma_f32_16x16x32_bf16(Bt[n][k], At[m][k], acc[ai][bj][m][n], 0, 0, 0); __builtin_amdgcn_s_setprio(0); } while (0)
; #define PG8_WAIT_V(n) asm volatile("s_waitcnt vmcnt(" #n ")" ::: "memory")
; #define PG8_WAIT_L(n) asm volatile("s_waitcnt lgkmcnt(" #n ")" ::: "memory")
; #define PG8_BAR __builtin_amdgcn_s_barrier()
; #define PG8_SCHED __builtin_amdgcn_sched_barrier(0)
; template <class Epi, bool ALIGN_EPI = PG8_ALIGN, bool SP2 = PG8_SP2>
; __device__ __forceinline__ void gemm_phase(LAS uchar* lds, const Gemm g, const StaticOrder& S, const Epi& E) {
;     ...
;             PG8_WAIT_V(8); PG8_WAIT_L(0); PG8_BAR; PG8_MMA(0, 0, At, B0); PG8_MMA(0, 1, At, B1); PG8_BAR; PG8_SCHED;
;             PG8_LDA(At, 0, 1); PG8_STAGE(PG8_SB(0, 0), b2, voffB); PG8_STAGE(PG8_SB(0, 1), b2 + hstepB, voffB); PG8_STAGE(PG8_SA(0, 0), a2, voffA);
;             PG8_WAIT_V(8); PG8_WAIT_L(0); PG8_BAR; PG8_MMA(1, 0, At, B0); PG8_MMA(1, 1, At, B1); PG8_BAR; PG8_SCHED;
	v_mfma_f32_16x16x32_bf16 v[126:129], v[164:167], v[204:207], v[126:129]
	v_mfma_f32_16x16x32_bf16 v[122:125], v[176:179], v[204:207], v[122:125]
	v_mfma_f32_16x16x32_bf16 v[118:121], v[164:167], v[212:215], v[118:121]
	v_mfma_f32_16x16x32_bf16 v[110:113], v[176:179], v[212:215], v[110:113]
	v_mfma_f32_16x16x32_bf16 v[102:105], v[164:167], v[220:223], v[102:105]
	v_mfma_f32_16x16x32_bf16 v[94:97], v[176:179], v[220:223], v[94:97]
	v_mfma_f32_16x16x32_bf16 v[86:89], v[164:167], v[228:231], v[86:89]
	v_mfma_f32_16x16x32_bf16 v[78:81], v[176:179], v[228:231], v[78:81]
	v_mfma_f32_16x16x32_bf16 v[126:129], v[172:175], v[208:211], v[126:129]
	v_mfma_f32_16x16x32_bf16 v[122:125], v[184:187], v[208:211], v[122:125]
	v_mfma_f32_16x16x32_bf16 v[118:121], v[172:175], v[216:219], v[118:121]
	v_mfma_f32_16x16x32_bf16 v[110:113], v[184:187], v[216:219], v[110:113]
	v_mfma_f32_16x16x32_bf16 v[102:105], v[172:175], v[224:227], v[102:105]
	v_mfma_f32_16x16x32_bf16 v[94:97], v[184:187], v[224:227], v[94:97]
	v_mfma_f32_16x16x32_bf16 v[86:89], v[172:175], v[232:235], v[86:89]
	v_mfma_f32_16x16x32_bf16 v[78:81], v[184:187], v[232:235], v[78:81]
	v_mfma_f32_16x16x32_bf16 v[114:117], v[188:191], v[204:207], v[114:117]
	v_mfma_f32_16x16x32_bf16 v[106:109], v[196:199], v[204:207], v[106:109]
	v_mfma_f32_16x16x32_bf16 v[98:101], v[188:191], v[212:215], v[98:101]
	v_mfma_f32_16x16x32_bf16 v[90:93], v[196:199], v[212:215], v[90:93]
	v_mfma_f32_16x16x32_bf16 v[82:85], v[188:191], v[220:223], v[82:85]
	v_mfma_f32_16x16x32_bf16 v[74:77], v[196:199], v[220:223], v[74:77]
	v_mfma_f32_16x16x32_bf16 v[70:73], v[188:191], v[228:231], v[70:73]
	v_mfma_f32_16x16x32_bf16 v[66:69], v[196:199], v[228:231], v[66:69]
	v_mfma_f32_16x16x32_bf16 v[114:117], v[192:195], v[208:211], v[114:117]
	v_mfma_f32_16x16x32_bf16 v[106:109], v[200:203], v[208:211], v[106:109]
	v_mfma_f32_16x16x32_bf16 v[98:101], v[192:195], v[216:219], v[98:101]
	v_mfma_f32_16x16x32_bf16 v[90:93], v[200:203], v[216:219], v[90:93]
	v_mfma_f32_16x16x32_bf16 v[82:85], v[192:195], v[224:227], v[82:85]
	v_mfma_f32_16x16x32_bf16 v[74:77], v[200:203], v[224:227], v[74:77]
	v_mfma_f32_16x16x32_bf16 v[70:73], v[192:195], v[232:235], v[70:73]
	v_mfma_f32_16x16x32_bf16 v[66:69], v[200:203], v[232:235], v[66:69]
	s_barrier
	s_setprio 0
	s_add_i32 s16, s41, s23
	s_mov_b32 m0, s16
	ds_read_b128 v[204:207], v171 offset:16384
	ds_read_b128 v[208:211], v171 offset:17408
	ds_read_b128 v[212:215], v171 offset:18432
	ds_read_b128 v[216:219], v171 offset:19456
	ds_read_b128 v[220:223], v171 offset:20480
	ds_read_b128 v[224:227], v171 offset:21504
	ds_read_b128 v[228:231], v171 offset:22528
	ds_read_b128 v[232:235], v171 offset:23552
	global_load_lds_dwordx4 v134, s[4:5]
	s_add_i32 m0, s16, 0x2000
	s_add_u32 s16, s4, 0x44000
	v_lshl_add_u64 v[180:181], s[4:5], 0, v[130:131]
	s_addc_u32 s17, s5, 0
	s_add_i32 s41, s42, s23
	global_load_lds_dwordx4 v130, s[4:5]
	s_mov_b32 m0, s41
	s_nop 0
	global_load_lds_dwordx4 v134, s[16:17]
	s_add_i32 m0, s41, 0x2000
	s_nop 0
	global_load_lds_dwordx4 v130, s[16:17]
	s_mov_b32 m0, s25
	s_nop 0
	global_load_lds_dwordx4 v156, s[20:21]
	s_mov_b32 m0, s26
	s_nop 0
	global_load_lds_dwordx4 v132, s[20:21]
	s_waitcnt vmcnt(8)
	s_waitcnt lgkmcnt(0)
	s_setprio 1
	s_barrier
	v_mfma_f32_16x16x32_bf16 v[62:65], v[164:167], v[204:207], v[62:65]
	v_mfma_f32_16x16x32_bf16 v[58:61], v[176:179], v[204:207], v[58:61]
	v_mfma_f32_16x16x32_bf16 v[54:57], v[164:167], v[212:215], v[54:57]
	v_mfma_f32_16x16x32_bf16 v[46:49], v[176:179], v[212:215], v[46:49]
	v_mfma_f32_16x16x32_bf16 v[38:41], v[164:167], v[220:223], v[38:41]
	v_mfma_f32_16x16x32_bf16 v[30:33], v[176:179], v[220:223], v[30:33]
	v_mfma_f32_16x16x32_bf16 v[22:25], v[164:167], v[228:231], v[22:25]
	v_mfma_f32_16x16x32_bf16 v[14:17], v[176:179], v[228:231], v[14:17]
	v_mfma_f32_16x16x32_bf16 v[62:65], v[172:175], v[208:211], v[62:65]
	v_mfma_f32_16x16x32_bf16 v[58:61], v[184:187], v[208:211], v[58:61]
	v_mfma_f32_16x16x32_bf16 v[54:57], v[172:175], v[216:219], v[54:57]
	v_mfma_f32_16x16x32_bf16 v[46:49], v[184:187], v[216:219], v[46:49]
	v_mfma_f32_16x16x32_bf16 v[38:41], v[172:175], v[224:227], v[38:41]
	v_mfma_f32_16x16x32_bf16 v[30:33], v[184:187], v[224:227], v[30:33]
	v_mfma_f32_16x16x32_bf16 v[22:25], v[172:175], v[232:235], v[22:25]
	v_mfma_f32_16x16x32_bf16 v[14:17], v[184:187], v[232:235], v[14:17]
	v_mfma_f32_16x16x32_bf16 v[50:53], v[188:191], v[204:207], v[50:53]
	v_mfma_f32_16x16x32_bf16 v[42:45], v[196:199], v[204:207], v[42:45]
	v_mfma_f32_16x16x32_bf16 v[34:37], v[188:191], v[212:215], v[34:37]
	v_mfma_f32_16x16x32_bf16 v[26:29], v[196:199], v[212:215], v[26:29]
	v_mfma_f32_16x16x32_bf16 v[18:21], v[188:191], v[220:223], v[18:21]
	v_mfma_f32_16x16x32_bf16 v[10:13], v[196:199], v[220:223], v[10:13]
	v_mfma_f32_16x16x32_bf16 v[6:9], v[188:191], v[228:231], v[6:9]
	v_mfma_f32_16x16x32_bf16 v[2:5], v[196:199], v[228:231], v[2:5]
	v_mfma_f32_16x16x32_bf16 v[50:53], v[192:195], v[208:211], v[50:53]
	v_mfma_f32_16x16x32_bf16 v[42:45], v[200:203], v[208:211], v[42:45]
	v_mfma_f32_16x16x32_bf16 v[34:37], v[192:195], v[216:219], v[34:37]
	v_mfma_f32_16x16x32_bf16 v[26:29], v[200:203], v[216:219], v[26:29]
	v_mfma_f32_16x16x32_bf16 v[18:21], v[192:195], v[224:227], v[18:21]
	v_mfma_f32_16x16x32_bf16 v[10:13], v[200:203], v[224:227], v[10:13]
	v_mfma_f32_16x16x32_bf16 v[6:9], v[192:195], v[232:235], v[6:9]
	v_mfma_f32_16x16x32_bf16 v[2:5], v[200:203], v[232:235], v[2:5]
	s_barrier
; #define PG8_STAGE(bufoff, gbase, voff) do { _Pragma("unroll") for (int _i = 0; _i < 2; ++_i) \
;         __builtin_amdgcn_global_load_lds((const unsigned*)((const char*)(gbase) + (voff)[_i]), (LAS unsigned*)(lds + (bufoff) + ldsw + _i * 8192), 16, 0, 0); } while (0)
; #define PG8_LDA(dst, b, h) do { _Pragma("unroll") for (int m = 0; m < 4; ++m) _Pragma("unroll") for (int k = 0; k < 2; ++k) dst[m][k] = *(const LAS bf16x8*)(lds + PG8_SA(b, h) + aoff + m * 2048 + k * 1024); } while (0)
; #define PG8_LDB(dst, b, h) do { _Pragma("unroll") for (int n = 0; n < 2; ++n) _Pragma("unroll") for (int k = 0; k < 2; ++k) dst[n][k] = *(const LAS bf16x8*)(lds + PG8_SB(b, h) + boff + n * 2048 + k * 1024); } while (0)
; #define PG8_MMA(ai, bj, At, Bt) do { __builtin_amdgcn_s_setprio(1); _Pragma("unroll") for (int m = 0; m < 4; ++m) _Pragma("unroll") for (int n = 0; n < 2; ++n) _Pragma("unroll") for (int k = 0; k < 2; ++k) \
;         acc[ai][bj][m][n] = __builtin_amdgcn_mfma_f32_16x16x32_bf16(Bt[n][k], At[m][k], acc[ai][bj][m][n], 0, 0, 0); __builtin_amdgcn_s_setprio(0); } while (0)
; #define PG8_WAIT_V(n) asm volatile("s_waitcnt vmcnt(" #n ")" ::: "memory")
; #define PG8_WAIT_L(n) asm volatile("s_waitcnt lgkmcnt(" #n ")" ::: "memory")
; #define PG8_BAR __builtin_amdgcn_s_barrier()
; #define PG8_SCHED __builtin_amdgcn_sched_barrier(0)
; template <class Epi, bool ALIGN_EPI = PG8_ALIGN, bool SP2 = PG8_SP2>
; __device__ __forceinline__ void gemm_phase(LAS uchar* lds, const Gemm g, const StaticOrder& S, const Epi& E) {
;     ...
;             PG8_LDB(B0, 1, 0); PG8_LDB(B1, 1, 1); PG8_SCHED; PG8_LDA(At, 1, 0); PG8_STAGE(PG8_SA(0, 1), a2 + hstepA, voffA);
;             PG8_WAIT_V(8); PG8_WAIT_L(0); PG8_BAR; PG8_MMA(0, 0, At, B0); PG8_MMA(0, 1, At, B1); PG8_BAR; PG8_SCHED;
;             PG8_LDA(At, 1, 1); PG8_STAGE(PG8_SB(1, 0), b3, voffB); PG8_STAGE(PG8_SB(1, 1), b3 + hstepB, voffB); PG8_STAGE(PG8_SA(1, 0), a3, voffA);
;             PG8_WAIT_V(8); PG8_WAIT_L(0); PG8_BAR; PG8_MMA(1, 0, At, B0); PG8_MMA(1, 1, At, B1); PG8_BAR; PG8_SCHED;
;     __device__ __forceinline__ void operator()(const f32x4 (&acc)[2][2][4][2], const pg8::Unit& u, int wr, int wc, int fr, int fq, int) const {
;         const int row0 = u.pm * 256 + wr * 64 + fr;
;         if (u.pn < 24) {
	s_setprio 0
	s_add_i32 s41, 0, 0x18000
	s_add_i32 s42, 0, 0x1c000
	v_add_u32_e32 v184, s41, v139
	v_add_u32_e32 v200, s42, v139
	ds_read_b128 v[164:167], v184
	ds_read_b128 v[172:175], v184 offset:1024
	ds_read_b128 v[176:179], v184 offset:2048
	ds_read_b128 v[184:187], v184 offset:3072
	ds_read_b128 v[188:191], v200
	ds_read_b128 v[192:195], v200 offset:1024
	ds_read_b128 v[196:199], v200 offset:2048
	ds_read_b128 v[200:203], v200 offset:3072
	s_add_u32 s16, s20, 0x44000
	s_addc_u32 s17, s21, 0
	s_mov_b32 m0, s27
	ds_read_b128 v[204:207], v171 offset:32768
	ds_read_b128 v[208:211], v171 offset:33792
	ds_read_b128 v[212:215], v171 offset:34816
	ds_read_b128 v[216:219], v171 offset:35840
	ds_read_b128 v[220:223], v171 offset:36864
	ds_read_b128 v[224:227], v171 offset:37888
	ds_read_b128 v[228:231], v171 offset:38912
	ds_read_b128 v[232:235], v171 offset:39936
	global_load_lds_dwordx4 v156, s[16:17]
	s_mov_b32 m0, s28
	s_nop 0
	global_load_lds_dwordx4 v132, s[16:17]
	s_waitcnt vmcnt(8)
	s_waitcnt lgkmcnt(0)
	s_setprio 1
	s_barrier
	v_mfma_f32_16x16x32_bf16 v[126:129], v[164:167], v[204:207], v[126:129]
	v_mfma_f32_16x16x32_bf16 v[122:125], v[176:179], v[204:207], v[122:125]
	v_mfma_f32_16x16x32_bf16 v[118:121], v[164:167], v[212:215], v[118:121]
	v_mfma_f32_16x16x32_bf16 v[110:113], v[176:179], v[212:215], v[110:113]
	v_mfma_f32_16x16x32_bf16 v[102:105], v[164:167], v[220:223], v[102:105]
	v_mfma_f32_16x16x32_bf16 v[94:97], v[176:179], v[220:223], v[94:97]
	v_mfma_f32_16x16x32_bf16 v[86:89], v[164:167], v[228:231], v[86:89]
	v_mfma_f32_16x16x32_bf16 v[78:81], v[176:179], v[228:231], v[78:81]
	v_mfma_f32_16x16x32_bf16 v[126:129], v[172:175], v[208:211], v[126:129]
	v_mfma_f32_16x16x32_bf16 v[122:125], v[184:187], v[208:211], v[122:125]
	v_mfma_f32_16x16x32_bf16 v[118:121], v[172:175], v[216:219], v[118:121]
	v_mfma_f32_16x16x32_bf16 v[110:113], v[184:187], v[216:219], v[110:113]
	v_mfma_f32_16x16x32_bf16 v[102:105], v[172:175], v[224:227], v[102:105]
	v_mfma_f32_16x16x32_bf16 v[94:97], v[184:187], v[224:227], v[94:97]
	v_mfma_f32_16x16x32_bf16 v[86:89], v[172:175], v[232:235], v[86:89]
	v_mfma_f32_16x16x32_bf16 v[78:81], v[184:187], v[232:235], v[78:81]
	v_mfma_f32_16x16x32_bf16 v[114:117], v[188:191], v[204:207], v[114:117]
	v_mfma_f32_16x16x32_bf16 v[106:109], v[196:199], v[204:207], v[106:109]
	v_mfma_f32_16x16x32_bf16 v[98:101], v[188:191], v[212:215], v[98:101]
	v_mfma_f32_16x16x32_bf16 v[90:93], v[196:199], v[212:215], v[90:93]
	v_mfma_f32_16x16x32_bf16 v[82:85], v[188:191], v[220:223], v[82:85]
	v_mfma_f32_16x16x32_bf16 v[74:77], v[196:199], v[220:223], v[74:77]
	v_mfma_f32_16x16x32_bf16 v[70:73], v[188:191], v[228:231], v[70:73]
	v_mfma_f32_16x16x32_bf16 v[66:69], v[196:199], v[228:231], v[66:69]
	v_mfma_f32_16x16x32_bf16 v[114:117], v[192:195], v[208:211], v[114:117]
	v_mfma_f32_16x16x32_bf16 v[106:109], v[200:203], v[208:211], v[106:109]
	v_mfma_f32_16x16x32_bf16 v[98:101], v[192:195], v[216:219], v[98:101]
	v_mfma_f32_16x16x32_bf16 v[90:93], v[200:203], v[216:219], v[90:93]
	v_mfma_f32_16x16x32_bf16 v[82:85], v[192:195], v[224:227], v[82:85]
	v_mfma_f32_16x16x32_bf16 v[74:77], v[200:203], v[224:227], v[74:77]
	v_mfma_f32_16x16x32_bf16 v[70:73], v[192:195], v[232:235], v[70:73]
	v_mfma_f32_16x16x32_bf16 v[66:69], v[200:203], v[232:235], v[66:69]
	s_barrier
	s_setprio 0
	s_add_i32 s16, s41, s23
	s_add_i32 m0, s16, 0xffffff80
	ds_read_b128 v[204:207], v171 offset:49152
	ds_read_b128 v[208:211], v171 offset:50176
	ds_read_b128 v[212:215], v171 offset:51200
	ds_read_b128 v[216:219], v171 offset:52224
	ds_read_b128 v[220:223], v171 offset:53248
	ds_read_b128 v[224:227], v171 offset:54272
	ds_read_b128 v[228:231], v171 offset:55296
	ds_read_b128 v[232:235], v171 offset:56320
	global_load_lds_dwordx4 v134, s[4:5] offset:128
	s_add_i32 m0, s16, 0x2000
	s_add_u32 s4, s4, 0x44080
	v_lshl_add_u64 v[168:169], v[180:181], 0, s[84:85]
	s_addc_u32 s5, s5, 0
	s_add_i32 s16, s42, s23
	global_load_lds_dwordx4 v[168:169], off
	s_mov_b32 m0, s16
	s_nop 0
	global_load_lds_dwordx4 v134, s[4:5]
	s_add_i32 m0, s16, 0x2000
	s_nop 0
	global_load_lds_dwordx4 v130, s[4:5]
	s_add_i32 m0, s29, 0xffffff80
	s_nop 0
	global_load_lds_dwordx4 v156, s[20:21] offset:128
	s_add_i32 m0, s30, 0xffffff80
	s_nop 0
	global_load_lds_dwordx4 v132, s[20:21] offset:128
	s_waitcnt vmcnt(8)
	s_waitcnt lgkmcnt(0)
	s_setprio 1
	s_barrier
	v_mfma_f32_16x16x32_bf16 v[62:65], v[164:167], v[204:207], v[62:65]
	v_mfma_f32_16x16x32_bf16 v[58:61], v[176:179], v[204:207], v[58:61]
	v_mfma_f32_16x16x32_bf16 v[54:57], v[164:167], v[212:215], v[54:57]
	v_mfma_f32_16x16x32_bf16 v[46:49], v[176:179], v[212:215], v[46:49]
	v_mfma_f32_16x16x32_bf16 v[38:41], v[164:167], v[220:223], v[38:41]
	v_mfma_f32_16x16x32_bf16 v[30:33], v[176:179], v[220:223], v[30:33]
	v_mfma_f32_16x16x32_bf16 v[22:25], v[164:167], v[228:231], v[22:25]
	v_mfma_f32_16x16x32_bf16 v[14:17], v[176:179], v[228:231], v[14:17]
	v_mfma_f32_16x16x32_bf16 v[62:65], v[172:175], v[208:211], v[62:65]
	v_mfma_f32_16x16x32_bf16 v[58:61], v[184:187], v[208:211], v[58:61]
	v_mfma_f32_16x16x32_bf16 v[54:57], v[172:175], v[216:219], v[54:57]
	v_mfma_f32_16x16x32_bf16 v[46:49], v[184:187], v[216:219], v[46:49]
	v_mfma_f32_16x16x32_bf16 v[38:41], v[172:175], v[224:227], v[38:41]
	v_mfma_f32_16x16x32_bf16 v[30:33], v[184:187], v[224:227], v[30:33]
	v_mfma_f32_16x16x32_bf16 v[22:25], v[172:175], v[232:235], v[22:25]
	v_mfma_f32_16x16x32_bf16 v[14:17], v[184:187], v[232:235], v[14:17]
	v_mfma_f32_16x16x32_bf16 v[50:53], v[188:191], v[204:207], v[50:53]
	v_mfma_f32_16x16x32_bf16 v[42:45], v[196:199], v[204:207], v[42:45]
	v_mfma_f32_16x16x32_bf16 v[34:37], v[188:191], v[212:215], v[34:37]
	v_mfma_f32_16x16x32_bf16 v[26:29], v[196:199], v[212:215], v[26:29]
	v_mfma_f32_16x16x32_bf16 v[18:21], v[188:191], v[220:223], v[18:21]
	v_mfma_f32_16x16x32_bf16 v[10:13], v[196:199], v[220:223], v[10:13]
	v_mfma_f32_16x16x32_bf16 v[6:9], v[188:191], v[228:231], v[6:9]
	v_mfma_f32_16x16x32_bf16 v[2:5], v[196:199], v[228:231], v[2:5]
	v_mfma_f32_16x16x32_bf16 v[50:53], v[192:195], v[208:211], v[50:53]
	v_mfma_f32_16x16x32_bf16 v[42:45], v[200:203], v[208:211], v[42:45]
	v_mfma_f32_16x16x32_bf16 v[34:37], v[192:195], v[216:219], v[34:37]
	v_mfma_f32_16x16x32_bf16 v[26:29], v[200:203], v[216:219], v[26:29]
	v_mfma_f32_16x16x32_bf16 v[18:21], v[192:195], v[224:227], v[18:21]
	v_mfma_f32_16x16x32_bf16 v[10:13], v[200:203], v[224:227], v[10:13]
	v_mfma_f32_16x16x32_bf16 v[6:9], v[192:195], v[232:235], v[6:9]
	v_mfma_f32_16x16x32_bf16 v[2:5], v[200:203], v[232:235], v[2:5]
	s_barrier
	s_setprio 0
	s_add_i32 s40, s40, 2
	s_add_u32 s38, s38, 0x100
	s_addc_u32 s39, s39, 0
	s_cmp_gt_u32 s40, 13
	s_mov_b64 s[16:17], s[18:19]
	s_cbranch_scc0 .LBB0_345
	s_mov_b32 s97, 0
	s_and_b64 vcc, exec, s[10:11]
	s_cbranch_vccnz .LBB0_350
	v_lshl_add_u32 v164, s37, 8, v1
	s_cmp_gt_i32 s36, 23
	s_mov_b64 s[4:5], -1
	s_cbranch_scc1 .LBB0_351

; #define PG8_STAGE(bufoff, gbase, voff) do { _Pragma("unroll") for (int _i = 0; _i < 2; ++_i) \
;         __builtin_amdgcn_global_load_lds((const unsigned*)((const char*)(gbase) + (voff)[_i]), (LAS unsigned*)(lds + (bufoff) + ldsw + _i * 8192), 16, 0, 0); } while (0)
; #define PG8_LDA(dst, b, h) do { _Pragma("unroll") for (int m = 0; m < 4; ++m) _Pragma("unroll") for (int k = 0; k < 2; ++k) dst[m][k] = *(const LAS bf16x8*)(lds + PG8_SA(b, h) + aoff + m * 2048 + k * 1024); } while (0)
; #define PG8_LDB(dst, b, h) do { _Pragma("unroll") for (int n = 0; n < 2; ++n) _Pragma("unroll") for (int k = 0; k < 2; ++k) dst[n][k] = *(const LAS bf16x8*)(lds + PG8_SB(b, h) + boff + n * 2048 + k * 1024); } while (0)
; #define PG8_MMA(ai, bj, At, Bt) do { __builtin_amdgcn_s_setprio(1); _Pragma("unroll") for (int m = 0; m < 4; ++m) _Pragma("unroll") for (int n = 0; n < 2; ++n) _Pragma("unroll") for (int k = 0; k < 2; ++k) \
;         acc[ai][bj][m][n] = __builtin_amdgcn_mfma_f32_16x16x32_bf16(Bt[n][k], At[m][k], acc[ai][bj][m][n], 0, 0, 0); __builtin_amdgcn_s_setprio(0); } while (0)
; #define PG8_WAIT_V(n) asm volatile("s_waitcnt vmcnt(" #n ")" ::: "memory")
; #define PG8_WAIT_L(n) asm volatile("s_waitcnt lgkmcnt(" #n ")" ::: "memory")
; #define PG8_BAR __builtin_amdgcn_s_barrier()
; template <class Epi, bool ALIGN_EPI = PG8_ALIGN, bool SP2 = PG8_SP2>
; __device__ __forceinline__ void gemm_phase(LAS uchar* lds, const Gemm g, const StaticOrder& S, const Epi& E) {
;     ...
;         for (int t = tb; t < tb + tblk; t += 2) {
;             const bool last = (t == nt - 2);
;             const char* a1 = cA + (size_t)(t + 1) * kstep;
;             const char* a2 = last ? nA : cA + (size_t)(t + 2) * kstep; const char* b2 = last ? nB : cB + (size_t)(t + 2) * kstep;
;             const char* a3 = a2 + kstep; const char* b3 = b2 + kstep;
;             if constexpr (SP2) {
;             PG8_LDB(B0, 0, 0); PG8_LDB(B1, 0, 1); PG8_SCHED; PG8_LDA(At, 0, 0); PG8_STAGE(PG8_SA(1, 1), a1 + hstepA, voffA);
;             PG8_WAIT_V(8); PG8_WAIT_L(0); PG8_BAR; PG8_MMA(0, 0, At, B0); PG8_MMA(0, 1, At, B1); PG8_BAR; PG8_SCHED;
;             PG8_LDA(At, 0, 1); PG8_STAGE(PG8_SB(0, 0), b2, voffB); PG8_STAGE(PG8_SB(0, 1), b2 + hstepB, voffB); PG8_STAGE(PG8_SA(0, 0), a2, voffA);
;             PG8_WAIT_V(8); PG8_WAIT_L(0); PG8_BAR; PG8_MMA(1, 0, At, B0); PG8_MMA(1, 1, At, B1); PG8_BAR; PG8_SCHED;
.LBB0_668:
	s_add_u32 s36, s14, 0x100
	s_addc_u32 s37, s15, 0
	s_mov_b32 s38, -2
	s_add_u32 s14, s12, 0x100
	s_addc_u32 s15, s13, 0
	s_add_i32 s39, 0, 0x10000
	s_cmp_eq_u32 s38, 12
	s_cselect_b32 s19, s5, s15
	s_cselect_b32 s18, s4, s14
	s_cselect_b32 s17, s11, s37
	s_cselect_b32 s16, s10, s36
	s_add_i32 s40, 0, 0x14000
	v_add_u32_e32 v174, s39, v139
	v_add_u32_e32 v192, s40, v139
	ds_read_b128 v[160:163], v174
	ds_read_b128 v[164:167], v174 offset:1024
	ds_read_b128 v[168:171], v174 offset:2048
	ds_read_b128 v[174:177], v174 offset:3072
	ds_read_b128 v[178:181], v192
	ds_read_b128 v[184:187], v192 offset:1024
	ds_read_b128 v[188:191], v192 offset:2048
	ds_read_b128 v[192:195], v192 offset:3072
	s_add_i32 m0, s23, 0xc000
	ds_read_b128 v[196:199], v173
	ds_read_b128 v[200:203], v173 offset:1024
	ds_read_b128 v[204:207], v173 offset:2048
	ds_read_b128 v[208:211], v173 offset:3072
	ds_read_b128 v[212:215], v173 offset:4096
	ds_read_b128 v[216:219], v173 offset:5120
	ds_read_b128 v[220:223], v173 offset:6144
	ds_read_b128 v[224:227], v173 offset:7168
	global_load_lds_dwordx4 v156, s[12:13]
	s_add_i32 m0, s23, 0xe000
	s_nop 0
	global_load_lds_dwordx4 v158, s[12:13]
	s_waitcnt vmcnt(8)
	s_waitcnt lgkmcnt(0)
	s_setprio 1
	s_barrier
	v_mfma_f32_16x16x32_bf16 v[126:129], v[160:163], v[196:199], 0
	v_mfma_f32_16x16x32_bf16 v[122:125], v[168:171], v[196:199], 0
	v_mfma_f32_16x16x32_bf16 v[118:121], v[160:163], v[204:207], 0
	v_mfma_f32_16x16x32_bf16 v[110:113], v[168:171], v[204:207], 0
	v_mfma_f32_16x16x32_bf16 v[102:105], v[160:163], v[212:215], 0
	v_mfma_f32_16x16x32_bf16 v[94:97], v[168:171], v[212:215], 0
	v_mfma_f32_16x16x32_bf16 v[86:89], v[160:163], v[220:223], 0
	v_mfma_f32_16x16x32_bf16 v[78:81], v[168:171], v[220:223], 0
	v_mfma_f32_16x16x32_bf16 v[126:129], v[164:167], v[200:203], v[126:129]
	v_mfma_f32_16x16x32_bf16 v[122:125], v[174:177], v[200:203], v[122:125]
	v_mfma_f32_16x16x32_bf16 v[118:121], v[164:167], v[208:211], v[118:121]
	v_mfma_f32_16x16x32_bf16 v[110:113], v[174:177], v[208:211], v[110:113]
	v_mfma_f32_16x16x32_bf16 v[102:105], v[164:167], v[216:219], v[102:105]
	v_mfma_f32_16x16x32_bf16 v[94:97], v[174:177], v[216:219], v[94:97]
	v_mfma_f32_16x16x32_bf16 v[86:89], v[164:167], v[224:227], v[86:89]
	v_mfma_f32_16x16x32_bf16 v[78:81], v[174:177], v[224:227], v[78:81]
	v_mfma_f32_16x16x32_bf16 v[114:117], v[178:181], v[196:199], 0
	v_mfma_f32_16x16x32_bf16 v[106:109], v[188:191], v[196:199], 0
	v_mfma_f32_16x16x32_bf16 v[98:101], v[178:181], v[204:207], 0
	v_mfma_f32_16x16x32_bf16 v[90:93], v[188:191], v[204:207], 0
	v_mfma_f32_16x16x32_bf16 v[82:85], v[178:181], v[212:215], 0
	v_mfma_f32_16x16x32_bf16 v[74:77], v[188:191], v[212:215], 0
	v_mfma_f32_16x16x32_bf16 v[70:73], v[178:181], v[220:223], 0
	v_mfma_f32_16x16x32_bf16 v[66:69], v[188:191], v[220:223], 0
	v_mfma_f32_16x16x32_bf16 v[114:117], v[184:187], v[200:203], v[114:117]
	v_mfma_f32_16x16x32_bf16 v[106:109], v[192:195], v[200:203], v[106:109]
	v_mfma_f32_16x16x32_bf16 v[98:101], v[184:187], v[208:211], v[98:101]
	v_mfma_f32_16x16x32_bf16 v[90:93], v[192:195], v[208:211], v[90:93]
	v_mfma_f32_16x16x32_bf16 v[82:85], v[184:187], v[216:219], v[82:85]
	v_mfma_f32_16x16x32_bf16 v[74:77], v[192:195], v[216:219], v[74:77]
	v_mfma_f32_16x16x32_bf16 v[70:73], v[184:187], v[224:227], v[70:73]
	v_mfma_f32_16x16x32_bf16 v[66:69], v[192:195], v[224:227], v[66:69]
	s_barrier
	s_setprio 0
	s_add_i32 s12, s39, s21
	s_mov_b32 m0, s12
	ds_read_b128 v[196:199], v173 offset:16384
	ds_read_b128 v[200:203], v173 offset:17408
	ds_read_b128 v[204:207], v173 offset:18432
	ds_read_b128 v[208:211], v173 offset:19456
	ds_read_b128 v[212:215], v173 offset:20480
	ds_read_b128 v[216:219], v173 offset:21504
	ds_read_b128 v[220:223], v173 offset:22528
	ds_read_b128 v[224:227], v173 offset:23552
	global_load_lds_dwordx4 v134, s[16:17]
	s_add_i32 m0, s12, 0x2000
	s_add_u32 s12, s16, 0x44000
	s_addc_u32 s13, s17, 0
	s_add_i32 s39, s40, s21
	global_load_lds_dwordx4 v130, s[16:17]
	s_mov_b32 m0, s39
	s_nop 0
	global_load_lds_dwordx4 v134, s[12:13]
	s_add_i32 m0, s39, 0x2000
	s_nop 0
	global_load_lds_dwordx4 v130, s[12:13]
	s_mov_b32 m0, s23
	s_nop 0
	global_load_lds_dwordx4 v152, s[18:19]
	s_mov_b32 m0, s24
	s_nop 0
	global_load_lds_dwordx4 v132, s[18:19]
	s_waitcnt vmcnt(8)
	s_waitcnt lgkmcnt(0)
	s_setprio 1
	s_barrier
	v_mfma_f32_16x16x32_bf16 v[62:65], v[160:163], v[196:199], 0
	v_mfma_f32_16x16x32_bf16 v[58:61], v[168:171], v[196:199], 0
	v_mfma_f32_16x16x32_bf16 v[54:57], v[160:163], v[204:207], 0
	v_mfma_f32_16x16x32_bf16 v[46:49], v[168:171], v[204:207], 0
	v_mfma_f32_16x16x32_bf16 v[38:41], v[160:163], v[212:215], 0
	v_mfma_f32_16x16x32_bf16 v[30:33], v[168:171], v[212:215], 0
	v_mfma_f32_16x16x32_bf16 v[22:25], v[160:163], v[220:223], 0
	v_mfma_f32_16x16x32_bf16 v[14:17], v[168:171], v[220:223], 0
	v_mfma_f32_16x16x32_bf16 v[62:65], v[164:167], v[200:203], v[62:65]
	v_mfma_f32_16x16x32_bf16 v[58:61], v[174:177], v[200:203], v[58:61]
	v_mfma_f32_16x16x32_bf16 v[54:57], v[164:167], v[208:211], v[54:57]
	v_mfma_f32_16x16x32_bf16 v[46:49], v[174:177], v[208:211], v[46:49]
	v_mfma_f32_16x16x32_bf16 v[38:41], v[164:167], v[216:219], v[38:41]
	v_mfma_f32_16x16x32_bf16 v[30:33], v[174:177], v[216:219], v[30:33]
	v_mfma_f32_16x16x32_bf16 v[22:25], v[164:167], v[224:227], v[22:25]
	v_mfma_f32_16x16x32_bf16 v[14:17], v[174:177], v[224:227], v[14:17]
	v_mfma_f32_16x16x32_bf16 v[50:53], v[178:181], v[196:199], 0
	v_mfma_f32_16x16x32_bf16 v[42:45], v[188:191], v[196:199], 0
	v_mfma_f32_16x16x32_bf16 v[34:37], v[178:181], v[204:207], 0
	v_mfma_f32_16x16x32_bf16 v[26:29], v[188:191], v[204:207], 0
	v_mfma_f32_16x16x32_bf16 v[18:21], v[178:181], v[212:215], 0
	v_mfma_f32_16x16x32_bf16 v[10:13], v[188:191], v[212:215], 0
	v_mfma_f32_16x16x32_bf16 v[6:9], v[178:181], v[220:223], 0
	v_mfma_f32_16x16x32_bf16 v[2:5], v[188:191], v[220:223], 0
	v_mfma_f32_16x16x32_bf16 v[50:53], v[184:187], v[200:203], v[50:53]
	v_mfma_f32_16x16x32_bf16 v[42:45], v[192:195], v[200:203], v[42:45]
	v_mfma_f32_16x16x32_bf16 v[34:37], v[184:187], v[208:211], v[34:37]
	v_mfma_f32_16x16x32_bf16 v[26:29], v[192:195], v[208:211], v[26:29]
	v_mfma_f32_16x16x32_bf16 v[18:21], v[184:187], v[216:219], v[18:21]
	v_mfma_f32_16x16x32_bf16 v[10:13], v[192:195], v[216:219], v[10:13]
	v_mfma_f32_16x16x32_bf16 v[6:9], v[184:187], v[224:227], v[6:9]
	v_mfma_f32_16x16x32_bf16 v[2:5], v[192:195], v[224:227], v[2:5]
	s_barrier
; #define PG8_STAGE(bufoff, gbase, voff) do { _Pragma("unroll") for (int _i = 0; _i < 2; ++_i) \
;         __builtin_amdgcn_global_load_lds((const unsigned*)((const char*)(gbase) + (voff)[_i]), (LAS unsigned*)(lds + (bufoff) + ldsw + _i * 8192), 16, 0, 0); } while (0)
; #define PG8_LDA(dst, b, h) do { _Pragma("unroll") for (int m = 0; m < 4; ++m) _Pragma("unroll") for (int k = 0; k < 2; ++k) dst[m][k] = *(const LAS bf16x8*)(lds + PG8_SA(b, h) + aoff + m * 2048 + k * 1024); } while (0)
; #define PG8_LDB(dst, b, h) do { _Pragma("unroll") for (int n = 0; n < 2; ++n) _Pragma("unroll") for (int k = 0; k < 2; ++k) dst[n][k] = *(const LAS bf16x8*)(lds + PG8_SB(b, h) + boff + n * 2048 + k * 1024); } while (0)
; #define PG8_MMA(ai, bj, At, Bt) do { __builtin_amdgcn_s_setprio(1); _Pragma("unroll") for (int m = 0; m < 4; ++m) _Pragma("unroll") for (int n = 0; n < 2; ++n) _Pragma("unroll") for (int k = 0; k < 2; ++k) \
;         acc[ai][bj][m][n] = __builtin_amdgcn_mfma_f32_16x16x32_bf16(Bt[n][k], At[m][k], acc[ai][bj][m][n], 0, 0, 0); __builtin_amdgcn_s_setprio(0); } while (0)
; #define PG8_WAIT_V(n) asm volatile("s_waitcnt vmcnt(" #n ")" ::: "memory")
; #define PG8_WAIT_L(n) asm volatile("s_waitcnt lgkmcnt(" #n ")" ::: "memory")
; #define PG8_BAR __builtin_amdgcn_s_barrier()
; #define PG8_SCHED __builtin_amdgcn_sched_barrier(0)
; template <class Epi, bool ALIGN_EPI = PG8_ALIGN, bool SP2 = PG8_SP2>
; __device__ __forceinline__ void gemm_phase(LAS uchar* lds, const Gemm g, const StaticOrder& S, const Epi& E) {
;     ...
;             PG8_LDB(B0, 1, 0); PG8_LDB(B1, 1, 1); PG8_SCHED; PG8_LDA(At, 1, 0); PG8_STAGE(PG8_SA(0, 1), a2 + hstepA, voffA);
;             PG8_WAIT_V(8); PG8_WAIT_L(0); PG8_BAR; PG8_MMA(0, 0, At, B0); PG8_MMA(0, 1, At, B1); PG8_BAR; PG8_SCHED;
;             PG8_LDA(At, 1, 1); PG8_STAGE(PG8_SB(1, 0), b3, voffB); PG8_STAGE(PG8_SB(1, 1), b3 + hstepB, voffB); PG8_STAGE(PG8_SA(1, 0), a3, voffA);
;             PG8_WAIT_V(8); PG8_WAIT_L(0); PG8_BAR; PG8_MMA(1, 0, At, B0); PG8_MMA(1, 1, At, B1); PG8_BAR; PG8_SCHED;
	s_setprio 0
	s_add_i32 s39, 0, 0x18000
	s_add_i32 s40, 0, 0x1c000
	v_add_u32_e32 v174, s39, v139
	v_add_u32_e32 v192, s40, v139
	ds_read_b128 v[160:163], v174
	ds_read_b128 v[164:167], v174 offset:1024
	ds_read_b128 v[168:171], v174 offset:2048
	ds_read_b128 v[174:177], v174 offset:3072
	ds_read_b128 v[178:181], v192
	ds_read_b128 v[184:187], v192 offset:1024
	ds_read_b128 v[188:191], v192 offset:2048
	ds_read_b128 v[192:195], v192 offset:3072
	s_add_u32 s12, s18, 0x44000
	s_addc_u32 s13, s19, 0
	s_mov_b32 m0, s25
	ds_read_b128 v[196:199], v173 offset:32768
	ds_read_b128 v[200:203], v173 offset:33792
	ds_read_b128 v[204:207], v173 offset:34816
	ds_read_b128 v[208:211], v173 offset:35840
	ds_read_b128 v[212:215], v173 offset:36864
	ds_read_b128 v[216:219], v173 offset:37888
	ds_read_b128 v[220:223], v173 offset:38912
	ds_read_b128 v[224:227], v173 offset:39936
	global_load_lds_dwordx4 v152, s[12:13]
	s_mov_b32 m0, s26
	s_nop 0
	global_load_lds_dwordx4 v132, s[12:13]
	s_waitcnt vmcnt(8)
	s_waitcnt lgkmcnt(0)
	s_setprio 1
	s_barrier
	v_mfma_f32_16x16x32_bf16 v[126:129], v[160:163], v[196:199], v[126:129]
	v_mfma_f32_16x16x32_bf16 v[122:125], v[168:171], v[196:199], v[122:125]
	v_mfma_f32_16x16x32_bf16 v[118:121], v[160:163], v[204:207], v[118:121]
	v_mfma_f32_16x16x32_bf16 v[110:113], v[168:171], v[204:207], v[110:113]
	v_mfma_f32_16x16x32_bf16 v[102:105], v[160:163], v[212:215], v[102:105]
	v_mfma_f32_16x16x32_bf16 v[94:97], v[168:171], v[212:215], v[94:97]
	v_mfma_f32_16x16x32_bf16 v[86:89], v[160:163], v[220:223], v[86:89]
	v_mfma_f32_16x16x32_bf16 v[78:81], v[168:171], v[220:223], v[78:81]
	v_mfma_f32_16x16x32_bf16 v[126:129], v[164:167], v[200:203], v[126:129]
	v_mfma_f32_16x16x32_bf16 v[122:125], v[174:177], v[200:203], v[122:125]
	v_mfma_f32_16x16x32_bf16 v[118:121], v[164:167], v[208:211], v[118:121]
	v_mfma_f32_16x16x32_bf16 v[110:113], v[174:177], v[208:211], v[110:113]
	v_mfma_f32_16x16x32_bf16 v[102:105], v[164:167], v[216:219], v[102:105]
	v_mfma_f32_16x16x32_bf16 v[94:97], v[174:177], v[216:219], v[94:97]
	v_mfma_f32_16x16x32_bf16 v[86:89], v[164:167], v[224:227], v[86:89]
	v_mfma_f32_16x16x32_bf16 v[78:81], v[174:177], v[224:227], v[78:81]
	v_mfma_f32_16x16x32_bf16 v[114:117], v[178:181], v[196:199], v[114:117]
	v_mfma_f32_16x16x32_bf16 v[106:109], v[188:191], v[196:199], v[106:109]
	v_mfma_f32_16x16x32_bf16 v[98:101], v[178:181], v[204:207], v[98:101]
	v_mfma_f32_16x16x32_bf16 v[90:93], v[188:191], v[204:207], v[90:93]
	v_mfma_f32_16x16x32_bf16 v[82:85], v[178:181], v[212:215], v[82:85]
	v_mfma_f32_16x16x32_bf16 v[74:77], v[188:191], v[212:215], v[74:77]
	v_mfma_f32_16x16x32_bf16 v[70:73], v[178:181], v[220:223], v[70:73]
	v_mfma_f32_16x16x32_bf16 v[66:69], v[188:191], v[220:223], v[66:69]
	v_mfma_f32_16x16x32_bf16 v[114:117], v[184:187], v[200:203], v[114:117]
	v_mfma_f32_16x16x32_bf16 v[106:109], v[192:195], v[200:203], v[106:109]
	v_mfma_f32_16x16x32_bf16 v[98:101], v[184:187], v[208:211], v[98:101]
	v_mfma_f32_16x16x32_bf16 v[90:93], v[192:195], v[208:211], v[90:93]
	v_mfma_f32_16x16x32_bf16 v[82:85], v[184:187], v[216:219], v[82:85]
	v_mfma_f32_16x16x32_bf16 v[74:77], v[192:195], v[216:219], v[74:77]
	v_mfma_f32_16x16x32_bf16 v[70:73], v[184:187], v[224:227], v[70:73]
	v_mfma_f32_16x16x32_bf16 v[66:69], v[192:195], v[224:227], v[66:69]
	s_barrier
	s_setprio 0
	s_add_i32 s12, s39, s21
	s_add_i32 m0, s12, 0xffffff80
	ds_read_b128 v[196:199], v173 offset:49152
	ds_read_b128 v[200:203], v173 offset:50176
	ds_read_b128 v[204:207], v173 offset:51200
	ds_read_b128 v[208:211], v173 offset:52224
	ds_read_b128 v[212:215], v173 offset:53248
	ds_read_b128 v[216:219], v173 offset:54272
	ds_read_b128 v[220:223], v173 offset:55296
	ds_read_b128 v[224:227], v173 offset:56320
	global_load_lds_dwordx4 v134, s[16:17] offset:128
	s_add_i32 m0, s12, 0x1f80
	s_add_u32 s12, s16, 0x44080
	s_addc_u32 s13, s17, 0
	global_load_lds_dwordx4 v130, s[16:17] offset:128
	s_add_i32 s16, s40, s21
	s_mov_b32 m0, s16
	s_nop 0
	global_load_lds_dwordx4 v134, s[12:13]
	s_add_i32 m0, s16, 0x2000
	s_nop 0
	global_load_lds_dwordx4 v130, s[12:13]
	s_add_i32 m0, s27, 0xffffff80
	s_nop 0
	global_load_lds_dwordx4 v152, s[18:19] offset:128
	s_add_i32 m0, s28, 0xffffff80
	s_nop 0
	global_load_lds_dwordx4 v132, s[18:19] offset:128
	s_waitcnt vmcnt(8)
	s_waitcnt lgkmcnt(0)
	s_setprio 1
	s_barrier
	v_mfma_f32_16x16x32_bf16 v[62:65], v[160:163], v[196:199], v[62:65]
	v_mfma_f32_16x16x32_bf16 v[58:61], v[168:171], v[196:199], v[58:61]
	v_mfma_f32_16x16x32_bf16 v[54:57], v[160:163], v[204:207], v[54:57]
	v_mfma_f32_16x16x32_bf16 v[46:49], v[168:171], v[204:207], v[46:49]
	v_mfma_f32_16x16x32_bf16 v[38:41], v[160:163], v[212:215], v[38:41]
	v_mfma_f32_16x16x32_bf16 v[30:33], v[168:171], v[212:215], v[30:33]
	v_mfma_f32_16x16x32_bf16 v[22:25], v[160:163], v[220:223], v[22:25]
	v_mfma_f32_16x16x32_bf16 v[14:17], v[168:171], v[220:223], v[14:17]
	v_mfma_f32_16x16x32_bf16 v[62:65], v[164:167], v[200:203], v[62:65]
	v_mfma_f32_16x16x32_bf16 v[58:61], v[174:177], v[200:203], v[58:61]
	v_mfma_f32_16x16x32_bf16 v[54:57], v[164:167], v[208:211], v[54:57]
	v_mfma_f32_16x16x32_bf16 v[46:49], v[174:177], v[208:211], v[46:49]
	v_mfma_f32_16x16x32_bf16 v[38:41], v[164:167], v[216:219], v[38:41]
	v_mfma_f32_16x16x32_bf16 v[30:33], v[174:177], v[216:219], v[30:33]
	v_mfma_f32_16x16x32_bf16 v[22:25], v[164:167], v[224:227], v[22:25]
	v_mfma_f32_16x16x32_bf16 v[14:17], v[174:177], v[224:227], v[14:17]
	v_mfma_f32_16x16x32_bf16 v[50:53], v[178:181], v[196:199], v[50:53]
	v_mfma_f32_16x16x32_bf16 v[42:45], v[188:191], v[196:199], v[42:45]
	v_mfma_f32_16x16x32_bf16 v[34:37], v[178:181], v[204:207], v[34:37]
	v_mfma_f32_16x16x32_bf16 v[26:29], v[188:191], v[204:207], v[26:29]
	v_mfma_f32_16x16x32_bf16 v[18:21], v[178:181], v[212:215], v[18:21]
	v_mfma_f32_16x16x32_bf16 v[10:13], v[188:191], v[212:215], v[10:13]
	v_mfma_f32_16x16x32_bf16 v[6:9], v[178:181], v[220:223], v[6:9]
	v_mfma_f32_16x16x32_bf16 v[2:5], v[188:191], v[220:223], v[2:5]
	v_mfma_f32_16x16x32_bf16 v[50:53], v[184:187], v[200:203], v[50:53]
	v_mfma_f32_16x16x32_bf16 v[42:45], v[192:195], v[200:203], v[42:45]
	v_mfma_f32_16x16x32_bf16 v[34:37], v[184:187], v[208:211], v[34:37]
	v_mfma_f32_16x16x32_bf16 v[26:29], v[192:195], v[208:211], v[26:29]
	v_mfma_f32_16x16x32_bf16 v[18:21], v[184:187], v[216:219], v[18:21]
	v_mfma_f32_16x16x32_bf16 v[10:13], v[192:195], v[216:219], v[10:13]
	v_mfma_f32_16x16x32_bf16 v[6:9], v[184:187], v[224:227], v[6:9]
	v_mfma_f32_16x16x32_bf16 v[2:5], v[192:195], v[224:227], v[2:5]
	s_barrier
	s_setprio 0
	s_add_i32 s38, s38, 2
	s_add_u32 s36, s36, 0x100
	s_addc_u32 s37, s37, 0
	s_cmp_gt_u32 s38, 13
	s_mov_b64 s[12:13], s[14:15]
; #define PG8_STAGE(bufoff, gbase, voff) do { _Pragma("unroll") for (int _i = 0; _i < 2; ++_i) \
;         __builtin_amdgcn_global_load_lds((const unsigned*)((const char*)(gbase) + (voff)[_i]), (LAS unsigned*)(lds + (bufoff) + ldsw + _i * 8192), 16, 0, 0); } while (0)
; #define PG8_LDA(dst, b, h) do { _Pragma("unroll") for (int m = 0; m < 4; ++m) _Pragma("unroll") for (int k = 0; k < 2; ++k) dst[m][k] = *(const LAS bf16x8*)(lds + PG8_SA(b, h) + aoff + m * 2048 + k * 1024); } while (0)
; #define PG8_LDB(dst, b, h) do { _Pragma("unroll") for (int n = 0; n < 2; ++n) _Pragma("unroll") for (int k = 0; k < 2; ++k) dst[n][k] = *(const LAS bf16x8*)(lds + PG8_SB(b, h) + boff + n * 2048 + k * 1024); } while (0)
; #define PG8_MMA(ai, bj, At, Bt) do { __builtin_amdgcn_s_setprio(1); _Pragma("unroll") for (int m = 0; m < 4; ++m) _Pragma("unroll") for (int n = 0; n < 2; ++n) _Pragma("unroll") for (int k = 0; k < 2; ++k) \
;         acc[ai][bj][m][n] = __builtin_amdgcn_mfma_f32_16x16x32_bf16(Bt[n][k], At[m][k], acc[ai][bj][m][n], 0, 0, 0); __builtin_amdgcn_s_setprio(0); } while (0)
; #define PG8_WAIT_V(n) asm volatile("s_waitcnt vmcnt(" #n ")" ::: "memory")
; #define PG8_WAIT_L(n) asm volatile("s_waitcnt lgkmcnt(" #n ")" ::: "memory")
; #define PG8_BAR __builtin_amdgcn_s_barrier()
; template <class Epi, bool ALIGN_EPI = PG8_ALIGN, bool SP2 = PG8_SP2>
; __device__ __forceinline__ void gemm_phase(LAS uchar* lds, const Gemm g, const StaticOrder& S, const Epi& E) {
;     ...
;         for (int t = tb; t < tb + tblk; t += 2) {
;             const bool last = (t == nt - 2);
;             const char* a1 = cA + (size_t)(t + 1) * kstep;
;             const char* a2 = last ? nA : cA + (size_t)(t + 2) * kstep; const char* b2 = last ? nB : cB + (size_t)(t + 2) * kstep;
;             const char* a3 = a2 + kstep; const char* b3 = b2 + kstep;
;             if constexpr (SP2) {
;             PG8_LDB(B0, 0, 0); PG8_LDB(B1, 0, 1); PG8_SCHED; PG8_LDA(At, 0, 0); PG8_STAGE(PG8_SA(1, 1), a1 + hstepA, voffA);
;             PG8_WAIT_V(8); PG8_WAIT_L(0); PG8_BAR; PG8_MMA(0, 0, At, B0); PG8_MMA(0, 1, At, B1); PG8_BAR; PG8_SCHED;
;             PG8_LDA(At, 0, 1); PG8_STAGE(PG8_SB(0, 0), b2, voffB); PG8_STAGE(PG8_SB(0, 1), b2 + hstepB, voffB); PG8_STAGE(PG8_SA(0, 0), a2, voffA);
;             PG8_WAIT_V(8); PG8_WAIT_L(0); PG8_BAR; PG8_MMA(1, 0, At, B0); PG8_MMA(1, 1, At, B1); PG8_BAR; PG8_SCHED;
.LBB0_669:
	s_add_u32 s14, s12, 0x100
	s_addc_u32 s15, s13, 0
	s_add_i32 s39, 0, 0x10000
	s_cmp_eq_u32 s38, 12
	s_cselect_b32 s19, s5, s15
	s_cselect_b32 s18, s4, s14
	s_cselect_b32 s17, s11, s37
	s_cselect_b32 s16, s10, s36
	s_add_i32 s40, 0, 0x14000
	v_add_u32_e32 v174, s39, v139
	v_add_u32_e32 v192, s40, v139
	ds_read_b128 v[160:163], v174
	ds_read_b128 v[164:167], v174 offset:1024
	ds_read_b128 v[168:171], v174 offset:2048
	ds_read_b128 v[174:177], v174 offset:3072
	ds_read_b128 v[178:181], v192
	ds_read_b128 v[184:187], v192 offset:1024
	ds_read_b128 v[188:191], v192 offset:2048
	ds_read_b128 v[192:195], v192 offset:3072
	s_add_i32 m0, s23, 0xc000
	ds_read_b128 v[196:199], v173
	ds_read_b128 v[200:203], v173 offset:1024
	ds_read_b128 v[204:207], v173 offset:2048
	ds_read_b128 v[208:211], v173 offset:3072
	ds_read_b128 v[212:215], v173 offset:4096
	ds_read_b128 v[216:219], v173 offset:5120
	ds_read_b128 v[220:223], v173 offset:6144
	ds_read_b128 v[224:227], v173 offset:7168
	global_load_lds_dwordx4 v156, s[12:13]
	s_add_i32 m0, s23, 0xe000
	s_nop 0
	global_load_lds_dwordx4 v158, s[12:13]
	s_waitcnt vmcnt(8)
	s_waitcnt lgkmcnt(0)
	s_setprio 1
	s_barrier
	v_mfma_f32_16x16x32_bf16 v[126:129], v[160:163], v[196:199], v[126:129]
	v_mfma_f32_16x16x32_bf16 v[122:125], v[168:171], v[196:199], v[122:125]
	v_mfma_f32_16x16x32_bf16 v[118:121], v[160:163], v[204:207], v[118:121]
	v_mfma_f32_16x16x32_bf16 v[110:113], v[168:171], v[204:207], v[110:113]
	v_mfma_f32_16x16x32_bf16 v[102:105], v[160:163], v[212:215], v[102:105]
	v_mfma_f32_16x16x32_bf16 v[94:97], v[168:171], v[212:215], v[94:97]
	v_mfma_f32_16x16x32_bf16 v[86:89], v[160:163], v[220:223], v[86:89]
	v_mfma_f32_16x16x32_bf16 v[78:81], v[168:171], v[220:223], v[78:81]
	v_mfma_f32_16x16x32_bf16 v[126:129], v[164:167], v[200:203], v[126:129]
	v_mfma_f32_16x16x32_bf16 v[122:125], v[174:177], v[200:203], v[122:125]
	v_mfma_f32_16x16x32_bf16 v[118:121], v[164:167], v[208:211], v[118:121]
	v_mfma_f32_16x16x32_bf16 v[110:113], v[174:177], v[208:211], v[110:113]
	v_mfma_f32_16x16x32_bf16 v[102:105], v[164:167], v[216:219], v[102:105]
	v_mfma_f32_16x16x32_bf16 v[94:97], v[174:177], v[216:219], v[94:97]
	v_mfma_f32_16x16x32_bf16 v[86:89], v[164:167], v[224:227], v[86:89]
	v_mfma_f32_16x16x32_bf16 v[78:81], v[174:177], v[224:227], v[78:81]
	v_mfma_f32_16x16x32_bf16 v[114:117], v[178:181], v[196:199], v[114:117]
	v_mfma_f32_16x16x32_bf16 v[106:109], v[188:191], v[196:199], v[106:109]
	v_mfma_f32_16x16x32_bf16 v[98:101], v[178:181], v[204:207], v[98:101]
	v_mfma_f32_16x16x32_bf16 v[90:93], v[188:191], v[204:207], v[90:93]
	v_mfma_f32_16x16x32_bf16 v[82:85], v[178:181], v[212:215], v[82:85]
	v_mfma_f32_16x16x32_bf16 v[74:77], v[188:191], v[212:215], v[74:77]
	v_mfma_f32_16x16x32_bf16 v[70:73], v[178:181], v[220:223], v[70:73]
	v_mfma_f32_16x16x32_bf16 v[66:69], v[188:191], v[220:223], v[66:69]
	v_mfma_f32_16x16x32_bf16 v[114:117], v[184:187], v[200:203], v[114:117]
	v_mfma_f32_16x16x32_bf16 v[106:109], v[192:195], v[200:203], v[106:109]
	v_mfma_f32_16x16x32_bf16 v[98:101], v[184:187], v[208:211], v[98:101]
	v_mfma_f32_16x16x32_bf16 v[90:93], v[192:195], v[208:211], v[90:93]
	v_mfma_f32_16x16x32_bf16 v[82:85], v[184:187], v[216:219], v[82:85]
	v_mfma_f32_16x16x32_bf16 v[74:77], v[192:195], v[216:219], v[74:77]
	v_mfma_f32_16x16x32_bf16 v[70:73], v[184:187], v[224:227], v[70:73]
	v_mfma_f32_16x16x32_bf16 v[66:69], v[192:195], v[224:227], v[66:69]
	s_barrier
	s_setprio 0
	s_add_i32 s12, s39, s21
	s_mov_b32 m0, s12
	ds_read_b128 v[196:199], v173 offset:16384
	ds_read_b128 v[200:203], v173 offset:17408
	ds_read_b128 v[204:207], v173 offset:18432
	ds_read_b128 v[208:211], v173 offset:19456
	ds_read_b128 v[212:215], v173 offset:20480
	ds_read_b128 v[216:219], v173 offset:21504
	ds_read_b128 v[220:223], v173 offset:22528
	ds_read_b128 v[224:227], v173 offset:23552
	global_load_lds_dwordx4 v134, s[16:17]
	s_add_i32 m0, s12, 0x2000
	s_add_u32 s12, s16, 0x44000
	s_addc_u32 s13, s17, 0
	s_add_i32 s39, s40, s21
	global_load_lds_dwordx4 v130, s[16:17]
	s_mov_b32 m0, s39
	s_nop 0
	global_load_lds_dwordx4 v134, s[12:13]
	s_add_i32 m0, s39, 0x2000
	s_nop 0
	global_load_lds_dwordx4 v130, s[12:13]
	s_mov_b32 m0, s23
	s_nop 0
	global_load_lds_dwordx4 v152, s[18:19]
	s_mov_b32 m0, s24
	s_nop 0
	global_load_lds_dwordx4 v132, s[18:19]
	s_waitcnt vmcnt(8)
	s_waitcnt lgkmcnt(0)
	s_setprio 1
	s_barrier
	v_mfma_f32_16x16x32_bf16 v[62:65], v[160:163], v[196:199], v[62:65]
	v_mfma_f32_16x16x32_bf16 v[58:61], v[168:171], v[196:199], v[58:61]
	v_mfma_f32_16x16x32_bf16 v[54:57], v[160:163], v[204:207], v[54:57]
	v_mfma_f32_16x16x32_bf16 v[46:49], v[168:171], v[204:207], v[46:49]
	v_mfma_f32_16x16x32_bf16 v[38:41], v[160:163], v[212:215], v[38:41]
	v_mfma_f32_16x16x32_bf16 v[30:33], v[168:171], v[212:215], v[30:33]
	v_mfma_f32_16x16x32_bf16 v[22:25], v[160:163], v[220:223], v[22:25]
	v_mfma_f32_16x16x32_bf16 v[14:17], v[168:171], v[220:223], v[14:17]
	v_mfma_f32_16x16x32_bf16 v[62:65], v[164:167], v[200:203], v[62:65]
	v_mfma_f32_16x16x32_bf16 v[58:61], v[174:177], v[200:203], v[58:61]
	v_mfma_f32_16x16x32_bf16 v[54:57], v[164:167], v[208:211], v[54:57]
	v_mfma_f32_16x16x32_bf16 v[46:49], v[174:177], v[208:211], v[46:49]
	v_mfma_f32_16x16x32_bf16 v[38:41], v[164:167], v[216:219], v[38:41]
	v_mfma_f32_16x16x32_bf16 v[30:33], v[174:177], v[216:219], v[30:33]
	v_mfma_f32_16x16x32_bf16 v[22:25], v[164:167], v[224:227], v[22:25]
	v_mfma_f32_16x16x32_bf16 v[14:17], v[174:177], v[224:227], v[14:17]
	v_mfma_f32_16x16x32_bf16 v[50:53], v[178:181], v[196:199], v[50:53]
	v_mfma_f32_16x16x32_bf16 v[42:45], v[188:191], v[196:199], v[42:45]
	v_mfma_f32_16x16x32_bf16 v[34:37], v[178:181], v[204:207], v[34:37]
	v_mfma_f32_16x16x32_bf16 v[26:29], v[188:191], v[204:207], v[26:29]
	v_mfma_f32_16x16x32_bf16 v[18:21], v[178:181], v[212:215], v[18:21]
	v_mfma_f32_16x16x32_bf16 v[10:13], v[188:191], v[212:215], v[10:13]
	v_mfma_f32_16x16x32_bf16 v[6:9], v[178:181], v[220:223], v[6:9]
	v_mfma_f32_16x16x32_bf16 v[2:5], v[188:191], v[220:223], v[2:5]
	v_mfma_f32_16x16x32_bf16 v[50:53], v[184:187], v[200:203], v[50:53]
	v_mfma_f32_16x16x32_bf16 v[42:45], v[192:195], v[200:203], v[42:45]
	v_mfma_f32_16x16x32_bf16 v[34:37], v[184:187], v[208:211], v[34:37]
	v_mfma_f32_16x16x32_bf16 v[26:29], v[192:195], v[208:211], v[26:29]
	v_mfma_f32_16x16x32_bf16 v[18:21], v[184:187], v[216:219], v[18:21]
	v_mfma_f32_16x16x32_bf16 v[10:13], v[192:195], v[216:219], v[10:13]
	v_mfma_f32_16x16x32_bf16 v[6:9], v[184:187], v[224:227], v[6:9]
	v_mfma_f32_16x16x32_bf16 v[2:5], v[192:195], v[224:227], v[2:5]
	s_barrier
; #define PG8_STAGE(bufoff, gbase, voff) do { _Pragma("unroll") for (int _i = 0; _i < 2; ++_i) \
;         __builtin_amdgcn_global_load_lds((const unsigned*)((const char*)(gbase) + (voff)[_i]), (LAS unsigned*)(lds + (bufoff) + ldsw + _i * 8192), 16, 0, 0); } while (0)
; #define PG8_LDA(dst, b, h) do { _Pragma("unroll") for (int m = 0; m < 4; ++m) _Pragma("unroll") for (int k = 0; k < 2; ++k) dst[m][k] = *(const LAS bf16x8*)(lds + PG8_SA(b, h) + aoff + m * 2048 + k * 1024); } while (0)
; #define PG8_LDB(dst, b, h) do { _Pragma("unroll") for (int n = 0; n < 2; ++n) _Pragma("unroll") for (int k = 0; k < 2; ++k) dst[n][k] = *(const LAS bf16x8*)(lds + PG8_SB(b, h) + boff + n * 2048 + k * 1024); } while (0)
; #define PG8_MMA(ai, bj, At, Bt) do { __builtin_amdgcn_s_setprio(1); _Pragma("unroll") for (int m = 0; m < 4; ++m) _Pragma("unroll") for (int n = 0; n < 2; ++n) _Pragma("unroll") for (int k = 0; k < 2; ++k) \
;         acc[ai][bj][m][n] = __builtin_amdgcn_mfma_f32_16x16x32_bf16(Bt[n][k], At[m][k], acc[ai][bj][m][n], 0, 0, 0); __builtin_amdgcn_s_setprio(0); } while (0)
; #define PG8_WAIT_V(n) asm volatile("s_waitcnt vmcnt(" #n ")" ::: "memory")
; #define PG8_WAIT_L(n) asm volatile("s_waitcnt lgkmcnt(" #n ")" ::: "memory")
; #define PG8_BAR __builtin_amdgcn_s_barrier()
; #define PG8_SCHED __builtin_amdgcn_sched_barrier(0)
; template <class Epi, bool ALIGN_EPI = PG8_ALIGN, bool SP2 = PG8_SP2>
; __device__ __forceinline__ void gemm_phase(LAS uchar* lds, const Gemm g, const StaticOrder& S, const Epi& E) {
;     ...
;             PG8_LDB(B0, 1, 0); PG8_LDB(B1, 1, 1); PG8_SCHED; PG8_LDA(At, 1, 0); PG8_STAGE(PG8_SA(0, 1), a2 + hstepA, voffA);
;             PG8_WAIT_V(8); PG8_WAIT_L(0); PG8_BAR; PG8_MMA(0, 0, At, B0); PG8_MMA(0, 1, At, B1); PG8_BAR; PG8_SCHED;
;             PG8_LDA(At, 1, 1); PG8_STAGE(PG8_SB(1, 0), b3, voffB); PG8_STAGE(PG8_SB(1, 1), b3 + hstepB, voffB); PG8_STAGE(PG8_SA(1, 0), a3, voffA);
;             PG8_WAIT_V(8); PG8_WAIT_L(0); PG8_BAR; PG8_MMA(1, 0, At, B0); PG8_MMA(1, 1, At, B1); PG8_BAR; PG8_SCHED;
;     ...
;         if constexpr (ALIGN_EPI) { if (wr == 0) PG8_BAR; }
	s_setprio 0
	s_add_i32 s39, 0, 0x18000
	s_add_i32 s40, 0, 0x1c000
	v_add_u32_e32 v174, s39, v139
	v_add_u32_e32 v192, s40, v139
	ds_read_b128 v[160:163], v174
	ds_read_b128 v[164:167], v174 offset:1024
	ds_read_b128 v[168:171], v174 offset:2048
	ds_read_b128 v[174:177], v174 offset:3072
	ds_read_b128 v[178:181], v192
	ds_read_b128 v[184:187], v192 offset:1024
	ds_read_b128 v[188:191], v192 offset:2048
	ds_read_b128 v[192:195], v192 offset:3072
	s_add_u32 s12, s18, 0x44000
	s_addc_u32 s13, s19, 0
	s_mov_b32 m0, s25
	ds_read_b128 v[196:199], v173 offset:32768
	ds_read_b128 v[200:203], v173 offset:33792
	ds_read_b128 v[204:207], v173 offset:34816
	ds_read_b128 v[208:211], v173 offset:35840
	ds_read_b128 v[212:215], v173 offset:36864
	ds_read_b128 v[216:219], v173 offset:37888
	ds_read_b128 v[220:223], v173 offset:38912
	ds_read_b128 v[224:227], v173 offset:39936
	global_load_lds_dwordx4 v152, s[12:13]
	s_mov_b32 m0, s26
	s_nop 0
	global_load_lds_dwordx4 v132, s[12:13]
	s_waitcnt vmcnt(8)
	s_waitcnt lgkmcnt(0)
	s_setprio 1
	s_barrier
	v_mfma_f32_16x16x32_bf16 v[126:129], v[160:163], v[196:199], v[126:129]
	v_mfma_f32_16x16x32_bf16 v[122:125], v[168:171], v[196:199], v[122:125]
	v_mfma_f32_16x16x32_bf16 v[118:121], v[160:163], v[204:207], v[118:121]
	v_mfma_f32_16x16x32_bf16 v[110:113], v[168:171], v[204:207], v[110:113]
	v_mfma_f32_16x16x32_bf16 v[102:105], v[160:163], v[212:215], v[102:105]
	v_mfma_f32_16x16x32_bf16 v[94:97], v[168:171], v[212:215], v[94:97]
	v_mfma_f32_16x16x32_bf16 v[86:89], v[160:163], v[220:223], v[86:89]
	v_mfma_f32_16x16x32_bf16 v[78:81], v[168:171], v[220:223], v[78:81]
	v_mfma_f32_16x16x32_bf16 v[126:129], v[164:167], v[200:203], v[126:129]
	v_mfma_f32_16x16x32_bf16 v[122:125], v[174:177], v[200:203], v[122:125]
	v_mfma_f32_16x16x32_bf16 v[118:121], v[164:167], v[208:211], v[118:121]
	v_mfma_f32_16x16x32_bf16 v[110:113], v[174:177], v[208:211], v[110:113]
	v_mfma_f32_16x16x32_bf16 v[102:105], v[164:167], v[216:219], v[102:105]
	v_mfma_f32_16x16x32_bf16 v[94:97], v[174:177], v[216:219], v[94:97]
	v_mfma_f32_16x16x32_bf16 v[86:89], v[164:167], v[224:227], v[86:89]
	v_mfma_f32_16x16x32_bf16 v[78:81], v[174:177], v[224:227], v[78:81]
	v_mfma_f32_16x16x32_bf16 v[114:117], v[178:181], v[196:199], v[114:117]
	v_mfma_f32_16x16x32_bf16 v[106:109], v[188:191], v[196:199], v[106:109]
	v_mfma_f32_16x16x32_bf16 v[98:101], v[178:181], v[204:207], v[98:101]
	v_mfma_f32_16x16x32_bf16 v[90:93], v[188:191], v[204:207], v[90:93]
	v_mfma_f32_16x16x32_bf16 v[82:85], v[178:181], v[212:215], v[82:85]
	v_mfma_f32_16x16x32_bf16 v[74:77], v[188:191], v[212:215], v[74:77]
	v_mfma_f32_16x16x32_bf16 v[70:73], v[178:181], v[220:223], v[70:73]
	v_mfma_f32_16x16x32_bf16 v[66:69], v[188:191], v[220:223], v[66:69]
	v_mfma_f32_16x16x32_bf16 v[114:117], v[184:187], v[200:203], v[114:117]
	v_mfma_f32_16x16x32_bf16 v[106:109], v[192:195], v[200:203], v[106:109]
	v_mfma_f32_16x16x32_bf16 v[98:101], v[184:187], v[208:211], v[98:101]
	v_mfma_f32_16x16x32_bf16 v[90:93], v[192:195], v[208:211], v[90:93]
	v_mfma_f32_16x16x32_bf16 v[82:85], v[184:187], v[216:219], v[82:85]
	v_mfma_f32_16x16x32_bf16 v[74:77], v[192:195], v[216:219], v[74:77]
	v_mfma_f32_16x16x32_bf16 v[70:73], v[184:187], v[224:227], v[70:73]
	v_mfma_f32_16x16x32_bf16 v[66:69], v[192:195], v[224:227], v[66:69]
	s_barrier
	s_setprio 0
	s_add_i32 s12, s39, s21
	s_add_i32 m0, s12, 0xffffff80
	ds_read_b128 v[196:199], v173 offset:49152
	ds_read_b128 v[200:203], v173 offset:50176
	ds_read_b128 v[204:207], v173 offset:51200
	ds_read_b128 v[208:211], v173 offset:52224
	ds_read_b128 v[212:215], v173 offset:53248
	ds_read_b128 v[216:219], v173 offset:54272
	ds_read_b128 v[220:223], v173 offset:55296
	ds_read_b128 v[224:227], v173 offset:56320
	global_load_lds_dwordx4 v134, s[16:17] offset:128
	s_add_i32 m0, s12, 0x1f80
	s_add_u32 s12, s16, 0x44080
	s_addc_u32 s13, s17, 0
	global_load_lds_dwordx4 v130, s[16:17] offset:128
	s_add_i32 s16, s40, s21
	s_mov_b32 m0, s16
	s_nop 0
	global_load_lds_dwordx4 v134, s[12:13]
	s_add_i32 m0, s16, 0x2000
	s_nop 0
	global_load_lds_dwordx4 v130, s[12:13]
	s_add_i32 m0, s27, 0xffffff80
	s_nop 0
	global_load_lds_dwordx4 v152, s[18:19] offset:128
	s_add_i32 m0, s28, 0xffffff80
	s_nop 0
	global_load_lds_dwordx4 v132, s[18:19] offset:128
	s_waitcnt vmcnt(8)
	s_waitcnt lgkmcnt(0)
	s_setprio 1
	s_barrier
	v_mfma_f32_16x16x32_bf16 v[62:65], v[160:163], v[196:199], v[62:65]
	v_mfma_f32_16x16x32_bf16 v[58:61], v[168:171], v[196:199], v[58:61]
	v_mfma_f32_16x16x32_bf16 v[54:57], v[160:163], v[204:207], v[54:57]
	v_mfma_f32_16x16x32_bf16 v[46:49], v[168:171], v[204:207], v[46:49]
	v_mfma_f32_16x16x32_bf16 v[38:41], v[160:163], v[212:215], v[38:41]
	v_mfma_f32_16x16x32_bf16 v[30:33], v[168:171], v[212:215], v[30:33]
	v_mfma_f32_16x16x32_bf16 v[22:25], v[160:163], v[220:223], v[22:25]
	v_mfma_f32_16x16x32_bf16 v[14:17], v[168:171], v[220:223], v[14:17]
	v_mfma_f32_16x16x32_bf16 v[62:65], v[164:167], v[200:203], v[62:65]
	v_mfma_f32_16x16x32_bf16 v[58:61], v[174:177], v[200:203], v[58:61]
	v_mfma_f32_16x16x32_bf16 v[54:57], v[164:167], v[208:211], v[54:57]
	v_mfma_f32_16x16x32_bf16 v[46:49], v[174:177], v[208:211], v[46:49]
	v_mfma_f32_16x16x32_bf16 v[38:41], v[164:167], v[216:219], v[38:41]
	v_mfma_f32_16x16x32_bf16 v[30:33], v[174:177], v[216:219], v[30:33]
	v_mfma_f32_16x16x32_bf16 v[22:25], v[164:167], v[224:227], v[22:25]
	v_mfma_f32_16x16x32_bf16 v[14:17], v[174:177], v[224:227], v[14:17]
	v_mfma_f32_16x16x32_bf16 v[50:53], v[178:181], v[196:199], v[50:53]
	v_mfma_f32_16x16x32_bf16 v[42:45], v[188:191], v[196:199], v[42:45]
	v_mfma_f32_16x16x32_bf16 v[34:37], v[178:181], v[204:207], v[34:37]
	v_mfma_f32_16x16x32_bf16 v[26:29], v[188:191], v[204:207], v[26:29]
	v_mfma_f32_16x16x32_bf16 v[18:21], v[178:181], v[212:215], v[18:21]
	v_mfma_f32_16x16x32_bf16 v[10:13], v[188:191], v[212:215], v[10:13]
	v_mfma_f32_16x16x32_bf16 v[6:9], v[178:181], v[220:223], v[6:9]
	v_mfma_f32_16x16x32_bf16 v[2:5], v[188:191], v[220:223], v[2:5]
	v_mfma_f32_16x16x32_bf16 v[50:53], v[184:187], v[200:203], v[50:53]
	v_mfma_f32_16x16x32_bf16 v[42:45], v[192:195], v[200:203], v[42:45]
	v_mfma_f32_16x16x32_bf16 v[34:37], v[184:187], v[208:211], v[34:37]
	v_mfma_f32_16x16x32_bf16 v[26:29], v[192:195], v[208:211], v[26:29]
	v_mfma_f32_16x16x32_bf16 v[18:21], v[184:187], v[216:219], v[18:21]
	v_mfma_f32_16x16x32_bf16 v[10:13], v[192:195], v[216:219], v[10:13]
	v_mfma_f32_16x16x32_bf16 v[6:9], v[184:187], v[224:227], v[6:9]
	v_mfma_f32_16x16x32_bf16 v[2:5], v[192:195], v[224:227], v[2:5]
	s_barrier
	s_setprio 0
	s_add_i32 s38, s38, 2
	s_add_u32 s36, s36, 0x100
	s_addc_u32 s37, s37, 0
	s_cmp_gt_u32 s38, 13
	s_mov_b64 s[12:13], s[14:15]
	s_cbranch_scc0 .LBB0_669
	s_and_b64 vcc, exec, s[8:9]
	s_cbranch_vccz .LBB0_672
	s_barrier

; #define PG8_STAGE(bufoff, gbase, voff) do { _Pragma("unroll") for (int _i = 0; _i < 2; ++_i) \
;         __builtin_amdgcn_global_load_lds((const unsigned*)((const char*)(gbase) + (voff)[_i]), (LAS unsigned*)(lds + (bufoff) + ldsw + _i * 8192), 16, 0, 0); } while (0)
; #define PG8_LDA(dst, b, h) do { _Pragma("unroll") for (int m = 0; m < 4; ++m) _Pragma("unroll") for (int k = 0; k < 2; ++k) dst[m][k] = *(const LAS bf16x8*)(lds + PG8_SA(b, h) + aoff + m * 2048 + k * 1024); } while (0)
; #define PG8_LDB(dst, b, h) do { _Pragma("unroll") for (int n = 0; n < 2; ++n) _Pragma("unroll") for (int k = 0; k < 2; ++k) dst[n][k] = *(const LAS bf16x8*)(lds + PG8_SB(b, h) + boff + n * 2048 + k * 1024); } while (0)
; #define PG8_MMA(ai, bj, At, Bt) do { __builtin_amdgcn_s_setprio(1); _Pragma("unroll") for (int m = 0; m < 4; ++m) _Pragma("unroll") for (int n = 0; n < 2; ++n) _Pragma("unroll") for (int k = 0; k < 2; ++k) \
;         acc[ai][bj][m][n] = __builtin_amdgcn_mfma_f32_16x16x32_bf16(Bt[n][k], At[m][k], acc[ai][bj][m][n], 0, 0, 0); __builtin_amdgcn_s_setprio(0); } while (0)
; #define PG8_WAIT_V(n) asm volatile("s_waitcnt vmcnt(" #n ")" ::: "memory")
; #define PG8_WAIT_L(n) asm volatile("s_waitcnt lgkmcnt(" #n ")" ::: "memory")
; #define PG8_BAR __builtin_amdgcn_s_barrier()
; template <class Epi, bool ALIGN_EPI = PG8_ALIGN, bool SP2 = PG8_SP2>
; __device__ __forceinline__ void gemm_phase(LAS uchar* lds, const Gemm g, const StaticOrder& S, const Epi& E) {
;     ...
;         for (int t = tb; t < tb + tblk; t += 2) {
;             const bool last = (t == nt - 2);
;             const char* a1 = cA + (size_t)(t + 1) * kstep;
;             const char* a2 = last ? nA : cA + (size_t)(t + 2) * kstep; const char* b2 = last ? nB : cB + (size_t)(t + 2) * kstep;
;             const char* a3 = a2 + kstep; const char* b3 = b2 + kstep;
;             if constexpr (SP2) {
;             PG8_LDB(B0, 0, 0); PG8_LDB(B1, 0, 1); PG8_SCHED; PG8_LDA(At, 0, 0); PG8_STAGE(PG8_SA(1, 1), a1 + hstepA, voffA);
;             PG8_WAIT_V(8); PG8_WAIT_L(0); PG8_BAR; PG8_MMA(0, 0, At, B0); PG8_MMA(0, 1, At, B1); PG8_BAR; PG8_SCHED;
;             PG8_LDA(At, 0, 1); PG8_STAGE(PG8_SB(0, 0), b2, voffB); PG8_STAGE(PG8_SB(0, 1), b2 + hstepB, voffB); PG8_STAGE(PG8_SA(0, 0), a2, voffA);
;             PG8_WAIT_V(8); PG8_WAIT_L(0); PG8_BAR; PG8_MMA(1, 0, At, B0); PG8_MMA(1, 1, At, B1); PG8_BAR; PG8_SCHED;
.LBB0_836:
	s_add_u32 s36, s14, 0x100
	s_addc_u32 s37, s15, 0
	s_mov_b32 s38, -2
	s_add_u32 s14, s12, 0x100
	s_addc_u32 s15, s13, 0
	s_add_i32 s39, 0, 0x10000
	s_cmp_eq_u32 s38, 12
	s_cselect_b32 s19, s5, s15
	s_cselect_b32 s18, s4, s14
	s_cselect_b32 s17, s11, s37
	s_cselect_b32 s16, s10, s36
	s_add_i32 s40, 0, 0x14000
	v_add_u32_e32 v174, s39, v139
	v_add_u32_e32 v192, s40, v139
	ds_read_b128 v[160:163], v174
	ds_read_b128 v[166:169], v174 offset:1024
	ds_read_b128 v[170:173], v174 offset:2048
	ds_read_b128 v[174:177], v174 offset:3072
	ds_read_b128 v[178:181], v192
	ds_read_b128 v[184:187], v192 offset:1024
	ds_read_b128 v[188:191], v192 offset:2048
	ds_read_b128 v[192:195], v192 offset:3072
	s_add_i32 m0, s23, 0xc000
	ds_read_b128 v[196:199], v165
	ds_read_b128 v[200:203], v165 offset:1024
	ds_read_b128 v[204:207], v165 offset:2048
	ds_read_b128 v[208:211], v165 offset:3072
	ds_read_b128 v[212:215], v165 offset:4096
	ds_read_b128 v[216:219], v165 offset:5120
	ds_read_b128 v[220:223], v165 offset:6144
	ds_read_b128 v[224:227], v165 offset:7168
	global_load_lds_dwordx4 v156, s[12:13]
	s_add_i32 m0, s23, 0xe000
	s_nop 0
	global_load_lds_dwordx4 v158, s[12:13]
	s_waitcnt vmcnt(8)
	s_waitcnt lgkmcnt(0)
	s_setprio 1
	s_barrier
	v_mfma_f32_16x16x32_bf16 v[126:129], v[160:163], v[196:199], 0
	v_mfma_f32_16x16x32_bf16 v[122:125], v[170:173], v[196:199], 0
	v_mfma_f32_16x16x32_bf16 v[118:121], v[160:163], v[204:207], 0
	v_mfma_f32_16x16x32_bf16 v[110:113], v[170:173], v[204:207], 0
	v_mfma_f32_16x16x32_bf16 v[102:105], v[160:163], v[212:215], 0
	v_mfma_f32_16x16x32_bf16 v[94:97], v[170:173], v[212:215], 0
	v_mfma_f32_16x16x32_bf16 v[86:89], v[160:163], v[220:223], 0
	v_mfma_f32_16x16x32_bf16 v[78:81], v[170:173], v[220:223], 0
	v_mfma_f32_16x16x32_bf16 v[126:129], v[166:169], v[200:203], v[126:129]
	v_mfma_f32_16x16x32_bf16 v[122:125], v[174:177], v[200:203], v[122:125]
	v_mfma_f32_16x16x32_bf16 v[118:121], v[166:169], v[208:211], v[118:121]
	v_mfma_f32_16x16x32_bf16 v[110:113], v[174:177], v[208:211], v[110:113]
	v_mfma_f32_16x16x32_bf16 v[102:105], v[166:169], v[216:219], v[102:105]
	v_mfma_f32_16x16x32_bf16 v[94:97], v[174:177], v[216:219], v[94:97]
	v_mfma_f32_16x16x32_bf16 v[86:89], v[166:169], v[224:227], v[86:89]
	v_mfma_f32_16x16x32_bf16 v[78:81], v[174:177], v[224:227], v[78:81]
	v_mfma_f32_16x16x32_bf16 v[114:117], v[178:181], v[196:199], 0
	v_mfma_f32_16x16x32_bf16 v[106:109], v[188:191], v[196:199], 0
	v_mfma_f32_16x16x32_bf16 v[98:101], v[178:181], v[204:207], 0
	v_mfma_f32_16x16x32_bf16 v[90:93], v[188:191], v[204:207], 0
	v_mfma_f32_16x16x32_bf16 v[82:85], v[178:181], v[212:215], 0
	v_mfma_f32_16x16x32_bf16 v[74:77], v[188:191], v[212:215], 0
	v_mfma_f32_16x16x32_bf16 v[70:73], v[178:181], v[220:223], 0
	v_mfma_f32_16x16x32_bf16 v[66:69], v[188:191], v[220:223], 0
	v_mfma_f32_16x16x32_bf16 v[114:117], v[184:187], v[200:203], v[114:117]
	v_mfma_f32_16x16x32_bf16 v[106:109], v[192:195], v[200:203], v[106:109]
	v_mfma_f32_16x16x32_bf16 v[98:101], v[184:187], v[208:211], v[98:101]
	v_mfma_f32_16x16x32_bf16 v[90:93], v[192:195], v[208:211], v[90:93]
	v_mfma_f32_16x16x32_bf16 v[82:85], v[184:187], v[216:219], v[82:85]
	v_mfma_f32_16x16x32_bf16 v[74:77], v[192:195], v[216:219], v[74:77]
	v_mfma_f32_16x16x32_bf16 v[70:73], v[184:187], v[224:227], v[70:73]
	v_mfma_f32_16x16x32_bf16 v[66:69], v[192:195], v[224:227], v[66:69]
	s_barrier
	s_setprio 0
	s_add_i32 s12, s39, s22
	s_mov_b32 m0, s12
	ds_read_b128 v[196:199], v165 offset:16384
	ds_read_b128 v[200:203], v165 offset:17408
	ds_read_b128 v[204:207], v165 offset:18432
	ds_read_b128 v[208:211], v165 offset:19456
	ds_read_b128 v[212:215], v165 offset:20480
	ds_read_b128 v[216:219], v165 offset:21504
	ds_read_b128 v[220:223], v165 offset:22528
	ds_read_b128 v[224:227], v165 offset:23552
	global_load_lds_dwordx4 v132, s[16:17]
	s_add_i32 m0, s12, 0x2000
	s_add_u32 s12, s16, 0x44000
	s_addc_u32 s13, s17, 0
	s_add_i32 s39, s40, s22
	global_load_lds_dwordx4 v152, s[16:17]
	s_mov_b32 m0, s39
	s_nop 0
	global_load_lds_dwordx4 v132, s[12:13]
	s_add_i32 m0, s39, 0x2000
	s_nop 0
	global_load_lds_dwordx4 v152, s[12:13]
	s_mov_b32 m0, s23
	s_nop 0
	global_load_lds_dwordx4 v130, s[18:19]
	s_mov_b32 m0, s24
	s_nop 0
	global_load_lds_dwordx4 v134, s[18:19]
	s_waitcnt vmcnt(8)
	s_waitcnt lgkmcnt(0)
	s_setprio 1
	s_barrier
	v_mfma_f32_16x16x32_bf16 v[62:65], v[160:163], v[196:199], 0
	v_mfma_f32_16x16x32_bf16 v[58:61], v[170:173], v[196:199], 0
	v_mfma_f32_16x16x32_bf16 v[54:57], v[160:163], v[204:207], 0
	v_mfma_f32_16x16x32_bf16 v[46:49], v[170:173], v[204:207], 0
	v_mfma_f32_16x16x32_bf16 v[38:41], v[160:163], v[212:215], 0
	v_mfma_f32_16x16x32_bf16 v[30:33], v[170:173], v[212:215], 0
	v_mfma_f32_16x16x32_bf16 v[22:25], v[160:163], v[220:223], 0
	v_mfma_f32_16x16x32_bf16 v[14:17], v[170:173], v[220:223], 0
	v_mfma_f32_16x16x32_bf16 v[62:65], v[166:169], v[200:203], v[62:65]
	v_mfma_f32_16x16x32_bf16 v[58:61], v[174:177], v[200:203], v[58:61]
	v_mfma_f32_16x16x32_bf16 v[54:57], v[166:169], v[208:211], v[54:57]
	v_mfma_f32_16x16x32_bf16 v[46:49], v[174:177], v[208:211], v[46:49]
	v_mfma_f32_16x16x32_bf16 v[38:41], v[166:169], v[216:219], v[38:41]
	v_mfma_f32_16x16x32_bf16 v[30:33], v[174:177], v[216:219], v[30:33]
	v_mfma_f32_16x16x32_bf16 v[22:25], v[166:169], v[224:227], v[22:25]
	v_mfma_f32_16x16x32_bf16 v[14:17], v[174:177], v[224:227], v[14:17]
	v_mfma_f32_16x16x32_bf16 v[50:53], v[178:181], v[196:199], 0
	v_mfma_f32_16x16x32_bf16 v[42:45], v[188:191], v[196:199], 0
	v_mfma_f32_16x16x32_bf16 v[34:37], v[178:181], v[204:207], 0
	v_mfma_f32_16x16x32_bf16 v[26:29], v[188:191], v[204:207], 0
	v_mfma_f32_16x16x32_bf16 v[18:21], v[178:181], v[212:215], 0
	v_mfma_f32_16x16x32_bf16 v[10:13], v[188:191], v[212:215], 0
	v_mfma_f32_16x16x32_bf16 v[6:9], v[178:181], v[220:223], 0
	v_mfma_f32_16x16x32_bf16 v[2:5], v[188:191], v[220:223], 0
	v_mfma_f32_16x16x32_bf16 v[50:53], v[184:187], v[200:203], v[50:53]
	v_mfma_f32_16x16x32_bf16 v[42:45], v[192:195], v[200:203], v[42:45]
	v_mfma_f32_16x16x32_bf16 v[34:37], v[184:187], v[208:211], v[34:37]
	v_mfma_f32_16x16x32_bf16 v[26:29], v[192:195], v[208:211], v[26:29]
	v_mfma_f32_16x16x32_bf16 v[18:21], v[184:187], v[216:219], v[18:21]
	v_mfma_f32_16x16x32_bf16 v[10:13], v[192:195], v[216:219], v[10:13]
	v_mfma_f32_16x16x32_bf16 v[6:9], v[184:187], v[224:227], v[6:9]
	v_mfma_f32_16x16x32_bf16 v[2:5], v[192:195], v[224:227], v[2:5]
	s_barrier
; #define PG8_STAGE(bufoff, gbase, voff) do { _Pragma("unroll") for (int _i = 0; _i < 2; ++_i) \
;         __builtin_amdgcn_global_load_lds((const unsigned*)((const char*)(gbase) + (voff)[_i]), (LAS unsigned*)(lds + (bufoff) + ldsw + _i * 8192), 16, 0, 0); } while (0)
; #define PG8_LDA(dst, b, h) do { _Pragma("unroll") for (int m = 0; m < 4; ++m) _Pragma("unroll") for (int k = 0; k < 2; ++k) dst[m][k] = *(const LAS bf16x8*)(lds + PG8_SA(b, h) + aoff + m * 2048 + k * 1024); } while (0)
; #define PG8_LDB(dst, b, h) do { _Pragma("unroll") for (int n = 0; n < 2; ++n) _Pragma("unroll") for (int k = 0; k < 2; ++k) dst[n][k] = *(const LAS bf16x8*)(lds + PG8_SB(b, h) + boff + n * 2048 + k * 1024); } while (0)
; #define PG8_MMA(ai, bj, At, Bt) do { __builtin_amdgcn_s_setprio(1); _Pragma("unroll") for (int m = 0; m < 4; ++m) _Pragma("unroll") for (int n = 0; n < 2; ++n) _Pragma("unroll") for (int k = 0; k < 2; ++k) \
;         acc[ai][bj][m][n] = __builtin_amdgcn_mfma_f32_16x16x32_bf16(Bt[n][k], At[m][k], acc[ai][bj][m][n], 0, 0, 0); __builtin_amdgcn_s_setprio(0); } while (0)
; #define PG8_WAIT_V(n) asm volatile("s_waitcnt vmcnt(" #n ")" ::: "memory")
; #define PG8_WAIT_L(n) asm volatile("s_waitcnt lgkmcnt(" #n ")" ::: "memory")
; #define PG8_BAR __builtin_amdgcn_s_barrier()
; #define PG8_SCHED __builtin_amdgcn_sched_barrier(0)
; template <class Epi, bool ALIGN_EPI = PG8_ALIGN, bool SP2 = PG8_SP2>
; __device__ __forceinline__ void gemm_phase(LAS uchar* lds, const Gemm g, const StaticOrder& S, const Epi& E) {
;     ...
;             PG8_LDB(B0, 1, 0); PG8_LDB(B1, 1, 1); PG8_SCHED; PG8_LDA(At, 1, 0); PG8_STAGE(PG8_SA(0, 1), a2 + hstepA, voffA);
;             PG8_WAIT_V(8); PG8_WAIT_L(0); PG8_BAR; PG8_MMA(0, 0, At, B0); PG8_MMA(0, 1, At, B1); PG8_BAR; PG8_SCHED;
;             PG8_LDA(At, 1, 1); PG8_STAGE(PG8_SB(1, 0), b3, voffB); PG8_STAGE(PG8_SB(1, 1), b3 + hstepB, voffB); PG8_STAGE(PG8_SA(1, 0), a3, voffA);
;             PG8_WAIT_V(8); PG8_WAIT_L(0); PG8_BAR; PG8_MMA(1, 0, At, B0); PG8_MMA(1, 1, At, B1); PG8_BAR; PG8_SCHED;
	s_setprio 0
	s_add_i32 s39, 0, 0x18000
	s_add_i32 s40, 0, 0x1c000
	v_add_u32_e32 v174, s39, v139
	v_add_u32_e32 v192, s40, v139
	ds_read_b128 v[160:163], v174
	ds_read_b128 v[166:169], v174 offset:1024
	ds_read_b128 v[170:173], v174 offset:2048
	ds_read_b128 v[174:177], v174 offset:3072
	ds_read_b128 v[178:181], v192
	ds_read_b128 v[184:187], v192 offset:1024
	ds_read_b128 v[188:191], v192 offset:2048
	ds_read_b128 v[192:195], v192 offset:3072
	s_add_u32 s12, s18, 0x44000
	s_addc_u32 s13, s19, 0
	s_mov_b32 m0, s25
	ds_read_b128 v[196:199], v165 offset:32768
	ds_read_b128 v[200:203], v165 offset:33792
	ds_read_b128 v[204:207], v165 offset:34816
	ds_read_b128 v[208:211], v165 offset:35840
	ds_read_b128 v[212:215], v165 offset:36864
	ds_read_b128 v[216:219], v165 offset:37888
	ds_read_b128 v[220:223], v165 offset:38912
	ds_read_b128 v[224:227], v165 offset:39936
	global_load_lds_dwordx4 v130, s[12:13]
	s_mov_b32 m0, s26
	s_nop 0
	global_load_lds_dwordx4 v134, s[12:13]
	s_waitcnt vmcnt(8)
	s_waitcnt lgkmcnt(0)
	s_setprio 1
	s_barrier
	v_mfma_f32_16x16x32_bf16 v[126:129], v[160:163], v[196:199], v[126:129]
	v_mfma_f32_16x16x32_bf16 v[122:125], v[170:173], v[196:199], v[122:125]
	v_mfma_f32_16x16x32_bf16 v[118:121], v[160:163], v[204:207], v[118:121]
	v_mfma_f32_16x16x32_bf16 v[110:113], v[170:173], v[204:207], v[110:113]
	v_mfma_f32_16x16x32_bf16 v[102:105], v[160:163], v[212:215], v[102:105]
	v_mfma_f32_16x16x32_bf16 v[94:97], v[170:173], v[212:215], v[94:97]
	v_mfma_f32_16x16x32_bf16 v[86:89], v[160:163], v[220:223], v[86:89]
	v_mfma_f32_16x16x32_bf16 v[78:81], v[170:173], v[220:223], v[78:81]
	v_mfma_f32_16x16x32_bf16 v[126:129], v[166:169], v[200:203], v[126:129]
	v_mfma_f32_16x16x32_bf16 v[122:125], v[174:177], v[200:203], v[122:125]
	v_mfma_f32_16x16x32_bf16 v[118:121], v[166:169], v[208:211], v[118:121]
	v_mfma_f32_16x16x32_bf16 v[110:113], v[174:177], v[208:211], v[110:113]
	v_mfma_f32_16x16x32_bf16 v[102:105], v[166:169], v[216:219], v[102:105]
	v_mfma_f32_16x16x32_bf16 v[94:97], v[174:177], v[216:219], v[94:97]
	v_mfma_f32_16x16x32_bf16 v[86:89], v[166:169], v[224:227], v[86:89]
	v_mfma_f32_16x16x32_bf16 v[78:81], v[174:177], v[224:227], v[78:81]
	v_mfma_f32_16x16x32_bf16 v[114:117], v[178:181], v[196:199], v[114:117]
	v_mfma_f32_16x16x32_bf16 v[106:109], v[188:191], v[196:199], v[106:109]
	v_mfma_f32_16x16x32_bf16 v[98:101], v[178:181], v[204:207], v[98:101]
	v_mfma_f32_16x16x32_bf16 v[90:93], v[188:191], v[204:207], v[90:93]
	v_mfma_f32_16x16x32_bf16 v[82:85], v[178:181], v[212:215], v[82:85]
	v_mfma_f32_16x16x32_bf16 v[74:77], v[188:191], v[212:215], v[74:77]
	v_mfma_f32_16x16x32_bf16 v[70:73], v[178:181], v[220:223], v[70:73]
	v_mfma_f32_16x16x32_bf16 v[66:69], v[188:191], v[220:223], v[66:69]
	v_mfma_f32_16x16x32_bf16 v[114:117], v[184:187], v[200:203], v[114:117]
	v_mfma_f32_16x16x32_bf16 v[106:109], v[192:195], v[200:203], v[106:109]
	v_mfma_f32_16x16x32_bf16 v[98:101], v[184:187], v[208:211], v[98:101]
	v_mfma_f32_16x16x32_bf16 v[90:93], v[192:195], v[208:211], v[90:93]
	v_mfma_f32_16x16x32_bf16 v[82:85], v[184:187], v[216:219], v[82:85]
	v_mfma_f32_16x16x32_bf16 v[74:77], v[192:195], v[216:219], v[74:77]
	v_mfma_f32_16x16x32_bf16 v[70:73], v[184:187], v[224:227], v[70:73]
	v_mfma_f32_16x16x32_bf16 v[66:69], v[192:195], v[224:227], v[66:69]
	s_barrier
	s_setprio 0
	s_add_i32 s12, s39, s22
	s_add_i32 m0, s12, 0xffffff80
	ds_read_b128 v[196:199], v165 offset:49152
	ds_read_b128 v[200:203], v165 offset:50176
	ds_read_b128 v[204:207], v165 offset:51200
	ds_read_b128 v[208:211], v165 offset:52224
	ds_read_b128 v[212:215], v165 offset:53248
	ds_read_b128 v[216:219], v165 offset:54272
	ds_read_b128 v[220:223], v165 offset:55296
	ds_read_b128 v[224:227], v165 offset:56320
	global_load_lds_dwordx4 v132, s[16:17] offset:128
	s_add_i32 m0, s12, 0x1f80
	s_add_u32 s12, s16, 0x44080
	s_addc_u32 s13, s17, 0
	global_load_lds_dwordx4 v152, s[16:17] offset:128
	s_add_i32 s16, s40, s22
	s_mov_b32 m0, s16
	s_nop 0
	global_load_lds_dwordx4 v132, s[12:13]
	s_add_i32 m0, s16, 0x2000
	s_nop 0
	global_load_lds_dwordx4 v152, s[12:13]
	s_add_i32 m0, s27, 0xffffff80
	s_nop 0
	global_load_lds_dwordx4 v130, s[18:19] offset:128
	s_add_i32 m0, s28, 0xffffff80
	s_nop 0
	global_load_lds_dwordx4 v134, s[18:19] offset:128
	s_waitcnt vmcnt(8)
	s_waitcnt lgkmcnt(0)
	s_setprio 1
	s_barrier
	v_mfma_f32_16x16x32_bf16 v[62:65], v[160:163], v[196:199], v[62:65]
	v_mfma_f32_16x16x32_bf16 v[58:61], v[170:173], v[196:199], v[58:61]
	v_mfma_f32_16x16x32_bf16 v[54:57], v[160:163], v[204:207], v[54:57]
	v_mfma_f32_16x16x32_bf16 v[46:49], v[170:173], v[204:207], v[46:49]
	v_mfma_f32_16x16x32_bf16 v[38:41], v[160:163], v[212:215], v[38:41]
	v_mfma_f32_16x16x32_bf16 v[30:33], v[170:173], v[212:215], v[30:33]
	v_mfma_f32_16x16x32_bf16 v[22:25], v[160:163], v[220:223], v[22:25]
	v_mfma_f32_16x16x32_bf16 v[14:17], v[170:173], v[220:223], v[14:17]
	v_mfma_f32_16x16x32_bf16 v[62:65], v[166:169], v[200:203], v[62:65]
	v_mfma_f32_16x16x32_bf16 v[58:61], v[174:177], v[200:203], v[58:61]
	v_mfma_f32_16x16x32_bf16 v[54:57], v[166:169], v[208:211], v[54:57]
	v_mfma_f32_16x16x32_bf16 v[46:49], v[174:177], v[208:211], v[46:49]
	v_mfma_f32_16x16x32_bf16 v[38:41], v[166:169], v[216:219], v[38:41]
	v_mfma_f32_16x16x32_bf16 v[30:33], v[174:177], v[216:219], v[30:33]
	v_mfma_f32_16x16x32_bf16 v[22:25], v[166:169], v[224:227], v[22:25]
	v_mfma_f32_16x16x32_bf16 v[14:17], v[174:177], v[224:227], v[14:17]
	v_mfma_f32_16x16x32_bf16 v[50:53], v[178:181], v[196:199], v[50:53]
	v_mfma_f32_16x16x32_bf16 v[42:45], v[188:191], v[196:199], v[42:45]
	v_mfma_f32_16x16x32_bf16 v[34:37], v[178:181], v[204:207], v[34:37]
	v_mfma_f32_16x16x32_bf16 v[26:29], v[188:191], v[204:207], v[26:29]
	v_mfma_f32_16x16x32_bf16 v[18:21], v[178:181], v[212:215], v[18:21]
	v_mfma_f32_16x16x32_bf16 v[10:13], v[188:191], v[212:215], v[10:13]
	v_mfma_f32_16x16x32_bf16 v[6:9], v[178:181], v[220:223], v[6:9]
	v_mfma_f32_16x16x32_bf16 v[2:5], v[188:191], v[220:223], v[2:5]
	v_mfma_f32_16x16x32_bf16 v[50:53], v[184:187], v[200:203], v[50:53]
	v_mfma_f32_16x16x32_bf16 v[42:45], v[192:195], v[200:203], v[42:45]
	v_mfma_f32_16x16x32_bf16 v[34:37], v[184:187], v[208:211], v[34:37]
	v_mfma_f32_16x16x32_bf16 v[26:29], v[192:195], v[208:211], v[26:29]
	v_mfma_f32_16x16x32_bf16 v[18:21], v[184:187], v[216:219], v[18:21]
	v_mfma_f32_16x16x32_bf16 v[10:13], v[192:195], v[216:219], v[10:13]
	v_mfma_f32_16x16x32_bf16 v[6:9], v[184:187], v[224:227], v[6:9]
	v_mfma_f32_16x16x32_bf16 v[2:5], v[192:195], v[224:227], v[2:5]
	s_barrier
	s_setprio 0
	s_add_i32 s38, s38, 2
	s_add_u32 s36, s36, 0x100
	s_addc_u32 s37, s37, 0
	s_cmp_gt_u32 s38, 13
	s_mov_b64 s[12:13], s[14:15]
; #define PG8_STAGE(bufoff, gbase, voff) do { _Pragma("unroll") for (int _i = 0; _i < 2; ++_i) \
;         __builtin_amdgcn_global_load_lds((const unsigned*)((const char*)(gbase) + (voff)[_i]), (LAS unsigned*)(lds + (bufoff) + ldsw + _i * 8192), 16, 0, 0); } while (0)
; #define PG8_LDA(dst, b, h) do { _Pragma("unroll") for (int m = 0; m < 4; ++m) _Pragma("unroll") for (int k = 0; k < 2; ++k) dst[m][k] = *(const LAS bf16x8*)(lds + PG8_SA(b, h) + aoff + m * 2048 + k * 1024); } while (0)
; #define PG8_LDB(dst, b, h) do { _Pragma("unroll") for (int n = 0; n < 2; ++n) _Pragma("unroll") for (int k = 0; k < 2; ++k) dst[n][k] = *(const LAS bf16x8*)(lds + PG8_SB(b, h) + boff + n * 2048 + k * 1024); } while (0)
; #define PG8_MMA(ai, bj, At, Bt) do { __builtin_amdgcn_s_setprio(1); _Pragma("unroll") for (int m = 0; m < 4; ++m) _Pragma("unroll") for (int n = 0; n < 2; ++n) _Pragma("unroll") for (int k = 0; k < 2; ++k) \
;         acc[ai][bj][m][n] = __builtin_amdgcn_mfma_f32_16x16x32_bf16(Bt[n][k], At[m][k], acc[ai][bj][m][n], 0, 0, 0); __builtin_amdgcn_s_setprio(0); } while (0)
; #define PG8_WAIT_V(n) asm volatile("s_waitcnt vmcnt(" #n ")" ::: "memory")
; #define PG8_WAIT_L(n) asm volatile("s_waitcnt lgkmcnt(" #n ")" ::: "memory")
; #define PG8_BAR __builtin_amdgcn_s_barrier()
; template <class Epi, bool ALIGN_EPI = PG8_ALIGN, bool SP2 = PG8_SP2>
; __device__ __forceinline__ void gemm_phase(LAS uchar* lds, const Gemm g, const StaticOrder& S, const Epi& E) {
;     ...
;         for (int t = tb; t < tb + tblk; t += 2) {
;             const bool last = (t == nt - 2);
;             const char* a1 = cA + (size_t)(t + 1) * kstep;
;             const char* a2 = last ? nA : cA + (size_t)(t + 2) * kstep; const char* b2 = last ? nB : cB + (size_t)(t + 2) * kstep;
;             const char* a3 = a2 + kstep; const char* b3 = b2 + kstep;
;             if constexpr (SP2) {
;             PG8_LDB(B0, 0, 0); PG8_LDB(B1, 0, 1); PG8_SCHED; PG8_LDA(At, 0, 0); PG8_STAGE(PG8_SA(1, 1), a1 + hstepA, voffA);
;             PG8_WAIT_V(8); PG8_WAIT_L(0); PG8_BAR; PG8_MMA(0, 0, At, B0); PG8_MMA(0, 1, At, B1); PG8_BAR; PG8_SCHED;
;             PG8_LDA(At, 0, 1); PG8_STAGE(PG8_SB(0, 0), b2, voffB); PG8_STAGE(PG8_SB(0, 1), b2 + hstepB, voffB); PG8_STAGE(PG8_SA(0, 0), a2, voffA);
;             PG8_WAIT_V(8); PG8_WAIT_L(0); PG8_BAR; PG8_MMA(1, 0, At, B0); PG8_MMA(1, 1, At, B1); PG8_BAR; PG8_SCHED;
.LBB0_837:
	s_add_u32 s14, s12, 0x100
	s_addc_u32 s15, s13, 0
	s_add_i32 s39, 0, 0x10000
	s_cmp_eq_u32 s38, 12
	s_cselect_b32 s19, s5, s15
	s_cselect_b32 s18, s4, s14
	s_cselect_b32 s17, s11, s37
	s_cselect_b32 s16, s10, s36
	s_add_i32 s40, 0, 0x14000
	v_add_u32_e32 v174, s39, v139
	v_add_u32_e32 v192, s40, v139
	ds_read_b128 v[160:163], v174
	ds_read_b128 v[166:169], v174 offset:1024
	ds_read_b128 v[170:173], v174 offset:2048
	ds_read_b128 v[174:177], v174 offset:3072
	ds_read_b128 v[178:181], v192
	ds_read_b128 v[184:187], v192 offset:1024
	ds_read_b128 v[188:191], v192 offset:2048
	ds_read_b128 v[192:195], v192 offset:3072
	s_add_i32 m0, s23, 0xc000
	ds_read_b128 v[196:199], v165
	ds_read_b128 v[200:203], v165 offset:1024
	ds_read_b128 v[204:207], v165 offset:2048
	ds_read_b128 v[208:211], v165 offset:3072
	ds_read_b128 v[212:215], v165 offset:4096
	ds_read_b128 v[216:219], v165 offset:5120
	ds_read_b128 v[220:223], v165 offset:6144
	ds_read_b128 v[224:227], v165 offset:7168
	global_load_lds_dwordx4 v156, s[12:13]
	s_add_i32 m0, s23, 0xe000
	s_nop 0
	global_load_lds_dwordx4 v158, s[12:13]
	s_waitcnt vmcnt(8)
	s_waitcnt lgkmcnt(0)
	s_setprio 1
	s_barrier
	v_mfma_f32_16x16x32_bf16 v[126:129], v[160:163], v[196:199], v[126:129]
	v_mfma_f32_16x16x32_bf16 v[122:125], v[170:173], v[196:199], v[122:125]
	v_mfma_f32_16x16x32_bf16 v[118:121], v[160:163], v[204:207], v[118:121]
	v_mfma_f32_16x16x32_bf16 v[110:113], v[170:173], v[204:207], v[110:113]
	v_mfma_f32_16x16x32_bf16 v[102:105], v[160:163], v[212:215], v[102:105]
	v_mfma_f32_16x16x32_bf16 v[94:97], v[170:173], v[212:215], v[94:97]
	v_mfma_f32_16x16x32_bf16 v[86:89], v[160:163], v[220:223], v[86:89]
	v_mfma_f32_16x16x32_bf16 v[78:81], v[170:173], v[220:223], v[78:81]
	v_mfma_f32_16x16x32_bf16 v[126:129], v[166:169], v[200:203], v[126:129]
	v_mfma_f32_16x16x32_bf16 v[122:125], v[174:177], v[200:203], v[122:125]
	v_mfma_f32_16x16x32_bf16 v[118:121], v[166:169], v[208:211], v[118:121]
	v_mfma_f32_16x16x32_bf16 v[110:113], v[174:177], v[208:211], v[110:113]
	v_mfma_f32_16x16x32_bf16 v[102:105], v[166:169], v[216:219], v[102:105]
	v_mfma_f32_16x16x32_bf16 v[94:97], v[174:177], v[216:219], v[94:97]
	v_mfma_f32_16x16x32_bf16 v[86:89], v[166:169], v[224:227], v[86:89]
	v_mfma_f32_16x16x32_bf16 v[78:81], v[174:177], v[224:227], v[78:81]
	v_mfma_f32_16x16x32_bf16 v[114:117], v[178:181], v[196:199], v[114:117]
	v_mfma_f32_16x16x32_bf16 v[106:109], v[188:191], v[196:199], v[106:109]
	v_mfma_f32_16x16x32_bf16 v[98:101], v[178:181], v[204:207], v[98:101]
	v_mfma_f32_16x16x32_bf16 v[90:93], v[188:191], v[204:207], v[90:93]
	v_mfma_f32_16x16x32_bf16 v[82:85], v[178:181], v[212:215], v[82:85]
	v_mfma_f32_16x16x32_bf16 v[74:77], v[188:191], v[212:215], v[74:77]
	v_mfma_f32_16x16x32_bf16 v[70:73], v[178:181], v[220:223], v[70:73]
	v_mfma_f32_16x16x32_bf16 v[66:69], v[188:191], v[220:223], v[66:69]
	v_mfma_f32_16x16x32_bf16 v[114:117], v[184:187], v[200:203], v[114:117]
	v_mfma_f32_16x16x32_bf16 v[106:109], v[192:195], v[200:203], v[106:109]
	v_mfma_f32_16x16x32_bf16 v[98:101], v[184:187], v[208:211], v[98:101]
	v_mfma_f32_16x16x32_bf16 v[90:93], v[192:195], v[208:211], v[90:93]
	v_mfma_f32_16x16x32_bf16 v[82:85], v[184:187], v[216:219], v[82:85]
	v_mfma_f32_16x16x32_bf16 v[74:77], v[192:195], v[216:219], v[74:77]
	v_mfma_f32_16x16x32_bf16 v[70:73], v[184:187], v[224:227], v[70:73]
	v_mfma_f32_16x16x32_bf16 v[66:69], v[192:195], v[224:227], v[66:69]
	s_barrier
	s_setprio 0
	s_add_i32 s12, s39, s22
	s_mov_b32 m0, s12
	ds_read_b128 v[196:199], v165 offset:16384
	ds_read_b128 v[200:203], v165 offset:17408
	ds_read_b128 v[204:207], v165 offset:18432
	ds_read_b128 v[208:211], v165 offset:19456
	ds_read_b128 v[212:215], v165 offset:20480
	ds_read_b128 v[216:219], v165 offset:21504
	ds_read_b128 v[220:223], v165 offset:22528
	ds_read_b128 v[224:227], v165 offset:23552
	global_load_lds_dwordx4 v132, s[16:17]
	s_add_i32 m0, s12, 0x2000
	s_add_u32 s12, s16, 0x44000
	s_addc_u32 s13, s17, 0
	s_add_i32 s39, s40, s22
	global_load_lds_dwordx4 v152, s[16:17]
	s_mov_b32 m0, s39
	s_nop 0
	global_load_lds_dwordx4 v132, s[12:13]
	s_add_i32 m0, s39, 0x2000
	s_nop 0
	global_load_lds_dwordx4 v152, s[12:13]
	s_mov_b32 m0, s23
	s_nop 0
	global_load_lds_dwordx4 v130, s[18:19]
	s_mov_b32 m0, s24
	s_nop 0
	global_load_lds_dwordx4 v134, s[18:19]
	s_waitcnt vmcnt(8)
	s_waitcnt lgkmcnt(0)
	s_setprio 1
	s_barrier
	v_mfma_f32_16x16x32_bf16 v[62:65], v[160:163], v[196:199], v[62:65]
	v_mfma_f32_16x16x32_bf16 v[58:61], v[170:173], v[196:199], v[58:61]
	v_mfma_f32_16x16x32_bf16 v[54:57], v[160:163], v[204:207], v[54:57]
	v_mfma_f32_16x16x32_bf16 v[46:49], v[170:173], v[204:207], v[46:49]
	v_mfma_f32_16x16x32_bf16 v[38:41], v[160:163], v[212:215], v[38:41]
	v_mfma_f32_16x16x32_bf16 v[30:33], v[170:173], v[212:215], v[30:33]
	v_mfma_f32_16x16x32_bf16 v[22:25], v[160:163], v[220:223], v[22:25]
	v_mfma_f32_16x16x32_bf16 v[14:17], v[170:173], v[220:223], v[14:17]
	v_mfma_f32_16x16x32_bf16 v[62:65], v[166:169], v[200:203], v[62:65]
	v_mfma_f32_16x16x32_bf16 v[58:61], v[174:177], v[200:203], v[58:61]
	v_mfma_f32_16x16x32_bf16 v[54:57], v[166:169], v[208:211], v[54:57]
	v_mfma_f32_16x16x32_bf16 v[46:49], v[174:177], v[208:211], v[46:49]
	v_mfma_f32_16x16x32_bf16 v[38:41], v[166:169], v[216:219], v[38:41]
	v_mfma_f32_16x16x32_bf16 v[30:33], v[174:177], v[216:219], v[30:33]
	v_mfma_f32_16x16x32_bf16 v[22:25], v[166:169], v[224:227], v[22:25]
	v_mfma_f32_16x16x32_bf16 v[14:17], v[174:177], v[224:227], v[14:17]
	v_mfma_f32_16x16x32_bf16 v[50:53], v[178:181], v[196:199], v[50:53]
	v_mfma_f32_16x16x32_bf16 v[42:45], v[188:191], v[196:199], v[42:45]
	v_mfma_f32_16x16x32_bf16 v[34:37], v[178:181], v[204:207], v[34:37]
	v_mfma_f32_16x16x32_bf16 v[26:29], v[188:191], v[204:207], v[26:29]
	v_mfma_f32_16x16x32_bf16 v[18:21], v[178:181], v[212:215], v[18:21]
	v_mfma_f32_16x16x32_bf16 v[10:13], v[188:191], v[212:215], v[10:13]
	v_mfma_f32_16x16x32_bf16 v[6:9], v[178:181], v[220:223], v[6:9]
	v_mfma_f32_16x16x32_bf16 v[2:5], v[188:191], v[220:223], v[2:5]
	v_mfma_f32_16x16x32_bf16 v[50:53], v[184:187], v[200:203], v[50:53]
	v_mfma_f32_16x16x32_bf16 v[42:45], v[192:195], v[200:203], v[42:45]
	v_mfma_f32_16x16x32_bf16 v[34:37], v[184:187], v[208:211], v[34:37]
	v_mfma_f32_16x16x32_bf16 v[26:29], v[192:195], v[208:211], v[26:29]
	v_mfma_f32_16x16x32_bf16 v[18:21], v[184:187], v[216:219], v[18:21]
	v_mfma_f32_16x16x32_bf16 v[10:13], v[192:195], v[216:219], v[10:13]
	v_mfma_f32_16x16x32_bf16 v[6:9], v[184:187], v[224:227], v[6:9]
	v_mfma_f32_16x16x32_bf16 v[2:5], v[192:195], v[224:227], v[2:5]
	s_barrier
; #define PG8_STAGE(bufoff, gbase, voff) do { _Pragma("unroll") for (int _i = 0; _i < 2; ++_i) \
;         __builtin_amdgcn_global_load_lds((const unsigned*)((const char*)(gbase) + (voff)[_i]), (LAS unsigned*)(lds + (bufoff) + ldsw + _i * 8192), 16, 0, 0); } while (0)
; #define PG8_LDA(dst, b, h) do { _Pragma("unroll") for (int m = 0; m < 4; ++m) _Pragma("unroll") for (int k = 0; k < 2; ++k) dst[m][k] = *(const LAS bf16x8*)(lds + PG8_SA(b, h) + aoff + m * 2048 + k * 1024); } while (0)
; #define PG8_LDB(dst, b, h) do { _Pragma("unroll") for (int n = 0; n < 2; ++n) _Pragma("unroll") for (int k = 0; k < 2; ++k) dst[n][k] = *(const LAS bf16x8*)(lds + PG8_SB(b, h) + boff + n * 2048 + k * 1024); } while (0)
; #define PG8_MMA(ai, bj, At, Bt) do { __builtin_amdgcn_s_setprio(1); _Pragma("unroll") for (int m = 0; m < 4; ++m) _Pragma("unroll") for (int n = 0; n < 2; ++n) _Pragma("unroll") for (int k = 0; k < 2; ++k) \
;         acc[ai][bj][m][n] = __builtin_amdgcn_mfma_f32_16x16x32_bf16(Bt[n][k], At[m][k], acc[ai][bj][m][n], 0, 0, 0); __builtin_amdgcn_s_setprio(0); } while (0)
; #define PG8_WAIT_V(n) asm volatile("s_waitcnt vmcnt(" #n ")" ::: "memory")
; #define PG8_WAIT_L(n) asm volatile("s_waitcnt lgkmcnt(" #n ")" ::: "memory")
; #define PG8_BAR __builtin_amdgcn_s_barrier()
; #define PG8_SCHED __builtin_amdgcn_sched_barrier(0)
; template <class Epi, bool ALIGN_EPI = PG8_ALIGN, bool SP2 = PG8_SP2>
; __device__ __forceinline__ void gemm_phase(LAS uchar* lds, const Gemm g, const StaticOrder& S, const Epi& E) {
;     ...
;             PG8_LDB(B0, 1, 0); PG8_LDB(B1, 1, 1); PG8_SCHED; PG8_LDA(At, 1, 0); PG8_STAGE(PG8_SA(0, 1), a2 + hstepA, voffA);
;             PG8_WAIT_V(8); PG8_WAIT_L(0); PG8_BAR; PG8_MMA(0, 0, At, B0); PG8_MMA(0, 1, At, B1); PG8_BAR; PG8_SCHED;
;             PG8_LDA(At, 1, 1); PG8_STAGE(PG8_SB(1, 0), b3, voffB); PG8_STAGE(PG8_SB(1, 1), b3 + hstepB, voffB); PG8_STAGE(PG8_SA(1, 0), a3, voffA);
;             PG8_WAIT_V(8); PG8_WAIT_L(0); PG8_BAR; PG8_MMA(1, 0, At, B0); PG8_MMA(1, 1, At, B1); PG8_BAR; PG8_SCHED;
;     ...
;         if constexpr (ALIGN_EPI) { if (wr == 0) PG8_BAR; }
	s_setprio 0
	s_add_i32 s39, 0, 0x18000
	s_add_i32 s40, 0, 0x1c000
	v_add_u32_e32 v174, s39, v139
	v_add_u32_e32 v192, s40, v139
	ds_read_b128 v[160:163], v174
	ds_read_b128 v[166:169], v174 offset:1024
	ds_read_b128 v[170:173], v174 offset:2048
	ds_read_b128 v[174:177], v174 offset:3072
	ds_read_b128 v[178:181], v192
	ds_read_b128 v[184:187], v192 offset:1024
	ds_read_b128 v[188:191], v192 offset:2048
	ds_read_b128 v[192:195], v192 offset:3072
	s_add_u32 s12, s18, 0x44000
	s_addc_u32 s13, s19, 0
	s_mov_b32 m0, s25
	ds_read_b128 v[196:199], v165 offset:32768
	ds_read_b128 v[200:203], v165 offset:33792
	ds_read_b128 v[204:207], v165 offset:34816
	ds_read_b128 v[208:211], v165 offset:35840
	ds_read_b128 v[212:215], v165 offset:36864
	ds_read_b128 v[216:219], v165 offset:37888
	ds_read_b128 v[220:223], v165 offset:38912
	ds_read_b128 v[224:227], v165 offset:39936
	global_load_lds_dwordx4 v130, s[12:13]
	s_mov_b32 m0, s26
	s_nop 0
	global_load_lds_dwordx4 v134, s[12:13]
	s_waitcnt vmcnt(8)
	s_waitcnt lgkmcnt(0)
	s_setprio 1
	s_barrier
	v_mfma_f32_16x16x32_bf16 v[126:129], v[160:163], v[196:199], v[126:129]
	v_mfma_f32_16x16x32_bf16 v[122:125], v[170:173], v[196:199], v[122:125]
	v_mfma_f32_16x16x32_bf16 v[118:121], v[160:163], v[204:207], v[118:121]
	v_mfma_f32_16x16x32_bf16 v[110:113], v[170:173], v[204:207], v[110:113]
	v_mfma_f32_16x16x32_bf16 v[102:105], v[160:163], v[212:215], v[102:105]
	v_mfma_f32_16x16x32_bf16 v[94:97], v[170:173], v[212:215], v[94:97]
	v_mfma_f32_16x16x32_bf16 v[86:89], v[160:163], v[220:223], v[86:89]
	v_mfma_f32_16x16x32_bf16 v[78:81], v[170:173], v[220:223], v[78:81]
	v_mfma_f32_16x16x32_bf16 v[126:129], v[166:169], v[200:203], v[126:129]
	v_mfma_f32_16x16x32_bf16 v[122:125], v[174:177], v[200:203], v[122:125]
	v_mfma_f32_16x16x32_bf16 v[118:121], v[166:169], v[208:211], v[118:121]
	v_mfma_f32_16x16x32_bf16 v[110:113], v[174:177], v[208:211], v[110:113]
	v_mfma_f32_16x16x32_bf16 v[102:105], v[166:169], v[216:219], v[102:105]
	v_mfma_f32_16x16x32_bf16 v[94:97], v[174:177], v[216:219], v[94:97]
	v_mfma_f32_16x16x32_bf16 v[86:89], v[166:169], v[224:227], v[86:89]
	v_mfma_f32_16x16x32_bf16 v[78:81], v[174:177], v[224:227], v[78:81]
	v_mfma_f32_16x16x32_bf16 v[114:117], v[178:181], v[196:199], v[114:117]
	v_mfma_f32_16x16x32_bf16 v[106:109], v[188:191], v[196:199], v[106:109]
	v_mfma_f32_16x16x32_bf16 v[98:101], v[178:181], v[204:207], v[98:101]
	v_mfma_f32_16x16x32_bf16 v[90:93], v[188:191], v[204:207], v[90:93]
	v_mfma_f32_16x16x32_bf16 v[82:85], v[178:181], v[212:215], v[82:85]
	v_mfma_f32_16x16x32_bf16 v[74:77], v[188:191], v[212:215], v[74:77]
	v_mfma_f32_16x16x32_bf16 v[70:73], v[178:181], v[220:223], v[70:73]
	v_mfma_f32_16x16x32_bf16 v[66:69], v[188:191], v[220:223], v[66:69]
	v_mfma_f32_16x16x32_bf16 v[114:117], v[184:187], v[200:203], v[114:117]
	v_mfma_f32_16x16x32_bf16 v[106:109], v[192:195], v[200:203], v[106:109]
	v_mfma_f32_16x16x32_bf16 v[98:101], v[184:187], v[208:211], v[98:101]
	v_mfma_f32_16x16x32_bf16 v[90:93], v[192:195], v[208:211], v[90:93]
	v_mfma_f32_16x16x32_bf16 v[82:85], v[184:187], v[216:219], v[82:85]
	v_mfma_f32_16x16x32_bf16 v[74:77], v[192:195], v[216:219], v[74:77]
	v_mfma_f32_16x16x32_bf16 v[70:73], v[184:187], v[224:227], v[70:73]
	v_mfma_f32_16x16x32_bf16 v[66:69], v[192:195], v[224:227], v[66:69]
	s_barrier
	s_setprio 0
	s_add_i32 s12, s39, s22
	s_add_i32 m0, s12, 0xffffff80
	ds_read_b128 v[196:199], v165 offset:49152
	ds_read_b128 v[200:203], v165 offset:50176
	ds_read_b128 v[204:207], v165 offset:51200
	ds_read_b128 v[208:211], v165 offset:52224
	ds_read_b128 v[212:215], v165 offset:53248
	ds_read_b128 v[216:219], v165 offset:54272
	ds_read_b128 v[220:223], v165 offset:55296
	ds_read_b128 v[224:227], v165 offset:56320
	global_load_lds_dwordx4 v132, s[16:17] offset:128
	s_add_i32 m0, s12, 0x1f80
	s_add_u32 s12, s16, 0x44080
	s_addc_u32 s13, s17, 0
	global_load_lds_dwordx4 v152, s[16:17] offset:128
	s_add_i32 s16, s40, s22
	s_mov_b32 m0, s16
	s_nop 0
	global_load_lds_dwordx4 v132, s[12:13]
	s_add_i32 m0, s16, 0x2000
	s_nop 0
	global_load_lds_dwordx4 v152, s[12:13]
	s_add_i32 m0, s27, 0xffffff80
	s_nop 0
	global_load_lds_dwordx4 v130, s[18:19] offset:128
	s_add_i32 m0, s28, 0xffffff80
	s_nop 0
	global_load_lds_dwordx4 v134, s[18:19] offset:128
	s_waitcnt vmcnt(8)
	s_waitcnt lgkmcnt(0)
	s_setprio 1
	s_barrier
	v_mfma_f32_16x16x32_bf16 v[62:65], v[160:163], v[196:199], v[62:65]
	v_mfma_f32_16x16x32_bf16 v[58:61], v[170:173], v[196:199], v[58:61]
	v_mfma_f32_16x16x32_bf16 v[54:57], v[160:163], v[204:207], v[54:57]
	v_mfma_f32_16x16x32_bf16 v[46:49], v[170:173], v[204:207], v[46:49]
	v_mfma_f32_16x16x32_bf16 v[38:41], v[160:163], v[212:215], v[38:41]
	v_mfma_f32_16x16x32_bf16 v[30:33], v[170:173], v[212:215], v[30:33]
	v_mfma_f32_16x16x32_bf16 v[22:25], v[160:163], v[220:223], v[22:25]
	v_mfma_f32_16x16x32_bf16 v[14:17], v[170:173], v[220:223], v[14:17]
	v_mfma_f32_16x16x32_bf16 v[62:65], v[166:169], v[200:203], v[62:65]
	v_mfma_f32_16x16x32_bf16 v[58:61], v[174:177], v[200:203], v[58:61]
	v_mfma_f32_16x16x32_bf16 v[54:57], v[166:169], v[208:211], v[54:57]
	v_mfma_f32_16x16x32_bf16 v[46:49], v[174:177], v[208:211], v[46:49]
	v_mfma_f32_16x16x32_bf16 v[38:41], v[166:169], v[216:219], v[38:41]
	v_mfma_f32_16x16x32_bf16 v[30:33], v[174:177], v[216:219], v[30:33]
	v_mfma_f32_16x16x32_bf16 v[22:25], v[166:169], v[224:227], v[22:25]
	v_mfma_f32_16x16x32_bf16 v[14:17], v[174:177], v[224:227], v[14:17]
	v_mfma_f32_16x16x32_bf16 v[50:53], v[178:181], v[196:199], v[50:53]
	v_mfma_f32_16x16x32_bf16 v[42:45], v[188:191], v[196:199], v[42:45]
	v_mfma_f32_16x16x32_bf16 v[34:37], v[178:181], v[204:207], v[34:37]
	v_mfma_f32_16x16x32_bf16 v[26:29], v[188:191], v[204:207], v[26:29]
	v_mfma_f32_16x16x32_bf16 v[18:21], v[178:181], v[212:215], v[18:21]
	v_mfma_f32_16x16x32_bf16 v[10:13], v[188:191], v[212:215], v[10:13]
	v_mfma_f32_16x16x32_bf16 v[6:9], v[178:181], v[220:223], v[6:9]
	v_mfma_f32_16x16x32_bf16 v[2:5], v[188:191], v[220:223], v[2:5]
	v_mfma_f32_16x16x32_bf16 v[50:53], v[184:187], v[200:203], v[50:53]
	v_mfma_f32_16x16x32_bf16 v[42:45], v[192:195], v[200:203], v[42:45]
	v_mfma_f32_16x16x32_bf16 v[34:37], v[184:187], v[208:211], v[34:37]
	v_mfma_f32_16x16x32_bf16 v[26:29], v[192:195], v[208:211], v[26:29]
	v_mfma_f32_16x16x32_bf16 v[18:21], v[184:187], v[216:219], v[18:21]
	v_mfma_f32_16x16x32_bf16 v[10:13], v[192:195], v[216:219], v[10:13]
	v_mfma_f32_16x16x32_bf16 v[6:9], v[184:187], v[224:227], v[6:9]
	v_mfma_f32_16x16x32_bf16 v[2:5], v[192:195], v[224:227], v[2:5]
	s_barrier
	s_setprio 0
	s_add_i32 s38, s38, 2
	s_add_u32 s36, s36, 0x100
	s_addc_u32 s37, s37, 0
	s_cmp_gt_u32 s38, 13
	s_mov_b64 s[12:13], s[14:15]
	s_cbranch_scc0 .LBB0_837
	s_and_b64 vcc, exec, s[8:9]
	s_cbranch_vccz .LBB0_840
	s_barrier

; #define PG8_STAGE(bufoff, gbase, voff) do { _Pragma("unroll") for (int _i = 0; _i < 2; ++_i) \
;         __builtin_amdgcn_global_load_lds((const unsigned*)((const char*)(gbase) + (voff)[_i]), (LAS unsigned*)(lds + (bufoff) + ldsw + _i * 8192), 16, 0, 0); } while (0)
; #define PG8_LDA(dst, b, h) do { _Pragma("unroll") for (int m = 0; m < 4; ++m) _Pragma("unroll") for (int k = 0; k < 2; ++k) dst[m][k] = *(const LAS bf16x8*)(lds + PG8_SA(b, h) + aoff + m * 2048 + k * 1024); } while (0)
; #define PG8_LDB(dst, b, h) do { _Pragma("unroll") for (int n = 0; n < 2; ++n) _Pragma("unroll") for (int k = 0; k < 2; ++k) dst[n][k] = *(const LAS bf16x8*)(lds + PG8_SB(b, h) + boff + n * 2048 + k * 1024); } while (0)
; #define PG8_SCHED __builtin_amdgcn_sched_barrier(0)
; template <class Epi, bool ALIGN_EPI = PG8_ALIGN, bool SP2 = PG8_SP2>
; __device__ __forceinline__ void gemm_phase(LAS uchar* lds, const Gemm g, const StaticOrder& S, const Epi& E) {
;     ...
;         for (int t = tb; t < tb + tblk; t += 2) {
;             const bool last = (t == nt - 2);
;             const char* a1 = cA + (size_t)(t + 1) * kstep;
;             const char* a2 = last ? nA : cA + (size_t)(t + 2) * kstep; const char* b2 = last ? nB : cB + (size_t)(t + 2) * kstep;
;             const char* a3 = a2 + kstep; const char* b3 = b2 + kstep;
;             if constexpr (SP2) {
;             PG8_LDB(B0, 0, 0); PG8_LDB(B1, 0, 1); PG8_SCHED; PG8_LDA(At, 0, 0); PG8_STAGE(PG8_SA(1, 1), a1 + hstepA, voffA);
.LBB0_1049:
	s_add_u32 s36, s14, 0x100
	s_addc_u32 s37, s15, 0
	s_mov_b32 s38, -2
	s_add_u32 s14, s12, 0x100
	s_addc_u32 s15, s13, 0
	s_add_i32 s39, 0, 0x10000
	s_cmp_eq_u32 s38, 12
	s_cselect_b32 s19, s1, s15
	s_cselect_b32 s18, s0, s14
	v_add_u32_e32 v144, s39, v139
	s_cselect_b32 s17, s11, s37
	s_cselect_b32 s16, s10, s36
	s_add_i32 s40, 0, 0x14000
	ds_read_b128 v[164:167], v144
	ds_read_b128 v[168:171], v144 offset:1024
	ds_read_b128 v[172:175], v144 offset:2048
	ds_read_b128 v[176:179], v144 offset:3072
	v_add_u32_e32 v144, s40, v139
	ds_read_b128 v[184:187], v144
	ds_read_b128 v[188:191], v144 offset:1024
	ds_read_b128 v[192:195], v144 offset:2048
	ds_read_b128 v[196:199], v144 offset:3072
	s_add_i32 m0, s23, 0xc000
	ds_read_b128 v[200:203], v163
	ds_read_b128 v[204:207], v163 offset:1024
	ds_read_b128 v[208:211], v163 offset:2048
	ds_read_b128 v[212:215], v163 offset:3072
	ds_read_b128 v[216:219], v163 offset:4096
	ds_read_b128 v[220:223], v163 offset:5120
	ds_read_b128 v[224:227], v163 offset:6144
	ds_read_b128 v[228:231], v163 offset:7168
	global_load_lds_dwordx4 v156, s[12:13]
	s_add_i32 m0, s23, 0xe000
	s_nop 0
	global_load_lds_dwordx4 v158, s[12:13]
	s_cmp_lt_u32 s29, 2
	s_cbranch_scc1 .Lrw_std_1050_0_pl
	s_waitcnt vmcnt(16)
	s_branch .Lrw_done_1050_0_pl

; #define PG8_STAGE(bufoff, gbase, voff) do { _Pragma("unroll") for (int _i = 0; _i < 2; ++_i) \
;         __builtin_amdgcn_global_load_lds((const unsigned*)((const char*)(gbase) + (voff)[_i]), (LAS unsigned*)(lds + (bufoff) + ldsw + _i * 8192), 16, 0, 0); } while (0)
; #define PG8_LDA(dst, b, h) do { _Pragma("unroll") for (int m = 0; m < 4; ++m) _Pragma("unroll") for (int k = 0; k < 2; ++k) dst[m][k] = *(const LAS bf16x8*)(lds + PG8_SA(b, h) + aoff + m * 2048 + k * 1024); } while (0)
; #define PG8_LDB(dst, b, h) do { _Pragma("unroll") for (int n = 0; n < 2; ++n) _Pragma("unroll") for (int k = 0; k < 2; ++k) dst[n][k] = *(const LAS bf16x8*)(lds + PG8_SB(b, h) + boff + n * 2048 + k * 1024); } while (0)
; #define PG8_MMA(ai, bj, At, Bt) do { __builtin_amdgcn_s_setprio(1); _Pragma("unroll") for (int m = 0; m < 4; ++m) _Pragma("unroll") for (int n = 0; n < 2; ++n) _Pragma("unroll") for (int k = 0; k < 2; ++k) \
;         acc[ai][bj][m][n] = __builtin_amdgcn_mfma_f32_16x16x32_bf16(Bt[n][k], At[m][k], acc[ai][bj][m][n], 0, 0, 0); __builtin_amdgcn_s_setprio(0); } while (0)
; #define PG8_WAIT_V(n) asm volatile("s_waitcnt vmcnt(" #n ")" ::: "memory")
; #define PG8_WAIT_L(n) asm volatile("s_waitcnt lgkmcnt(" #n ")" ::: "memory")
; #define PG8_BAR __builtin_amdgcn_s_barrier()
; #define PG8_SCHED __builtin_amdgcn_sched_barrier(0)
; template <class Epi, bool ALIGN_EPI = PG8_ALIGN, bool SP2 = PG8_SP2>
; __device__ __forceinline__ void gemm_phase(LAS uchar* lds, const Gemm g, const StaticOrder& S, const Epi& E) {
;     ...
;             PG8_LDB(B0, 0, 0); PG8_LDB(B1, 0, 1); PG8_SCHED; PG8_LDA(At, 0, 0); PG8_STAGE(PG8_SA(1, 1), a1 + hstepA, voffA);
;             PG8_WAIT_V(8); PG8_WAIT_L(0); PG8_BAR; PG8_MMA(0, 0, At, B0); PG8_MMA(0, 1, At, B1); PG8_BAR; PG8_SCHED;
;             PG8_LDA(At, 0, 1); PG8_STAGE(PG8_SB(0, 0), b2, voffB); PG8_STAGE(PG8_SB(0, 1), b2 + hstepB, voffB); PG8_STAGE(PG8_SA(0, 0), a2, voffA);
;             PG8_WAIT_V(8); PG8_WAIT_L(0); PG8_BAR; PG8_MMA(1, 0, At, B0); PG8_MMA(1, 1, At, B1); PG8_BAR; PG8_SCHED;
.Lrw_done_1050_0_pl:
	s_waitcnt lgkmcnt(0)
	s_setprio 1
	s_barrier
	v_mfma_f32_16x16x32_bf16 v[126:129], v[164:167], v[200:203], 0
	v_mfma_f32_16x16x32_bf16 v[118:121], v[172:175], v[200:203], 0
	v_mfma_f32_16x16x32_bf16 v[110:113], v[164:167], v[208:211], 0
	v_mfma_f32_16x16x32_bf16 v[102:105], v[172:175], v[208:211], 0
	v_mfma_f32_16x16x32_bf16 v[94:97], v[164:167], v[216:219], 0
	v_mfma_f32_16x16x32_bf16 v[86:89], v[172:175], v[216:219], 0
	v_mfma_f32_16x16x32_bf16 v[78:81], v[164:167], v[224:227], 0
	v_mfma_f32_16x16x32_bf16 v[70:73], v[172:175], v[224:227], 0
	v_mfma_f32_16x16x32_bf16 v[126:129], v[168:171], v[204:207], v[126:129]
	v_mfma_f32_16x16x32_bf16 v[118:121], v[176:179], v[204:207], v[118:121]
	v_mfma_f32_16x16x32_bf16 v[110:113], v[168:171], v[212:215], v[110:113]
	v_mfma_f32_16x16x32_bf16 v[102:105], v[176:179], v[212:215], v[102:105]
	v_mfma_f32_16x16x32_bf16 v[94:97], v[168:171], v[220:223], v[94:97]
	v_mfma_f32_16x16x32_bf16 v[86:89], v[176:179], v[220:223], v[86:89]
	v_mfma_f32_16x16x32_bf16 v[78:81], v[168:171], v[228:231], v[78:81]
	v_mfma_f32_16x16x32_bf16 v[70:73], v[176:179], v[228:231], v[70:73]
	v_mfma_f32_16x16x32_bf16 v[122:125], v[184:187], v[200:203], 0
	v_mfma_f32_16x16x32_bf16 v[114:117], v[192:195], v[200:203], 0
	v_mfma_f32_16x16x32_bf16 v[106:109], v[184:187], v[208:211], 0
	v_mfma_f32_16x16x32_bf16 v[98:101], v[192:195], v[208:211], 0
	v_mfma_f32_16x16x32_bf16 v[90:93], v[184:187], v[216:219], 0
	v_mfma_f32_16x16x32_bf16 v[82:85], v[192:195], v[216:219], 0
	v_mfma_f32_16x16x32_bf16 v[74:77], v[184:187], v[224:227], 0
	v_mfma_f32_16x16x32_bf16 v[66:69], v[192:195], v[224:227], 0
	v_mfma_f32_16x16x32_bf16 v[122:125], v[188:191], v[204:207], v[122:125]
	v_mfma_f32_16x16x32_bf16 v[114:117], v[196:199], v[204:207], v[114:117]
	v_mfma_f32_16x16x32_bf16 v[106:109], v[188:191], v[212:215], v[106:109]
	v_mfma_f32_16x16x32_bf16 v[98:101], v[196:199], v[212:215], v[98:101]
	v_mfma_f32_16x16x32_bf16 v[90:93], v[188:191], v[220:223], v[90:93]
	v_mfma_f32_16x16x32_bf16 v[82:85], v[196:199], v[220:223], v[82:85]
	v_mfma_f32_16x16x32_bf16 v[74:77], v[188:191], v[228:231], v[74:77]
	v_mfma_f32_16x16x32_bf16 v[66:69], v[196:199], v[228:231], v[66:69]
	s_barrier
	s_setprio 0
	s_add_i32 s12, s39, s21
	s_mov_b32 m0, s12
	ds_read_b128 v[200:203], v163 offset:16384
	ds_read_b128 v[204:207], v163 offset:17408
	ds_read_b128 v[208:211], v163 offset:18432
	ds_read_b128 v[212:215], v163 offset:19456
	ds_read_b128 v[216:219], v163 offset:20480
	ds_read_b128 v[220:223], v163 offset:21504
	ds_read_b128 v[224:227], v163 offset:22528
	ds_read_b128 v[228:231], v163 offset:23552
	global_load_lds_dwordx4 v134, s[16:17]
	s_add_i32 m0, s12, 0x2000
	s_add_u32 s12, s16, 0x44000
	s_addc_u32 s13, s17, 0
	s_add_i32 s39, s40, s21
	global_load_lds_dwordx4 v130, s[16:17]
	s_mov_b32 m0, s39
	s_nop 0
	global_load_lds_dwordx4 v134, s[12:13]
	s_add_i32 m0, s39, 0x2000
	s_nop 0
	global_load_lds_dwordx4 v130, s[12:13]
	s_mov_b32 m0, s23
	s_nop 0
	global_load_lds_dwordx4 v154, s[18:19]
	s_mov_b32 m0, s24
	s_nop 0
	global_load_lds_dwordx4 v132, s[18:19]
	s_cmp_lt_u32 s29, 2
	s_cbranch_scc1 .Lrw_std_1050_1_pl
	s_waitcnt vmcnt(16)
	s_branch .Lrw_done_1050_1_pl

; #define PG8_STAGE(bufoff, gbase, voff) do { _Pragma("unroll") for (int _i = 0; _i < 2; ++_i) \
;         __builtin_amdgcn_global_load_lds((const unsigned*)((const char*)(gbase) + (voff)[_i]), (LAS unsigned*)(lds + (bufoff) + ldsw + _i * 8192), 16, 0, 0); } while (0)
; #define PG8_LDA(dst, b, h) do { _Pragma("unroll") for (int m = 0; m < 4; ++m) _Pragma("unroll") for (int k = 0; k < 2; ++k) dst[m][k] = *(const LAS bf16x8*)(lds + PG8_SA(b, h) + aoff + m * 2048 + k * 1024); } while (0)
; #define PG8_LDB(dst, b, h) do { _Pragma("unroll") for (int n = 0; n < 2; ++n) _Pragma("unroll") for (int k = 0; k < 2; ++k) dst[n][k] = *(const LAS bf16x8*)(lds + PG8_SB(b, h) + boff + n * 2048 + k * 1024); } while (0)
; #define PG8_MMA(ai, bj, At, Bt) do { __builtin_amdgcn_s_setprio(1); _Pragma("unroll") for (int m = 0; m < 4; ++m) _Pragma("unroll") for (int n = 0; n < 2; ++n) _Pragma("unroll") for (int k = 0; k < 2; ++k) \
;         acc[ai][bj][m][n] = __builtin_amdgcn_mfma_f32_16x16x32_bf16(Bt[n][k], At[m][k], acc[ai][bj][m][n], 0, 0, 0); __builtin_amdgcn_s_setprio(0); } while (0)
; #define PG8_WAIT_V(n) asm volatile("s_waitcnt vmcnt(" #n ")" ::: "memory")
; #define PG8_WAIT_L(n) asm volatile("s_waitcnt lgkmcnt(" #n ")" ::: "memory")
; #define PG8_BAR __builtin_amdgcn_s_barrier()
; #define PG8_SCHED __builtin_amdgcn_sched_barrier(0)
; template <class Epi, bool ALIGN_EPI = PG8_ALIGN, bool SP2 = PG8_SP2>
; __device__ __forceinline__ void gemm_phase(LAS uchar* lds, const Gemm g, const StaticOrder& S, const Epi& E) {
;     ...
;             PG8_WAIT_V(8); PG8_WAIT_L(0); PG8_BAR; PG8_MMA(0, 0, At, B0); PG8_MMA(0, 1, At, B1); PG8_BAR; PG8_SCHED;
;             PG8_LDA(At, 0, 1); PG8_STAGE(PG8_SB(0, 0), b2, voffB); PG8_STAGE(PG8_SB(0, 1), b2 + hstepB, voffB); PG8_STAGE(PG8_SA(0, 0), a2, voffA);
;             PG8_WAIT_V(8); PG8_WAIT_L(0); PG8_BAR; PG8_MMA(1, 0, At, B0); PG8_MMA(1, 1, At, B1); PG8_BAR; PG8_SCHED;
;             PG8_LDB(B0, 1, 0); PG8_LDB(B1, 1, 1); PG8_SCHED; PG8_LDA(At, 1, 0); PG8_STAGE(PG8_SA(0, 1), a2 + hstepA, voffA);
;             PG8_WAIT_V(8); PG8_WAIT_L(0); PG8_BAR; PG8_MMA(0, 0, At, B0); PG8_MMA(0, 1, At, B1); PG8_BAR; PG8_SCHED;
.Lrw_done_1050_1_pl:
	s_waitcnt lgkmcnt(0)
	s_setprio 1
	s_barrier
	v_mfma_f32_16x16x32_bf16 v[62:65], v[164:167], v[200:203], 0
	v_mfma_f32_16x16x32_bf16 v[54:57], v[172:175], v[200:203], 0
	v_mfma_f32_16x16x32_bf16 v[46:49], v[164:167], v[208:211], 0
	v_mfma_f32_16x16x32_bf16 v[38:41], v[172:175], v[208:211], 0
	v_mfma_f32_16x16x32_bf16 v[30:33], v[164:167], v[216:219], 0
	v_mfma_f32_16x16x32_bf16 v[22:25], v[172:175], v[216:219], 0
	v_mfma_f32_16x16x32_bf16 v[14:17], v[164:167], v[224:227], 0
	v_mfma_f32_16x16x32_bf16 v[6:9], v[172:175], v[224:227], 0
	v_mfma_f32_16x16x32_bf16 v[62:65], v[168:171], v[204:207], v[62:65]
	v_mfma_f32_16x16x32_bf16 v[54:57], v[176:179], v[204:207], v[54:57]
	v_mfma_f32_16x16x32_bf16 v[46:49], v[168:171], v[212:215], v[46:49]
	v_mfma_f32_16x16x32_bf16 v[38:41], v[176:179], v[212:215], v[38:41]
	v_mfma_f32_16x16x32_bf16 v[30:33], v[168:171], v[220:223], v[30:33]
	v_mfma_f32_16x16x32_bf16 v[22:25], v[176:179], v[220:223], v[22:25]
	v_mfma_f32_16x16x32_bf16 v[14:17], v[168:171], v[228:231], v[14:17]
	v_mfma_f32_16x16x32_bf16 v[6:9], v[176:179], v[228:231], v[6:9]
	v_mfma_f32_16x16x32_bf16 v[58:61], v[184:187], v[200:203], 0
	v_mfma_f32_16x16x32_bf16 v[50:53], v[192:195], v[200:203], 0
	v_mfma_f32_16x16x32_bf16 v[42:45], v[184:187], v[208:211], 0
	v_mfma_f32_16x16x32_bf16 v[34:37], v[192:195], v[208:211], 0
	v_mfma_f32_16x16x32_bf16 v[26:29], v[184:187], v[216:219], 0
	v_mfma_f32_16x16x32_bf16 v[18:21], v[192:195], v[216:219], 0
	v_mfma_f32_16x16x32_bf16 v[10:13], v[184:187], v[224:227], 0
	v_mfma_f32_16x16x32_bf16 v[2:5], v[192:195], v[224:227], 0
	v_mfma_f32_16x16x32_bf16 v[58:61], v[188:191], v[204:207], v[58:61]
	v_mfma_f32_16x16x32_bf16 v[50:53], v[196:199], v[204:207], v[50:53]
	v_mfma_f32_16x16x32_bf16 v[42:45], v[188:191], v[212:215], v[42:45]
	v_mfma_f32_16x16x32_bf16 v[34:37], v[196:199], v[212:215], v[34:37]
	v_mfma_f32_16x16x32_bf16 v[26:29], v[188:191], v[220:223], v[26:29]
	v_mfma_f32_16x16x32_bf16 v[18:21], v[196:199], v[220:223], v[18:21]
	v_mfma_f32_16x16x32_bf16 v[10:13], v[188:191], v[228:231], v[10:13]
	v_mfma_f32_16x16x32_bf16 v[2:5], v[196:199], v[228:231], v[2:5]
	s_barrier
	s_setprio 0
	s_add_i32 s39, 0, 0x18000
	v_add_u32_e32 v144, s39, v139
	s_add_i32 s40, 0, 0x1c000
	ds_read_b128 v[164:167], v144
	ds_read_b128 v[168:171], v144 offset:1024
	ds_read_b128 v[172:175], v144 offset:2048
	ds_read_b128 v[176:179], v144 offset:3072
	v_add_u32_e32 v144, s40, v139
	ds_read_b128 v[184:187], v144
	ds_read_b128 v[188:191], v144 offset:1024
	ds_read_b128 v[192:195], v144 offset:2048
	ds_read_b128 v[196:199], v144 offset:3072
	s_add_u32 s12, s18, 0x44000
	s_addc_u32 s13, s19, 0
	s_mov_b32 m0, s25
	ds_read_b128 v[200:203], v163 offset:32768
	ds_read_b128 v[204:207], v163 offset:33792
	ds_read_b128 v[208:211], v163 offset:34816
	ds_read_b128 v[212:215], v163 offset:35840
	ds_read_b128 v[216:219], v163 offset:36864
	ds_read_b128 v[220:223], v163 offset:37888
	ds_read_b128 v[224:227], v163 offset:38912
	ds_read_b128 v[228:231], v163 offset:39936
	global_load_lds_dwordx4 v154, s[12:13]
	s_mov_b32 m0, s26
	s_nop 0
	global_load_lds_dwordx4 v132, s[12:13]
	s_waitcnt vmcnt(8)
	s_waitcnt lgkmcnt(0)
	s_setprio 1
	s_barrier
	v_mfma_f32_16x16x32_bf16 v[126:129], v[164:167], v[200:203], v[126:129]
	v_mfma_f32_16x16x32_bf16 v[118:121], v[172:175], v[200:203], v[118:121]
	v_mfma_f32_16x16x32_bf16 v[110:113], v[164:167], v[208:211], v[110:113]
	v_mfma_f32_16x16x32_bf16 v[102:105], v[172:175], v[208:211], v[102:105]
	v_mfma_f32_16x16x32_bf16 v[94:97], v[164:167], v[216:219], v[94:97]
	v_mfma_f32_16x16x32_bf16 v[86:89], v[172:175], v[216:219], v[86:89]
	v_mfma_f32_16x16x32_bf16 v[78:81], v[164:167], v[224:227], v[78:81]
	v_mfma_f32_16x16x32_bf16 v[70:73], v[172:175], v[224:227], v[70:73]
	v_mfma_f32_16x16x32_bf16 v[126:129], v[168:171], v[204:207], v[126:129]
	v_mfma_f32_16x16x32_bf16 v[118:121], v[176:179], v[204:207], v[118:121]
	v_mfma_f32_16x16x32_bf16 v[110:113], v[168:171], v[212:215], v[110:113]
	v_mfma_f32_16x16x32_bf16 v[102:105], v[176:179], v[212:215], v[102:105]
	v_mfma_f32_16x16x32_bf16 v[94:97], v[168:171], v[220:223], v[94:97]
	v_mfma_f32_16x16x32_bf16 v[86:89], v[176:179], v[220:223], v[86:89]
	v_mfma_f32_16x16x32_bf16 v[78:81], v[168:171], v[228:231], v[78:81]
	v_mfma_f32_16x16x32_bf16 v[70:73], v[176:179], v[228:231], v[70:73]
	v_mfma_f32_16x16x32_bf16 v[122:125], v[184:187], v[200:203], v[122:125]
	v_mfma_f32_16x16x32_bf16 v[114:117], v[192:195], v[200:203], v[114:117]
	v_mfma_f32_16x16x32_bf16 v[106:109], v[184:187], v[208:211], v[106:109]
	v_mfma_f32_16x16x32_bf16 v[98:101], v[192:195], v[208:211], v[98:101]
	v_mfma_f32_16x16x32_bf16 v[90:93], v[184:187], v[216:219], v[90:93]
	v_mfma_f32_16x16x32_bf16 v[82:85], v[192:195], v[216:219], v[82:85]
	v_mfma_f32_16x16x32_bf16 v[74:77], v[184:187], v[224:227], v[74:77]
	v_mfma_f32_16x16x32_bf16 v[66:69], v[192:195], v[224:227], v[66:69]
	v_mfma_f32_16x16x32_bf16 v[122:125], v[188:191], v[204:207], v[122:125]
	v_mfma_f32_16x16x32_bf16 v[114:117], v[196:199], v[204:207], v[114:117]
	v_mfma_f32_16x16x32_bf16 v[106:109], v[188:191], v[212:215], v[106:109]
	v_mfma_f32_16x16x32_bf16 v[98:101], v[196:199], v[212:215], v[98:101]
	v_mfma_f32_16x16x32_bf16 v[90:93], v[188:191], v[220:223], v[90:93]
	v_mfma_f32_16x16x32_bf16 v[82:85], v[196:199], v[220:223], v[82:85]
	v_mfma_f32_16x16x32_bf16 v[74:77], v[188:191], v[228:231], v[74:77]
	v_mfma_f32_16x16x32_bf16 v[66:69], v[196:199], v[228:231], v[66:69]
	s_barrier
; #define PG8_STAGE(bufoff, gbase, voff) do { _Pragma("unroll") for (int _i = 0; _i < 2; ++_i) \
;         __builtin_amdgcn_global_load_lds((const unsigned*)((const char*)(gbase) + (voff)[_i]), (LAS unsigned*)(lds + (bufoff) + ldsw + _i * 8192), 16, 0, 0); } while (0)
; #define PG8_LDA(dst, b, h) do { _Pragma("unroll") for (int m = 0; m < 4; ++m) _Pragma("unroll") for (int k = 0; k < 2; ++k) dst[m][k] = *(const LAS bf16x8*)(lds + PG8_SA(b, h) + aoff + m * 2048 + k * 1024); } while (0)
; #define PG8_LDB(dst, b, h) do { _Pragma("unroll") for (int n = 0; n < 2; ++n) _Pragma("unroll") for (int k = 0; k < 2; ++k) dst[n][k] = *(const LAS bf16x8*)(lds + PG8_SB(b, h) + boff + n * 2048 + k * 1024); } while (0)
; #define PG8_MMA(ai, bj, At, Bt) do { __builtin_amdgcn_s_setprio(1); _Pragma("unroll") for (int m = 0; m < 4; ++m) _Pragma("unroll") for (int n = 0; n < 2; ++n) _Pragma("unroll") for (int k = 0; k < 2; ++k) \
;         acc[ai][bj][m][n] = __builtin_amdgcn_mfma_f32_16x16x32_bf16(Bt[n][k], At[m][k], acc[ai][bj][m][n], 0, 0, 0); __builtin_amdgcn_s_setprio(0); } while (0)
; #define PG8_WAIT_V(n) asm volatile("s_waitcnt vmcnt(" #n ")" ::: "memory")
; #define PG8_WAIT_L(n) asm volatile("s_waitcnt lgkmcnt(" #n ")" ::: "memory")
; #define PG8_BAR __builtin_amdgcn_s_barrier()
; template <class Epi, bool ALIGN_EPI = PG8_ALIGN, bool SP2 = PG8_SP2>
; __device__ __forceinline__ void gemm_phase(LAS uchar* lds, const Gemm g, const StaticOrder& S, const Epi& E) {
;     ...
;         for (int t = tb; t < tb + tblk; t += 2) {
;             const bool last = (t == nt - 2);
;             const char* a1 = cA + (size_t)(t + 1) * kstep;
;             const char* a2 = last ? nA : cA + (size_t)(t + 2) * kstep; const char* b2 = last ? nB : cB + (size_t)(t + 2) * kstep;
;             const char* a3 = a2 + kstep; const char* b3 = b2 + kstep;
;             if constexpr (SP2) {
;             PG8_LDB(B0, 0, 0); PG8_LDB(B1, 0, 1); PG8_SCHED; PG8_LDA(At, 0, 0); PG8_STAGE(PG8_SA(1, 1), a1 + hstepA, voffA);
;             PG8_WAIT_V(8); PG8_WAIT_L(0); PG8_BAR; PG8_MMA(0, 0, At, B0); PG8_MMA(0, 1, At, B1); PG8_BAR; PG8_SCHED;
;     ...
;             PG8_LDA(At, 1, 1); PG8_STAGE(PG8_SB(1, 0), b3, voffB); PG8_STAGE(PG8_SB(1, 1), b3 + hstepB, voffB); PG8_STAGE(PG8_SA(1, 0), a3, voffA);
;             PG8_WAIT_V(8); PG8_WAIT_L(0); PG8_BAR; PG8_MMA(1, 0, At, B0); PG8_MMA(1, 1, At, B1); PG8_BAR; PG8_SCHED;
	s_setprio 0
	s_add_i32 s12, s39, s21
	s_add_i32 m0, s12, 0xffffff80
	ds_read_b128 v[200:203], v163 offset:49152
	ds_read_b128 v[204:207], v163 offset:50176
	ds_read_b128 v[208:211], v163 offset:51200
	ds_read_b128 v[212:215], v163 offset:52224
	ds_read_b128 v[216:219], v163 offset:53248
	ds_read_b128 v[220:223], v163 offset:54272
	ds_read_b128 v[224:227], v163 offset:55296
	ds_read_b128 v[228:231], v163 offset:56320
	global_load_lds_dwordx4 v134, s[16:17] offset:128
	s_add_i32 m0, s12, 0x1f80
	s_add_u32 s12, s16, 0x44080
	s_addc_u32 s13, s17, 0
	global_load_lds_dwordx4 v130, s[16:17] offset:128
	s_add_i32 s16, s40, s21
	s_mov_b32 m0, s16
	s_nop 0
	global_load_lds_dwordx4 v134, s[12:13]
	s_add_i32 m0, s16, 0x2000
	s_nop 0
	global_load_lds_dwordx4 v130, s[12:13]
	s_add_i32 m0, s27, 0xffffff80
	s_nop 0
	global_load_lds_dwordx4 v154, s[18:19] offset:128
	s_add_i32 m0, s28, 0xffffff80
	s_nop 0
	global_load_lds_dwordx4 v132, s[18:19] offset:128
	s_waitcnt vmcnt(8)
	s_waitcnt lgkmcnt(0)
	s_setprio 1
	s_barrier
	v_mfma_f32_16x16x32_bf16 v[62:65], v[164:167], v[200:203], v[62:65]
	v_mfma_f32_16x16x32_bf16 v[54:57], v[172:175], v[200:203], v[54:57]
	v_mfma_f32_16x16x32_bf16 v[46:49], v[164:167], v[208:211], v[46:49]
	v_mfma_f32_16x16x32_bf16 v[38:41], v[172:175], v[208:211], v[38:41]
	v_mfma_f32_16x16x32_bf16 v[30:33], v[164:167], v[216:219], v[30:33]
	v_mfma_f32_16x16x32_bf16 v[22:25], v[172:175], v[216:219], v[22:25]
	v_mfma_f32_16x16x32_bf16 v[14:17], v[164:167], v[224:227], v[14:17]
	v_mfma_f32_16x16x32_bf16 v[6:9], v[172:175], v[224:227], v[6:9]
	v_mfma_f32_16x16x32_bf16 v[62:65], v[168:171], v[204:207], v[62:65]
	v_mfma_f32_16x16x32_bf16 v[54:57], v[176:179], v[204:207], v[54:57]
	v_mfma_f32_16x16x32_bf16 v[46:49], v[168:171], v[212:215], v[46:49]
	v_mfma_f32_16x16x32_bf16 v[38:41], v[176:179], v[212:215], v[38:41]
	v_mfma_f32_16x16x32_bf16 v[30:33], v[168:171], v[220:223], v[30:33]
	v_mfma_f32_16x16x32_bf16 v[22:25], v[176:179], v[220:223], v[22:25]
	v_mfma_f32_16x16x32_bf16 v[14:17], v[168:171], v[228:231], v[14:17]
	v_mfma_f32_16x16x32_bf16 v[6:9], v[176:179], v[228:231], v[6:9]
	v_mfma_f32_16x16x32_bf16 v[58:61], v[184:187], v[200:203], v[58:61]
	v_mfma_f32_16x16x32_bf16 v[50:53], v[192:195], v[200:203], v[50:53]
	v_mfma_f32_16x16x32_bf16 v[42:45], v[184:187], v[208:211], v[42:45]
	v_mfma_f32_16x16x32_bf16 v[34:37], v[192:195], v[208:211], v[34:37]
	v_mfma_f32_16x16x32_bf16 v[26:29], v[184:187], v[216:219], v[26:29]
	v_mfma_f32_16x16x32_bf16 v[18:21], v[192:195], v[216:219], v[18:21]
	v_mfma_f32_16x16x32_bf16 v[10:13], v[184:187], v[224:227], v[10:13]
	v_mfma_f32_16x16x32_bf16 v[2:5], v[192:195], v[224:227], v[2:5]
	v_mfma_f32_16x16x32_bf16 v[58:61], v[188:191], v[204:207], v[58:61]
	v_mfma_f32_16x16x32_bf16 v[50:53], v[196:199], v[204:207], v[50:53]
	v_mfma_f32_16x16x32_bf16 v[42:45], v[188:191], v[212:215], v[42:45]
	v_mfma_f32_16x16x32_bf16 v[34:37], v[196:199], v[212:215], v[34:37]
	v_mfma_f32_16x16x32_bf16 v[26:29], v[188:191], v[220:223], v[26:29]
	v_mfma_f32_16x16x32_bf16 v[18:21], v[196:199], v[220:223], v[18:21]
	v_mfma_f32_16x16x32_bf16 v[10:13], v[188:191], v[228:231], v[10:13]
	v_mfma_f32_16x16x32_bf16 v[2:5], v[196:199], v[228:231], v[2:5]
	s_barrier
	s_setprio 0
	s_add_i32 s38, s38, 2
	s_add_u32 s36, s36, 0x100
	s_addc_u32 s37, s37, 0
	s_cmp_gt_u32 s38, 13
	s_mov_b64 s[12:13], s[14:15]
.LBB0_1050:
	s_add_u32 s14, s12, 0x100
	s_addc_u32 s15, s13, 0
	s_add_i32 s39, 0, 0x10000
	s_cmp_eq_u32 s38, 12
	s_cselect_b32 s19, s1, s15
	s_cselect_b32 s18, s0, s14
	v_add_u32_e32 v144, s39, v139
	s_cselect_b32 s17, s11, s37
	s_cselect_b32 s16, s10, s36
	s_add_i32 s40, 0, 0x14000
	ds_read_b128 v[164:167], v144
	ds_read_b128 v[168:171], v144 offset:1024
	ds_read_b128 v[172:175], v144 offset:2048
	ds_read_b128 v[176:179], v144 offset:3072
	v_add_u32_e32 v144, s40, v139
	ds_read_b128 v[184:187], v144
	ds_read_b128 v[188:191], v144 offset:1024
	ds_read_b128 v[192:195], v144 offset:2048
	ds_read_b128 v[196:199], v144 offset:3072
	s_add_i32 m0, s23, 0xc000
	ds_read_b128 v[200:203], v163
	ds_read_b128 v[204:207], v163 offset:1024
	ds_read_b128 v[208:211], v163 offset:2048
	ds_read_b128 v[212:215], v163 offset:3072
	ds_read_b128 v[216:219], v163 offset:4096
	ds_read_b128 v[220:223], v163 offset:5120
	ds_read_b128 v[224:227], v163 offset:6144
	ds_read_b128 v[228:231], v163 offset:7168
	global_load_lds_dwordx4 v156, s[12:13]
	s_add_i32 m0, s23, 0xe000
	s_nop 0
	global_load_lds_dwordx4 v158, s[12:13]
	s_waitcnt vmcnt(8)
	s_waitcnt lgkmcnt(0)
	s_setprio 1
	s_barrier
; #define PG8_STAGE(bufoff, gbase, voff) do { _Pragma("unroll") for (int _i = 0; _i < 2; ++_i) \
;         __builtin_amdgcn_global_load_lds((const unsigned*)((const char*)(gbase) + (voff)[_i]), (LAS unsigned*)(lds + (bufoff) + ldsw + _i * 8192), 16, 0, 0); } while (0)
; #define PG8_LDA(dst, b, h) do { _Pragma("unroll") for (int m = 0; m < 4; ++m) _Pragma("unroll") for (int k = 0; k < 2; ++k) dst[m][k] = *(const LAS bf16x8*)(lds + PG8_SA(b, h) + aoff + m * 2048 + k * 1024); } while (0)
; #define PG8_MMA(ai, bj, At, Bt) do { __builtin_amdgcn_s_setprio(1); _Pragma("unroll") for (int m = 0; m < 4; ++m) _Pragma("unroll") for (int n = 0; n < 2; ++n) _Pragma("unroll") for (int k = 0; k < 2; ++k) \
;         acc[ai][bj][m][n] = __builtin_amdgcn_mfma_f32_16x16x32_bf16(Bt[n][k], At[m][k], acc[ai][bj][m][n], 0, 0, 0); __builtin_amdgcn_s_setprio(0); } while (0)
; #define PG8_WAIT_V(n) asm volatile("s_waitcnt vmcnt(" #n ")" ::: "memory")
; #define PG8_WAIT_L(n) asm volatile("s_waitcnt lgkmcnt(" #n ")" ::: "memory")
; #define PG8_BAR __builtin_amdgcn_s_barrier()
; #define PG8_SCHED __builtin_amdgcn_sched_barrier(0)
; template <class Epi, bool ALIGN_EPI = PG8_ALIGN, bool SP2 = PG8_SP2>
; __device__ __forceinline__ void gemm_phase(LAS uchar* lds, const Gemm g, const StaticOrder& S, const Epi& E) {
;     ...
;             PG8_WAIT_V(8); PG8_WAIT_L(0); PG8_BAR; PG8_MMA(0, 0, At, B0); PG8_MMA(0, 1, At, B1); PG8_BAR; PG8_SCHED;
;             PG8_LDA(At, 0, 1); PG8_STAGE(PG8_SB(0, 0), b2, voffB); PG8_STAGE(PG8_SB(0, 1), b2 + hstepB, voffB); PG8_STAGE(PG8_SA(0, 0), a2, voffA);
;             PG8_WAIT_V(8); PG8_WAIT_L(0); PG8_BAR; PG8_MMA(1, 0, At, B0); PG8_MMA(1, 1, At, B1); PG8_BAR; PG8_SCHED;
	v_mfma_f32_16x16x32_bf16 v[126:129], v[164:167], v[200:203], v[126:129]
	v_mfma_f32_16x16x32_bf16 v[118:121], v[172:175], v[200:203], v[118:121]
	v_mfma_f32_16x16x32_bf16 v[110:113], v[164:167], v[208:211], v[110:113]
	v_mfma_f32_16x16x32_bf16 v[102:105], v[172:175], v[208:211], v[102:105]
	v_mfma_f32_16x16x32_bf16 v[94:97], v[164:167], v[216:219], v[94:97]
	v_mfma_f32_16x16x32_bf16 v[86:89], v[172:175], v[216:219], v[86:89]
	v_mfma_f32_16x16x32_bf16 v[78:81], v[164:167], v[224:227], v[78:81]
	v_mfma_f32_16x16x32_bf16 v[70:73], v[172:175], v[224:227], v[70:73]
	v_mfma_f32_16x16x32_bf16 v[126:129], v[168:171], v[204:207], v[126:129]
	v_mfma_f32_16x16x32_bf16 v[118:121], v[176:179], v[204:207], v[118:121]
	v_mfma_f32_16x16x32_bf16 v[110:113], v[168:171], v[212:215], v[110:113]
	v_mfma_f32_16x16x32_bf16 v[102:105], v[176:179], v[212:215], v[102:105]
	v_mfma_f32_16x16x32_bf16 v[94:97], v[168:171], v[220:223], v[94:97]
	v_mfma_f32_16x16x32_bf16 v[86:89], v[176:179], v[220:223], v[86:89]
	v_mfma_f32_16x16x32_bf16 v[78:81], v[168:171], v[228:231], v[78:81]
	v_mfma_f32_16x16x32_bf16 v[70:73], v[176:179], v[228:231], v[70:73]
	v_mfma_f32_16x16x32_bf16 v[122:125], v[184:187], v[200:203], v[122:125]
	v_mfma_f32_16x16x32_bf16 v[114:117], v[192:195], v[200:203], v[114:117]
	v_mfma_f32_16x16x32_bf16 v[106:109], v[184:187], v[208:211], v[106:109]
	v_mfma_f32_16x16x32_bf16 v[98:101], v[192:195], v[208:211], v[98:101]
	v_mfma_f32_16x16x32_bf16 v[90:93], v[184:187], v[216:219], v[90:93]
	v_mfma_f32_16x16x32_bf16 v[82:85], v[192:195], v[216:219], v[82:85]
	v_mfma_f32_16x16x32_bf16 v[74:77], v[184:187], v[224:227], v[74:77]
	v_mfma_f32_16x16x32_bf16 v[66:69], v[192:195], v[224:227], v[66:69]
	v_mfma_f32_16x16x32_bf16 v[122:125], v[188:191], v[204:207], v[122:125]
	v_mfma_f32_16x16x32_bf16 v[114:117], v[196:199], v[204:207], v[114:117]
	v_mfma_f32_16x16x32_bf16 v[106:109], v[188:191], v[212:215], v[106:109]
	v_mfma_f32_16x16x32_bf16 v[98:101], v[196:199], v[212:215], v[98:101]
	v_mfma_f32_16x16x32_bf16 v[90:93], v[188:191], v[220:223], v[90:93]
	v_mfma_f32_16x16x32_bf16 v[82:85], v[196:199], v[220:223], v[82:85]
	v_mfma_f32_16x16x32_bf16 v[74:77], v[188:191], v[228:231], v[74:77]
	v_mfma_f32_16x16x32_bf16 v[66:69], v[196:199], v[228:231], v[66:69]
	s_barrier
	s_setprio 0
	s_add_i32 s12, s39, s21
	s_mov_b32 m0, s12
	ds_read_b128 v[200:203], v163 offset:16384
	ds_read_b128 v[204:207], v163 offset:17408
	ds_read_b128 v[208:211], v163 offset:18432
	ds_read_b128 v[212:215], v163 offset:19456
	ds_read_b128 v[216:219], v163 offset:20480
	ds_read_b128 v[220:223], v163 offset:21504
	ds_read_b128 v[224:227], v163 offset:22528
	ds_read_b128 v[228:231], v163 offset:23552
	global_load_lds_dwordx4 v134, s[16:17]
	s_add_i32 m0, s12, 0x2000
	s_add_u32 s12, s16, 0x44000
	s_addc_u32 s13, s17, 0
	s_add_i32 s39, s40, s21
	global_load_lds_dwordx4 v130, s[16:17]
	s_mov_b32 m0, s39
	s_nop 0
	global_load_lds_dwordx4 v134, s[12:13]
	s_add_i32 m0, s39, 0x2000
	s_nop 0
	global_load_lds_dwordx4 v130, s[12:13]
	s_mov_b32 m0, s23
	s_nop 0
	global_load_lds_dwordx4 v154, s[18:19]
	s_mov_b32 m0, s24
	s_nop 0
	global_load_lds_dwordx4 v132, s[18:19]
	s_waitcnt vmcnt(8)
	s_waitcnt lgkmcnt(0)
	s_setprio 1
	s_barrier
	v_mfma_f32_16x16x32_bf16 v[62:65], v[164:167], v[200:203], v[62:65]
	v_mfma_f32_16x16x32_bf16 v[54:57], v[172:175], v[200:203], v[54:57]
	v_mfma_f32_16x16x32_bf16 v[46:49], v[164:167], v[208:211], v[46:49]
	v_mfma_f32_16x16x32_bf16 v[38:41], v[172:175], v[208:211], v[38:41]
	v_mfma_f32_16x16x32_bf16 v[30:33], v[164:167], v[216:219], v[30:33]
	v_mfma_f32_16x16x32_bf16 v[22:25], v[172:175], v[216:219], v[22:25]
	v_mfma_f32_16x16x32_bf16 v[14:17], v[164:167], v[224:227], v[14:17]
	v_mfma_f32_16x16x32_bf16 v[6:9], v[172:175], v[224:227], v[6:9]
	v_mfma_f32_16x16x32_bf16 v[62:65], v[168:171], v[204:207], v[62:65]
	v_mfma_f32_16x16x32_bf16 v[54:57], v[176:179], v[204:207], v[54:57]
	v_mfma_f32_16x16x32_bf16 v[46:49], v[168:171], v[212:215], v[46:49]
	v_mfma_f32_16x16x32_bf16 v[38:41], v[176:179], v[212:215], v[38:41]
	v_mfma_f32_16x16x32_bf16 v[30:33], v[168:171], v[220:223], v[30:33]
	v_mfma_f32_16x16x32_bf16 v[22:25], v[176:179], v[220:223], v[22:25]
	v_mfma_f32_16x16x32_bf16 v[14:17], v[168:171], v[228:231], v[14:17]
	v_mfma_f32_16x16x32_bf16 v[6:9], v[176:179], v[228:231], v[6:9]
	v_mfma_f32_16x16x32_bf16 v[58:61], v[184:187], v[200:203], v[58:61]
	v_mfma_f32_16x16x32_bf16 v[50:53], v[192:195], v[200:203], v[50:53]
	v_mfma_f32_16x16x32_bf16 v[42:45], v[184:187], v[208:211], v[42:45]
	v_mfma_f32_16x16x32_bf16 v[34:37], v[192:195], v[208:211], v[34:37]
	v_mfma_f32_16x16x32_bf16 v[26:29], v[184:187], v[216:219], v[26:29]
	v_mfma_f32_16x16x32_bf16 v[18:21], v[192:195], v[216:219], v[18:21]
	v_mfma_f32_16x16x32_bf16 v[10:13], v[184:187], v[224:227], v[10:13]
	v_mfma_f32_16x16x32_bf16 v[2:5], v[192:195], v[224:227], v[2:5]
	v_mfma_f32_16x16x32_bf16 v[58:61], v[188:191], v[204:207], v[58:61]
	v_mfma_f32_16x16x32_bf16 v[50:53], v[196:199], v[204:207], v[50:53]
	v_mfma_f32_16x16x32_bf16 v[42:45], v[188:191], v[212:215], v[42:45]
	v_mfma_f32_16x16x32_bf16 v[34:37], v[196:199], v[212:215], v[34:37]
	v_mfma_f32_16x16x32_bf16 v[26:29], v[188:191], v[220:223], v[26:29]
	v_mfma_f32_16x16x32_bf16 v[18:21], v[196:199], v[220:223], v[18:21]
	v_mfma_f32_16x16x32_bf16 v[10:13], v[188:191], v[228:231], v[10:13]
	v_mfma_f32_16x16x32_bf16 v[2:5], v[196:199], v[228:231], v[2:5]
	s_barrier
; #define PG8_STAGE(bufoff, gbase, voff) do { _Pragma("unroll") for (int _i = 0; _i < 2; ++_i) \
;         __builtin_amdgcn_global_load_lds((const unsigned*)((const char*)(gbase) + (voff)[_i]), (LAS unsigned*)(lds + (bufoff) + ldsw + _i * 8192), 16, 0, 0); } while (0)
; #define PG8_LDA(dst, b, h) do { _Pragma("unroll") for (int m = 0; m < 4; ++m) _Pragma("unroll") for (int k = 0; k < 2; ++k) dst[m][k] = *(const LAS bf16x8*)(lds + PG8_SA(b, h) + aoff + m * 2048 + k * 1024); } while (0)
; #define PG8_LDB(dst, b, h) do { _Pragma("unroll") for (int n = 0; n < 2; ++n) _Pragma("unroll") for (int k = 0; k < 2; ++k) dst[n][k] = *(const LAS bf16x8*)(lds + PG8_SB(b, h) + boff + n * 2048 + k * 1024); } while (0)
; #define PG8_MMA(ai, bj, At, Bt) do { __builtin_amdgcn_s_setprio(1); _Pragma("unroll") for (int m = 0; m < 4; ++m) _Pragma("unroll") for (int n = 0; n < 2; ++n) _Pragma("unroll") for (int k = 0; k < 2; ++k) \
;         acc[ai][bj][m][n] = __builtin_amdgcn_mfma_f32_16x16x32_bf16(Bt[n][k], At[m][k], acc[ai][bj][m][n], 0, 0, 0); __builtin_amdgcn_s_setprio(0); } while (0)
; #define PG8_WAIT_V(n) asm volatile("s_waitcnt vmcnt(" #n ")" ::: "memory")
; #define PG8_WAIT_L(n) asm volatile("s_waitcnt lgkmcnt(" #n ")" ::: "memory")
; #define PG8_BAR __builtin_amdgcn_s_barrier()
; #define PG8_SCHED __builtin_amdgcn_sched_barrier(0)
; template <class Epi, bool ALIGN_EPI = PG8_ALIGN, bool SP2 = PG8_SP2>
; __device__ __forceinline__ void gemm_phase(LAS uchar* lds, const Gemm g, const StaticOrder& S, const Epi& E) {
;     ...
;             PG8_LDB(B0, 1, 0); PG8_LDB(B1, 1, 1); PG8_SCHED; PG8_LDA(At, 1, 0); PG8_STAGE(PG8_SA(0, 1), a2 + hstepA, voffA);
;             PG8_WAIT_V(8); PG8_WAIT_L(0); PG8_BAR; PG8_MMA(0, 0, At, B0); PG8_MMA(0, 1, At, B1); PG8_BAR; PG8_SCHED;
;             PG8_LDA(At, 1, 1); PG8_STAGE(PG8_SB(1, 0), b3, voffB); PG8_STAGE(PG8_SB(1, 1), b3 + hstepB, voffB); PG8_STAGE(PG8_SA(1, 0), a3, voffA);
;             PG8_WAIT_V(8); PG8_WAIT_L(0); PG8_BAR; PG8_MMA(1, 0, At, B0); PG8_MMA(1, 1, At, B1); PG8_BAR; PG8_SCHED;
;     ...
;         if constexpr (ALIGN_EPI) { if (wr == 0) PG8_BAR; }
	s_setprio 0
	s_add_i32 s39, 0, 0x18000
	v_add_u32_e32 v144, s39, v139
	s_add_i32 s40, 0, 0x1c000
	ds_read_b128 v[164:167], v144
	ds_read_b128 v[168:171], v144 offset:1024
	ds_read_b128 v[172:175], v144 offset:2048
	ds_read_b128 v[176:179], v144 offset:3072
	v_add_u32_e32 v144, s40, v139
	ds_read_b128 v[184:187], v144
	ds_read_b128 v[188:191], v144 offset:1024
	ds_read_b128 v[192:195], v144 offset:2048
	ds_read_b128 v[196:199], v144 offset:3072
	s_add_u32 s12, s18, 0x44000
	s_addc_u32 s13, s19, 0
	s_mov_b32 m0, s25
	ds_read_b128 v[200:203], v163 offset:32768
	ds_read_b128 v[204:207], v163 offset:33792
	ds_read_b128 v[208:211], v163 offset:34816
	ds_read_b128 v[212:215], v163 offset:35840
	ds_read_b128 v[216:219], v163 offset:36864
	ds_read_b128 v[220:223], v163 offset:37888
	ds_read_b128 v[224:227], v163 offset:38912
	ds_read_b128 v[228:231], v163 offset:39936
	global_load_lds_dwordx4 v154, s[12:13]
	s_mov_b32 m0, s26
	s_nop 0
	global_load_lds_dwordx4 v132, s[12:13]
	s_waitcnt vmcnt(8)
	s_waitcnt lgkmcnt(0)
	s_setprio 1
	s_barrier
	v_mfma_f32_16x16x32_bf16 v[126:129], v[164:167], v[200:203], v[126:129]
	v_mfma_f32_16x16x32_bf16 v[118:121], v[172:175], v[200:203], v[118:121]
	v_mfma_f32_16x16x32_bf16 v[110:113], v[164:167], v[208:211], v[110:113]
	v_mfma_f32_16x16x32_bf16 v[102:105], v[172:175], v[208:211], v[102:105]
	v_mfma_f32_16x16x32_bf16 v[94:97], v[164:167], v[216:219], v[94:97]
	v_mfma_f32_16x16x32_bf16 v[86:89], v[172:175], v[216:219], v[86:89]
	v_mfma_f32_16x16x32_bf16 v[78:81], v[164:167], v[224:227], v[78:81]
	v_mfma_f32_16x16x32_bf16 v[70:73], v[172:175], v[224:227], v[70:73]
	v_mfma_f32_16x16x32_bf16 v[126:129], v[168:171], v[204:207], v[126:129]
	v_mfma_f32_16x16x32_bf16 v[118:121], v[176:179], v[204:207], v[118:121]
	v_mfma_f32_16x16x32_bf16 v[110:113], v[168:171], v[212:215], v[110:113]
	v_mfma_f32_16x16x32_bf16 v[102:105], v[176:179], v[212:215], v[102:105]
	v_mfma_f32_16x16x32_bf16 v[94:97], v[168:171], v[220:223], v[94:97]
	v_mfma_f32_16x16x32_bf16 v[86:89], v[176:179], v[220:223], v[86:89]
	v_mfma_f32_16x16x32_bf16 v[78:81], v[168:171], v[228:231], v[78:81]
	v_mfma_f32_16x16x32_bf16 v[70:73], v[176:179], v[228:231], v[70:73]
	v_mfma_f32_16x16x32_bf16 v[122:125], v[184:187], v[200:203], v[122:125]
	v_mfma_f32_16x16x32_bf16 v[114:117], v[192:195], v[200:203], v[114:117]
	v_mfma_f32_16x16x32_bf16 v[106:109], v[184:187], v[208:211], v[106:109]
	v_mfma_f32_16x16x32_bf16 v[98:101], v[192:195], v[208:211], v[98:101]
	v_mfma_f32_16x16x32_bf16 v[90:93], v[184:187], v[216:219], v[90:93]
	v_mfma_f32_16x16x32_bf16 v[82:85], v[192:195], v[216:219], v[82:85]
	v_mfma_f32_16x16x32_bf16 v[74:77], v[184:187], v[224:227], v[74:77]
	v_mfma_f32_16x16x32_bf16 v[66:69], v[192:195], v[224:227], v[66:69]
	v_mfma_f32_16x16x32_bf16 v[122:125], v[188:191], v[204:207], v[122:125]
	v_mfma_f32_16x16x32_bf16 v[114:117], v[196:199], v[204:207], v[114:117]
	v_mfma_f32_16x16x32_bf16 v[106:109], v[188:191], v[212:215], v[106:109]
	v_mfma_f32_16x16x32_bf16 v[98:101], v[196:199], v[212:215], v[98:101]
	v_mfma_f32_16x16x32_bf16 v[90:93], v[188:191], v[220:223], v[90:93]
	v_mfma_f32_16x16x32_bf16 v[82:85], v[196:199], v[220:223], v[82:85]
	v_mfma_f32_16x16x32_bf16 v[74:77], v[188:191], v[228:231], v[74:77]
	v_mfma_f32_16x16x32_bf16 v[66:69], v[196:199], v[228:231], v[66:69]
	s_barrier
	s_setprio 0
	s_add_i32 s12, s39, s21
	s_add_i32 m0, s12, 0xffffff80
	ds_read_b128 v[200:203], v163 offset:49152
	ds_read_b128 v[204:207], v163 offset:50176
	ds_read_b128 v[208:211], v163 offset:51200
	ds_read_b128 v[212:215], v163 offset:52224
	ds_read_b128 v[216:219], v163 offset:53248
	ds_read_b128 v[220:223], v163 offset:54272
	ds_read_b128 v[224:227], v163 offset:55296
	ds_read_b128 v[228:231], v163 offset:56320
	global_load_lds_dwordx4 v134, s[16:17] offset:128
	s_add_i32 m0, s12, 0x1f80
	s_add_u32 s12, s16, 0x44080
	s_addc_u32 s13, s17, 0
	global_load_lds_dwordx4 v130, s[16:17] offset:128
	s_add_i32 s16, s40, s21
	s_mov_b32 m0, s16
	s_nop 0
	global_load_lds_dwordx4 v134, s[12:13]
	s_add_i32 m0, s16, 0x2000
	s_nop 0
	global_load_lds_dwordx4 v130, s[12:13]
	s_add_i32 m0, s27, 0xffffff80
	s_nop 0
	global_load_lds_dwordx4 v154, s[18:19] offset:128
	s_add_i32 m0, s28, 0xffffff80
	s_nop 0
	global_load_lds_dwordx4 v132, s[18:19] offset:128
	s_waitcnt vmcnt(8)
	s_waitcnt lgkmcnt(0)
	s_setprio 1
	s_barrier
	v_mfma_f32_16x16x32_bf16 v[62:65], v[164:167], v[200:203], v[62:65]
	v_mfma_f32_16x16x32_bf16 v[54:57], v[172:175], v[200:203], v[54:57]
	v_mfma_f32_16x16x32_bf16 v[46:49], v[164:167], v[208:211], v[46:49]
	v_mfma_f32_16x16x32_bf16 v[38:41], v[172:175], v[208:211], v[38:41]
	v_mfma_f32_16x16x32_bf16 v[30:33], v[164:167], v[216:219], v[30:33]
	v_mfma_f32_16x16x32_bf16 v[22:25], v[172:175], v[216:219], v[22:25]
	v_mfma_f32_16x16x32_bf16 v[14:17], v[164:167], v[224:227], v[14:17]
	v_mfma_f32_16x16x32_bf16 v[6:9], v[172:175], v[224:227], v[6:9]
	v_mfma_f32_16x16x32_bf16 v[62:65], v[168:171], v[204:207], v[62:65]
	v_mfma_f32_16x16x32_bf16 v[54:57], v[176:179], v[204:207], v[54:57]
	v_mfma_f32_16x16x32_bf16 v[46:49], v[168:171], v[212:215], v[46:49]
	v_mfma_f32_16x16x32_bf16 v[38:41], v[176:179], v[212:215], v[38:41]
	v_mfma_f32_16x16x32_bf16 v[30:33], v[168:171], v[220:223], v[30:33]
	v_mfma_f32_16x16x32_bf16 v[22:25], v[176:179], v[220:223], v[22:25]
	v_mfma_f32_16x16x32_bf16 v[14:17], v[168:171], v[228:231], v[14:17]
	v_mfma_f32_16x16x32_bf16 v[6:9], v[176:179], v[228:231], v[6:9]
	v_mfma_f32_16x16x32_bf16 v[58:61], v[184:187], v[200:203], v[58:61]
	v_mfma_f32_16x16x32_bf16 v[50:53], v[192:195], v[200:203], v[50:53]
	v_mfma_f32_16x16x32_bf16 v[42:45], v[184:187], v[208:211], v[42:45]
	v_mfma_f32_16x16x32_bf16 v[34:37], v[192:195], v[208:211], v[34:37]
	v_mfma_f32_16x16x32_bf16 v[26:29], v[184:187], v[216:219], v[26:29]
	v_mfma_f32_16x16x32_bf16 v[18:21], v[192:195], v[216:219], v[18:21]
	v_mfma_f32_16x16x32_bf16 v[10:13], v[184:187], v[224:227], v[10:13]
	v_mfma_f32_16x16x32_bf16 v[2:5], v[192:195], v[224:227], v[2:5]
	v_mfma_f32_16x16x32_bf16 v[58:61], v[188:191], v[204:207], v[58:61]
	v_mfma_f32_16x16x32_bf16 v[50:53], v[196:199], v[204:207], v[50:53]
	v_mfma_f32_16x16x32_bf16 v[42:45], v[188:191], v[212:215], v[42:45]
	v_mfma_f32_16x16x32_bf16 v[34:37], v[196:199], v[212:215], v[34:37]
	v_mfma_f32_16x16x32_bf16 v[26:29], v[188:191], v[220:223], v[26:29]
	v_mfma_f32_16x16x32_bf16 v[18:21], v[196:199], v[220:223], v[18:21]
	v_mfma_f32_16x16x32_bf16 v[10:13], v[188:191], v[228:231], v[10:13]
	v_mfma_f32_16x16x32_bf16 v[2:5], v[196:199], v[228:231], v[2:5]
	s_barrier
	s_setprio 0
	s_add_i32 s38, s38, 2
	s_add_u32 s36, s36, 0x100
	s_addc_u32 s37, s37, 0
	s_cmp_gt_u32 s38, 13
	s_mov_b64 s[12:13], s[14:15]
	s_cbranch_scc0 .LBB0_1050
	s_and_b64 vcc, exec, s[8:9]
	s_cbranch_vccz .LBB0_1053
	s_barrier

; #define PG8_STAGE(bufoff, gbase, voff) do { _Pragma("unroll") for (int _i = 0; _i < 2; ++_i) \
;         __builtin_amdgcn_global_load_lds((const unsigned*)((const char*)(gbase) + (voff)[_i]), (LAS unsigned*)(lds + (bufoff) + ldsw + _i * 8192), 16, 0, 0); } while (0)
; #define PG8_LDA(dst, b, h) do { _Pragma("unroll") for (int m = 0; m < 4; ++m) _Pragma("unroll") for (int k = 0; k < 2; ++k) dst[m][k] = *(const LAS bf16x8*)(lds + PG8_SA(b, h) + aoff + m * 2048 + k * 1024); } while (0)
; #define PG8_LDB(dst, b, h) do { _Pragma("unroll") for (int n = 0; n < 2; ++n) _Pragma("unroll") for (int k = 0; k < 2; ++k) dst[n][k] = *(const LAS bf16x8*)(lds + PG8_SB(b, h) + boff + n * 2048 + k * 1024); } while (0)
; #define PG8_MMA(ai, bj, At, Bt) do { __builtin_amdgcn_s_setprio(1); _Pragma("unroll") for (int m = 0; m < 4; ++m) _Pragma("unroll") for (int n = 0; n < 2; ++n) _Pragma("unroll") for (int k = 0; k < 2; ++k) \
;         acc[ai][bj][m][n] = __builtin_amdgcn_mfma_f32_16x16x32_bf16(Bt[n][k], At[m][k], acc[ai][bj][m][n], 0, 0, 0); __builtin_amdgcn_s_setprio(0); } while (0)
; #define PG8_WAIT_V(n) asm volatile("s_waitcnt vmcnt(" #n ")" ::: "memory")
; #define PG8_WAIT_L(n) asm volatile("s_waitcnt lgkmcnt(" #n ")" ::: "memory")
; #define PG8_BAR __builtin_amdgcn_s_barrier()
; template <class Epi, bool ALIGN_EPI = PG8_ALIGN, bool SP2 = PG8_SP2>
; __device__ __forceinline__ void gemm_phase(LAS uchar* lds, const Gemm g, const StaticOrder& S, const Epi& E) {
;     ...
;         for (int t = tb; t < tb + tblk; t += 2) {
;             const bool last = (t == nt - 2);
;             const char* a1 = cA + (size_t)(t + 1) * kstep;
;             const char* a2 = last ? nA : cA + (size_t)(t + 2) * kstep; const char* b2 = last ? nB : cB + (size_t)(t + 2) * kstep;
;             const char* a3 = a2 + kstep; const char* b3 = b2 + kstep;
;             if constexpr (SP2) {
;             PG8_LDB(B0, 0, 0); PG8_LDB(B1, 0, 1); PG8_SCHED; PG8_LDA(At, 0, 0); PG8_STAGE(PG8_SA(1, 1), a1 + hstepA, voffA);
;             PG8_WAIT_V(8); PG8_WAIT_L(0); PG8_BAR; PG8_MMA(0, 0, At, B0); PG8_MMA(0, 1, At, B1); PG8_BAR; PG8_SCHED;
;             PG8_LDA(At, 0, 1); PG8_STAGE(PG8_SB(0, 0), b2, voffB); PG8_STAGE(PG8_SB(0, 1), b2 + hstepB, voffB); PG8_STAGE(PG8_SA(0, 0), a2, voffA);
;             PG8_WAIT_V(8); PG8_WAIT_L(0); PG8_BAR; PG8_MMA(1, 0, At, B0); PG8_MMA(1, 1, At, B1); PG8_BAR; PG8_SCHED;
.LBB0_1142:
	s_add_u32 s38, s16, 0x100
	s_addc_u32 s39, s17, 0
	s_mov_b32 s40, -2
	s_add_u32 s16, s14, 0x100
	s_addc_u32 s17, s15, 0
	s_add_i32 s41, 0, 0x10000
	s_cmp_eq_u32 s40, 40
	s_cselect_b32 s21, s5, s17
	s_cselect_b32 s20, s4, s16
	v_add_u32_e32 v144, s41, v139
	s_cselect_b32 s19, s13, s39
	s_cselect_b32 s18, s12, s38
	s_add_i32 s42, 0, 0x14000
	ds_read_b128 v[160:163], v144
	ds_read_b128 v[166:169], v144 offset:1024
	ds_read_b128 v[170:173], v144 offset:2048
	ds_read_b128 v[174:177], v144 offset:3072
	v_add_u32_e32 v144, s42, v139
	ds_read_b128 v[178:181], v144
	ds_read_b128 v[184:187], v144 offset:1024
	ds_read_b128 v[188:191], v144 offset:2048
	ds_read_b128 v[192:195], v144 offset:3072
	s_add_i32 m0, s25, 0xc000
	ds_read_b128 v[196:199], v165
	ds_read_b128 v[200:203], v165 offset:1024
	ds_read_b128 v[204:207], v165 offset:2048
	ds_read_b128 v[208:211], v165 offset:3072
	ds_read_b128 v[212:215], v165 offset:4096
	ds_read_b128 v[216:219], v165 offset:5120
	ds_read_b128 v[220:223], v165 offset:6144
	ds_read_b128 v[224:227], v165 offset:7168
	global_load_lds_dwordx4 v156, s[14:15]
	s_add_i32 m0, s25, 0xe000
	s_nop 0
	global_load_lds_dwordx4 v158, s[14:15]
	s_waitcnt vmcnt(8)
	s_waitcnt lgkmcnt(0)
	s_setprio 1
	s_barrier
	v_mfma_f32_16x16x32_bf16 v[126:129], v[160:163], v[196:199], 0
	v_mfma_f32_16x16x32_bf16 v[122:125], v[170:173], v[196:199], 0
	v_mfma_f32_16x16x32_bf16 v[118:121], v[160:163], v[204:207], 0
	v_mfma_f32_16x16x32_bf16 v[110:113], v[170:173], v[204:207], 0
	v_mfma_f32_16x16x32_bf16 v[102:105], v[160:163], v[212:215], 0
	v_mfma_f32_16x16x32_bf16 v[94:97], v[170:173], v[212:215], 0
	v_mfma_f32_16x16x32_bf16 v[86:89], v[160:163], v[220:223], 0
	v_mfma_f32_16x16x32_bf16 v[78:81], v[170:173], v[220:223], 0
	v_mfma_f32_16x16x32_bf16 v[126:129], v[166:169], v[200:203], v[126:129]
	v_mfma_f32_16x16x32_bf16 v[122:125], v[174:177], v[200:203], v[122:125]
	v_mfma_f32_16x16x32_bf16 v[118:121], v[166:169], v[208:211], v[118:121]
	v_mfma_f32_16x16x32_bf16 v[110:113], v[174:177], v[208:211], v[110:113]
	v_mfma_f32_16x16x32_bf16 v[102:105], v[166:169], v[216:219], v[102:105]
	v_mfma_f32_16x16x32_bf16 v[94:97], v[174:177], v[216:219], v[94:97]
	v_mfma_f32_16x16x32_bf16 v[86:89], v[166:169], v[224:227], v[86:89]
	v_mfma_f32_16x16x32_bf16 v[78:81], v[174:177], v[224:227], v[78:81]
	v_mfma_f32_16x16x32_bf16 v[114:117], v[178:181], v[196:199], 0
	v_mfma_f32_16x16x32_bf16 v[106:109], v[188:191], v[196:199], 0
	v_mfma_f32_16x16x32_bf16 v[98:101], v[178:181], v[204:207], 0
	v_mfma_f32_16x16x32_bf16 v[90:93], v[188:191], v[204:207], 0
	v_mfma_f32_16x16x32_bf16 v[82:85], v[178:181], v[212:215], 0
	v_mfma_f32_16x16x32_bf16 v[74:77], v[188:191], v[212:215], 0
	v_mfma_f32_16x16x32_bf16 v[70:73], v[178:181], v[220:223], 0
	v_mfma_f32_16x16x32_bf16 v[66:69], v[188:191], v[220:223], 0
	v_mfma_f32_16x16x32_bf16 v[114:117], v[184:187], v[200:203], v[114:117]
	v_mfma_f32_16x16x32_bf16 v[106:109], v[192:195], v[200:203], v[106:109]
	v_mfma_f32_16x16x32_bf16 v[98:101], v[184:187], v[208:211], v[98:101]
	v_mfma_f32_16x16x32_bf16 v[90:93], v[192:195], v[208:211], v[90:93]
	v_mfma_f32_16x16x32_bf16 v[82:85], v[184:187], v[216:219], v[82:85]
	v_mfma_f32_16x16x32_bf16 v[74:77], v[192:195], v[216:219], v[74:77]
	v_mfma_f32_16x16x32_bf16 v[70:73], v[184:187], v[224:227], v[70:73]
	v_mfma_f32_16x16x32_bf16 v[66:69], v[192:195], v[224:227], v[66:69]
	s_barrier
	s_setprio 0
	s_add_i32 s14, s41, s24
	s_mov_b32 m0, s14
	ds_read_b128 v[196:199], v165 offset:16384
	ds_read_b128 v[200:203], v165 offset:17408
	ds_read_b128 v[204:207], v165 offset:18432
	ds_read_b128 v[208:211], v165 offset:19456
	ds_read_b128 v[212:215], v165 offset:20480
	ds_read_b128 v[216:219], v165 offset:21504
	ds_read_b128 v[220:223], v165 offset:22528
	ds_read_b128 v[224:227], v165 offset:23552
	global_load_lds_dwordx4 v132, s[18:19]
	s_add_i32 m0, s14, 0x2000
	s_add_u32 s14, s18, 0xb0000
	s_addc_u32 s15, s19, 0
	s_add_i32 s41, s42, s24
	global_load_lds_dwordx4 v154, s[18:19]
	s_mov_b32 m0, s41
	s_nop 0
	global_load_lds_dwordx4 v132, s[14:15]
	s_add_i32 m0, s41, 0x2000
	s_nop 0
	global_load_lds_dwordx4 v154, s[14:15]
	s_mov_b32 m0, s25
	s_nop 0
	global_load_lds_dwordx4 v130, s[20:21]
	s_mov_b32 m0, s26
	s_nop 0
	global_load_lds_dwordx4 v134, s[20:21]
	s_waitcnt vmcnt(8)
	s_waitcnt lgkmcnt(0)
	s_setprio 1
	s_barrier
	v_mfma_f32_16x16x32_bf16 v[62:65], v[160:163], v[196:199], 0
	v_mfma_f32_16x16x32_bf16 v[58:61], v[170:173], v[196:199], 0
	v_mfma_f32_16x16x32_bf16 v[54:57], v[160:163], v[204:207], 0
	v_mfma_f32_16x16x32_bf16 v[46:49], v[170:173], v[204:207], 0
	v_mfma_f32_16x16x32_bf16 v[38:41], v[160:163], v[212:215], 0
	v_mfma_f32_16x16x32_bf16 v[30:33], v[170:173], v[212:215], 0
	v_mfma_f32_16x16x32_bf16 v[22:25], v[160:163], v[220:223], 0
	v_mfma_f32_16x16x32_bf16 v[14:17], v[170:173], v[220:223], 0
	v_mfma_f32_16x16x32_bf16 v[62:65], v[166:169], v[200:203], v[62:65]
	v_mfma_f32_16x16x32_bf16 v[58:61], v[174:177], v[200:203], v[58:61]
	v_mfma_f32_16x16x32_bf16 v[54:57], v[166:169], v[208:211], v[54:57]
	v_mfma_f32_16x16x32_bf16 v[46:49], v[174:177], v[208:211], v[46:49]
	v_mfma_f32_16x16x32_bf16 v[38:41], v[166:169], v[216:219], v[38:41]
	v_mfma_f32_16x16x32_bf16 v[30:33], v[174:177], v[216:219], v[30:33]
	v_mfma_f32_16x16x32_bf16 v[22:25], v[166:169], v[224:227], v[22:25]
	v_mfma_f32_16x16x32_bf16 v[14:17], v[174:177], v[224:227], v[14:17]
	v_mfma_f32_16x16x32_bf16 v[50:53], v[178:181], v[196:199], 0
	v_mfma_f32_16x16x32_bf16 v[42:45], v[188:191], v[196:199], 0
	v_mfma_f32_16x16x32_bf16 v[34:37], v[178:181], v[204:207], 0
	v_mfma_f32_16x16x32_bf16 v[26:29], v[188:191], v[204:207], 0
	v_mfma_f32_16x16x32_bf16 v[18:21], v[178:181], v[212:215], 0
	v_mfma_f32_16x16x32_bf16 v[10:13], v[188:191], v[212:215], 0
	v_mfma_f32_16x16x32_bf16 v[6:9], v[178:181], v[220:223], 0
	v_mfma_f32_16x16x32_bf16 v[2:5], v[188:191], v[220:223], 0
	v_mfma_f32_16x16x32_bf16 v[50:53], v[184:187], v[200:203], v[50:53]
	v_mfma_f32_16x16x32_bf16 v[42:45], v[192:195], v[200:203], v[42:45]
	v_mfma_f32_16x16x32_bf16 v[34:37], v[184:187], v[208:211], v[34:37]
	v_mfma_f32_16x16x32_bf16 v[26:29], v[192:195], v[208:211], v[26:29]
	v_mfma_f32_16x16x32_bf16 v[18:21], v[184:187], v[216:219], v[18:21]
	v_mfma_f32_16x16x32_bf16 v[10:13], v[192:195], v[216:219], v[10:13]
	v_mfma_f32_16x16x32_bf16 v[6:9], v[184:187], v[224:227], v[6:9]
	v_mfma_f32_16x16x32_bf16 v[2:5], v[192:195], v[224:227], v[2:5]
	s_barrier
; #define PG8_STAGE(bufoff, gbase, voff) do { _Pragma("unroll") for (int _i = 0; _i < 2; ++_i) \
;         __builtin_amdgcn_global_load_lds((const unsigned*)((const char*)(gbase) + (voff)[_i]), (LAS unsigned*)(lds + (bufoff) + ldsw + _i * 8192), 16, 0, 0); } while (0)
; #define PG8_LDA(dst, b, h) do { _Pragma("unroll") for (int m = 0; m < 4; ++m) _Pragma("unroll") for (int k = 0; k < 2; ++k) dst[m][k] = *(const LAS bf16x8*)(lds + PG8_SA(b, h) + aoff + m * 2048 + k * 1024); } while (0)
; #define PG8_LDB(dst, b, h) do { _Pragma("unroll") for (int n = 0; n < 2; ++n) _Pragma("unroll") for (int k = 0; k < 2; ++k) dst[n][k] = *(const LAS bf16x8*)(lds + PG8_SB(b, h) + boff + n * 2048 + k * 1024); } while (0)
; #define PG8_MMA(ai, bj, At, Bt) do { __builtin_amdgcn_s_setprio(1); _Pragma("unroll") for (int m = 0; m < 4; ++m) _Pragma("unroll") for (int n = 0; n < 2; ++n) _Pragma("unroll") for (int k = 0; k < 2; ++k) \
;         acc[ai][bj][m][n] = __builtin_amdgcn_mfma_f32_16x16x32_bf16(Bt[n][k], At[m][k], acc[ai][bj][m][n], 0, 0, 0); __builtin_amdgcn_s_setprio(0); } while (0)
; #define PG8_WAIT_V(n) asm volatile("s_waitcnt vmcnt(" #n ")" ::: "memory")
; #define PG8_WAIT_L(n) asm volatile("s_waitcnt lgkmcnt(" #n ")" ::: "memory")
; #define PG8_BAR __builtin_amdgcn_s_barrier()
; #define PG8_SCHED __builtin_amdgcn_sched_barrier(0)
; template <class Epi, bool ALIGN_EPI = PG8_ALIGN, bool SP2 = PG8_SP2>
; __device__ __forceinline__ void gemm_phase(LAS uchar* lds, const Gemm g, const StaticOrder& S, const Epi& E) {
;     ...
;             PG8_LDB(B0, 1, 0); PG8_LDB(B1, 1, 1); PG8_SCHED; PG8_LDA(At, 1, 0); PG8_STAGE(PG8_SA(0, 1), a2 + hstepA, voffA);
;             PG8_WAIT_V(8); PG8_WAIT_L(0); PG8_BAR; PG8_MMA(0, 0, At, B0); PG8_MMA(0, 1, At, B1); PG8_BAR; PG8_SCHED;
;             PG8_LDA(At, 1, 1); PG8_STAGE(PG8_SB(1, 0), b3, voffB); PG8_STAGE(PG8_SB(1, 1), b3 + hstepB, voffB); PG8_STAGE(PG8_SA(1, 0), a3, voffA);
;             PG8_WAIT_V(8); PG8_WAIT_L(0); PG8_BAR; PG8_MMA(1, 0, At, B0); PG8_MMA(1, 1, At, B1); PG8_BAR; PG8_SCHED;
	s_setprio 0
	s_add_i32 s41, 0, 0x18000
	v_add_u32_e32 v144, s41, v139
	s_add_i32 s42, 0, 0x1c000
	ds_read_b128 v[160:163], v144
	ds_read_b128 v[166:169], v144 offset:1024
	ds_read_b128 v[170:173], v144 offset:2048
	ds_read_b128 v[174:177], v144 offset:3072
	v_add_u32_e32 v144, s42, v139
	ds_read_b128 v[178:181], v144
	ds_read_b128 v[184:187], v144 offset:1024
	ds_read_b128 v[188:191], v144 offset:2048
	ds_read_b128 v[192:195], v144 offset:3072
	s_add_u32 s14, s20, 0xb0000
	s_addc_u32 s15, s21, 0
	s_mov_b32 m0, s27
	ds_read_b128 v[196:199], v165 offset:32768
	ds_read_b128 v[200:203], v165 offset:33792
	ds_read_b128 v[204:207], v165 offset:34816
	ds_read_b128 v[208:211], v165 offset:35840
	ds_read_b128 v[212:215], v165 offset:36864
	ds_read_b128 v[216:219], v165 offset:37888
	ds_read_b128 v[220:223], v165 offset:38912
	ds_read_b128 v[224:227], v165 offset:39936
	global_load_lds_dwordx4 v130, s[14:15]
	s_mov_b32 m0, s28
	s_nop 0
	global_load_lds_dwordx4 v134, s[14:15]
	s_waitcnt vmcnt(8)
	s_waitcnt lgkmcnt(0)
	s_setprio 1
	s_barrier
	v_mfma_f32_16x16x32_bf16 v[126:129], v[160:163], v[196:199], v[126:129]
	v_mfma_f32_16x16x32_bf16 v[122:125], v[170:173], v[196:199], v[122:125]
	v_mfma_f32_16x16x32_bf16 v[118:121], v[160:163], v[204:207], v[118:121]
	v_mfma_f32_16x16x32_bf16 v[110:113], v[170:173], v[204:207], v[110:113]
	v_mfma_f32_16x16x32_bf16 v[102:105], v[160:163], v[212:215], v[102:105]
	v_mfma_f32_16x16x32_bf16 v[94:97], v[170:173], v[212:215], v[94:97]
	v_mfma_f32_16x16x32_bf16 v[86:89], v[160:163], v[220:223], v[86:89]
	v_mfma_f32_16x16x32_bf16 v[78:81], v[170:173], v[220:223], v[78:81]
	v_mfma_f32_16x16x32_bf16 v[126:129], v[166:169], v[200:203], v[126:129]
	v_mfma_f32_16x16x32_bf16 v[122:125], v[174:177], v[200:203], v[122:125]
	v_mfma_f32_16x16x32_bf16 v[118:121], v[166:169], v[208:211], v[118:121]
	v_mfma_f32_16x16x32_bf16 v[110:113], v[174:177], v[208:211], v[110:113]
	v_mfma_f32_16x16x32_bf16 v[102:105], v[166:169], v[216:219], v[102:105]
	v_mfma_f32_16x16x32_bf16 v[94:97], v[174:177], v[216:219], v[94:97]
	v_mfma_f32_16x16x32_bf16 v[86:89], v[166:169], v[224:227], v[86:89]
	v_mfma_f32_16x16x32_bf16 v[78:81], v[174:177], v[224:227], v[78:81]
	v_mfma_f32_16x16x32_bf16 v[114:117], v[178:181], v[196:199], v[114:117]
	v_mfma_f32_16x16x32_bf16 v[106:109], v[188:191], v[196:199], v[106:109]
	v_mfma_f32_16x16x32_bf16 v[98:101], v[178:181], v[204:207], v[98:101]
	v_mfma_f32_16x16x32_bf16 v[90:93], v[188:191], v[204:207], v[90:93]
	v_mfma_f32_16x16x32_bf16 v[82:85], v[178:181], v[212:215], v[82:85]
	v_mfma_f32_16x16x32_bf16 v[74:77], v[188:191], v[212:215], v[74:77]
	v_mfma_f32_16x16x32_bf16 v[70:73], v[178:181], v[220:223], v[70:73]
	v_mfma_f32_16x16x32_bf16 v[66:69], v[188:191], v[220:223], v[66:69]
	v_mfma_f32_16x16x32_bf16 v[114:117], v[184:187], v[200:203], v[114:117]
	v_mfma_f32_16x16x32_bf16 v[106:109], v[192:195], v[200:203], v[106:109]
	v_mfma_f32_16x16x32_bf16 v[98:101], v[184:187], v[208:211], v[98:101]
	v_mfma_f32_16x16x32_bf16 v[90:93], v[192:195], v[208:211], v[90:93]
	v_mfma_f32_16x16x32_bf16 v[82:85], v[184:187], v[216:219], v[82:85]
	v_mfma_f32_16x16x32_bf16 v[74:77], v[192:195], v[216:219], v[74:77]
	v_mfma_f32_16x16x32_bf16 v[70:73], v[184:187], v[224:227], v[70:73]
	v_mfma_f32_16x16x32_bf16 v[66:69], v[192:195], v[224:227], v[66:69]
	s_barrier
	s_setprio 0
	s_add_i32 s14, s41, s24
	s_add_i32 m0, s14, 0xffffff80
	ds_read_b128 v[196:199], v165 offset:49152
	ds_read_b128 v[200:203], v165 offset:50176
	ds_read_b128 v[204:207], v165 offset:51200
	ds_read_b128 v[208:211], v165 offset:52224
	ds_read_b128 v[212:215], v165 offset:53248
	ds_read_b128 v[216:219], v165 offset:54272
	ds_read_b128 v[220:223], v165 offset:55296
	ds_read_b128 v[224:227], v165 offset:56320
	global_load_lds_dwordx4 v132, s[18:19] offset:128
	s_add_i32 m0, s14, 0x1f80
	s_add_u32 s14, s18, 0xb0080
	s_addc_u32 s15, s19, 0
	global_load_lds_dwordx4 v154, s[18:19] offset:128
	s_add_i32 s18, s42, s24
	s_mov_b32 m0, s18
	s_nop 0
	global_load_lds_dwordx4 v132, s[14:15]
	s_add_i32 m0, s18, 0x2000
	s_nop 0
	global_load_lds_dwordx4 v154, s[14:15]
	s_add_i32 m0, s29, 0xffffff80
	s_nop 0
	global_load_lds_dwordx4 v130, s[20:21] offset:128
	s_add_i32 m0, s30, 0xffffff80
	s_nop 0
	global_load_lds_dwordx4 v134, s[20:21] offset:128
	s_waitcnt vmcnt(8)
	s_waitcnt lgkmcnt(0)
	s_setprio 1
	s_barrier
	v_mfma_f32_16x16x32_bf16 v[62:65], v[160:163], v[196:199], v[62:65]
	v_mfma_f32_16x16x32_bf16 v[58:61], v[170:173], v[196:199], v[58:61]
	v_mfma_f32_16x16x32_bf16 v[54:57], v[160:163], v[204:207], v[54:57]
	v_mfma_f32_16x16x32_bf16 v[46:49], v[170:173], v[204:207], v[46:49]
	v_mfma_f32_16x16x32_bf16 v[38:41], v[160:163], v[212:215], v[38:41]
	v_mfma_f32_16x16x32_bf16 v[30:33], v[170:173], v[212:215], v[30:33]
	v_mfma_f32_16x16x32_bf16 v[22:25], v[160:163], v[220:223], v[22:25]
	v_mfma_f32_16x16x32_bf16 v[14:17], v[170:173], v[220:223], v[14:17]
	v_mfma_f32_16x16x32_bf16 v[62:65], v[166:169], v[200:203], v[62:65]
	v_mfma_f32_16x16x32_bf16 v[58:61], v[174:177], v[200:203], v[58:61]
	v_mfma_f32_16x16x32_bf16 v[54:57], v[166:169], v[208:211], v[54:57]
	v_mfma_f32_16x16x32_bf16 v[46:49], v[174:177], v[208:211], v[46:49]
	v_mfma_f32_16x16x32_bf16 v[38:41], v[166:169], v[216:219], v[38:41]
	v_mfma_f32_16x16x32_bf16 v[30:33], v[174:177], v[216:219], v[30:33]
	v_mfma_f32_16x16x32_bf16 v[22:25], v[166:169], v[224:227], v[22:25]
	v_mfma_f32_16x16x32_bf16 v[14:17], v[174:177], v[224:227], v[14:17]
	v_mfma_f32_16x16x32_bf16 v[50:53], v[178:181], v[196:199], v[50:53]
	v_mfma_f32_16x16x32_bf16 v[42:45], v[188:191], v[196:199], v[42:45]
	v_mfma_f32_16x16x32_bf16 v[34:37], v[178:181], v[204:207], v[34:37]
	v_mfma_f32_16x16x32_bf16 v[26:29], v[188:191], v[204:207], v[26:29]
	v_mfma_f32_16x16x32_bf16 v[18:21], v[178:181], v[212:215], v[18:21]
	v_mfma_f32_16x16x32_bf16 v[10:13], v[188:191], v[212:215], v[10:13]
	v_mfma_f32_16x16x32_bf16 v[6:9], v[178:181], v[220:223], v[6:9]
	v_mfma_f32_16x16x32_bf16 v[2:5], v[188:191], v[220:223], v[2:5]
	v_mfma_f32_16x16x32_bf16 v[50:53], v[184:187], v[200:203], v[50:53]
	v_mfma_f32_16x16x32_bf16 v[42:45], v[192:195], v[200:203], v[42:45]
	v_mfma_f32_16x16x32_bf16 v[34:37], v[184:187], v[208:211], v[34:37]
	v_mfma_f32_16x16x32_bf16 v[26:29], v[192:195], v[208:211], v[26:29]
	v_mfma_f32_16x16x32_bf16 v[18:21], v[184:187], v[216:219], v[18:21]
	v_mfma_f32_16x16x32_bf16 v[10:13], v[192:195], v[216:219], v[10:13]
	v_mfma_f32_16x16x32_bf16 v[6:9], v[184:187], v[224:227], v[6:9]
	v_mfma_f32_16x16x32_bf16 v[2:5], v[192:195], v[224:227], v[2:5]
	s_barrier
	s_setprio 0
	s_add_i32 s40, s40, 2
	s_add_u32 s38, s38, 0x100
	s_addc_u32 s39, s39, 0
	s_cmp_gt_u32 s40, 41
	s_mov_b64 s[14:15], s[16:17]
; #define PG8_STAGE(bufoff, gbase, voff) do { _Pragma("unroll") for (int _i = 0; _i < 2; ++_i) \
;         __builtin_amdgcn_global_load_lds((const unsigned*)((const char*)(gbase) + (voff)[_i]), (LAS unsigned*)(lds + (bufoff) + ldsw + _i * 8192), 16, 0, 0); } while (0)
; #define PG8_LDA(dst, b, h) do { _Pragma("unroll") for (int m = 0; m < 4; ++m) _Pragma("unroll") for (int k = 0; k < 2; ++k) dst[m][k] = *(const LAS bf16x8*)(lds + PG8_SA(b, h) + aoff + m * 2048 + k * 1024); } while (0)
; #define PG8_LDB(dst, b, h) do { _Pragma("unroll") for (int n = 0; n < 2; ++n) _Pragma("unroll") for (int k = 0; k < 2; ++k) dst[n][k] = *(const LAS bf16x8*)(lds + PG8_SB(b, h) + boff + n * 2048 + k * 1024); } while (0)
; #define PG8_MMA(ai, bj, At, Bt) do { __builtin_amdgcn_s_setprio(1); _Pragma("unroll") for (int m = 0; m < 4; ++m) _Pragma("unroll") for (int n = 0; n < 2; ++n) _Pragma("unroll") for (int k = 0; k < 2; ++k) \
;         acc[ai][bj][m][n] = __builtin_amdgcn_mfma_f32_16x16x32_bf16(Bt[n][k], At[m][k], acc[ai][bj][m][n], 0, 0, 0); __builtin_amdgcn_s_setprio(0); } while (0)
; #define PG8_WAIT_V(n) asm volatile("s_waitcnt vmcnt(" #n ")" ::: "memory")
; #define PG8_WAIT_L(n) asm volatile("s_waitcnt lgkmcnt(" #n ")" ::: "memory")
; #define PG8_BAR __builtin_amdgcn_s_barrier()
; #define PG8_SCHED __builtin_amdgcn_sched_barrier(0)
; template <class Epi, bool ALIGN_EPI = PG8_ALIGN, bool SP2 = PG8_SP2>
; __device__ __forceinline__ void gemm_phase(LAS uchar* lds, const Gemm g, const StaticOrder& S, const Epi& E) {
;     ...
;         for (int t = tb; t < tb + tblk; t += 2) {
;             const bool last = (t == nt - 2);
;             const char* a1 = cA + (size_t)(t + 1) * kstep;
;             const char* a2 = last ? nA : cA + (size_t)(t + 2) * kstep; const char* b2 = last ? nB : cB + (size_t)(t + 2) * kstep;
;             const char* a3 = a2 + kstep; const char* b3 = b2 + kstep;
;             if constexpr (SP2) {
;             PG8_LDB(B0, 0, 0); PG8_LDB(B1, 0, 1); PG8_SCHED; PG8_LDA(At, 0, 0); PG8_STAGE(PG8_SA(1, 1), a1 + hstepA, voffA);
;             PG8_WAIT_V(8); PG8_WAIT_L(0); PG8_BAR; PG8_MMA(0, 0, At, B0); PG8_MMA(0, 1, At, B1); PG8_BAR; PG8_SCHED;
;             PG8_LDA(At, 0, 1); PG8_STAGE(PG8_SB(0, 0), b2, voffB); PG8_STAGE(PG8_SB(0, 1), b2 + hstepB, voffB); PG8_STAGE(PG8_SA(0, 0), a2, voffA);
.LBB0_1143:
	s_add_u32 s16, s14, 0x100
	s_addc_u32 s17, s15, 0
	s_add_i32 s41, 0, 0x10000
	s_cmp_eq_u32 s40, 40
	s_cselect_b32 s21, s5, s17
	s_cselect_b32 s20, s4, s16
	v_add_u32_e32 v144, s41, v139
	s_cselect_b32 s19, s13, s39
	s_cselect_b32 s18, s12, s38
	s_add_i32 s42, 0, 0x14000
	ds_read_b128 v[160:163], v144
	ds_read_b128 v[166:169], v144 offset:1024
	ds_read_b128 v[170:173], v144 offset:2048
	ds_read_b128 v[174:177], v144 offset:3072
	v_add_u32_e32 v144, s42, v139
	ds_read_b128 v[178:181], v144
	ds_read_b128 v[184:187], v144 offset:1024
	ds_read_b128 v[188:191], v144 offset:2048
	ds_read_b128 v[192:195], v144 offset:3072
	s_add_i32 m0, s25, 0xc000
	ds_read_b128 v[196:199], v165
	ds_read_b128 v[200:203], v165 offset:1024
	ds_read_b128 v[204:207], v165 offset:2048
	ds_read_b128 v[208:211], v165 offset:3072
	ds_read_b128 v[212:215], v165 offset:4096
	ds_read_b128 v[216:219], v165 offset:5120
	ds_read_b128 v[220:223], v165 offset:6144
	ds_read_b128 v[224:227], v165 offset:7168
	global_load_lds_dwordx4 v156, s[14:15]
	s_add_i32 m0, s25, 0xe000
	s_nop 0
	global_load_lds_dwordx4 v158, s[14:15]
	s_waitcnt vmcnt(8)
	s_waitcnt lgkmcnt(0)
	s_setprio 1
	s_barrier
	v_mfma_f32_16x16x32_bf16 v[126:129], v[160:163], v[196:199], v[126:129]
	v_mfma_f32_16x16x32_bf16 v[122:125], v[170:173], v[196:199], v[122:125]
	v_mfma_f32_16x16x32_bf16 v[118:121], v[160:163], v[204:207], v[118:121]
	v_mfma_f32_16x16x32_bf16 v[110:113], v[170:173], v[204:207], v[110:113]
	v_mfma_f32_16x16x32_bf16 v[102:105], v[160:163], v[212:215], v[102:105]
	v_mfma_f32_16x16x32_bf16 v[94:97], v[170:173], v[212:215], v[94:97]
	v_mfma_f32_16x16x32_bf16 v[86:89], v[160:163], v[220:223], v[86:89]
	v_mfma_f32_16x16x32_bf16 v[78:81], v[170:173], v[220:223], v[78:81]
	v_mfma_f32_16x16x32_bf16 v[126:129], v[166:169], v[200:203], v[126:129]
	v_mfma_f32_16x16x32_bf16 v[122:125], v[174:177], v[200:203], v[122:125]
	v_mfma_f32_16x16x32_bf16 v[118:121], v[166:169], v[208:211], v[118:121]
	v_mfma_f32_16x16x32_bf16 v[110:113], v[174:177], v[208:211], v[110:113]
	v_mfma_f32_16x16x32_bf16 v[102:105], v[166:169], v[216:219], v[102:105]
	v_mfma_f32_16x16x32_bf16 v[94:97], v[174:177], v[216:219], v[94:97]
	v_mfma_f32_16x16x32_bf16 v[86:89], v[166:169], v[224:227], v[86:89]
	v_mfma_f32_16x16x32_bf16 v[78:81], v[174:177], v[224:227], v[78:81]
	v_mfma_f32_16x16x32_bf16 v[114:117], v[178:181], v[196:199], v[114:117]
	v_mfma_f32_16x16x32_bf16 v[106:109], v[188:191], v[196:199], v[106:109]
	v_mfma_f32_16x16x32_bf16 v[98:101], v[178:181], v[204:207], v[98:101]
	v_mfma_f32_16x16x32_bf16 v[90:93], v[188:191], v[204:207], v[90:93]
	v_mfma_f32_16x16x32_bf16 v[82:85], v[178:181], v[212:215], v[82:85]
	v_mfma_f32_16x16x32_bf16 v[74:77], v[188:191], v[212:215], v[74:77]
	v_mfma_f32_16x16x32_bf16 v[70:73], v[178:181], v[220:223], v[70:73]
	v_mfma_f32_16x16x32_bf16 v[66:69], v[188:191], v[220:223], v[66:69]
	v_mfma_f32_16x16x32_bf16 v[114:117], v[184:187], v[200:203], v[114:117]
	v_mfma_f32_16x16x32_bf16 v[106:109], v[192:195], v[200:203], v[106:109]
	v_mfma_f32_16x16x32_bf16 v[98:101], v[184:187], v[208:211], v[98:101]
	v_mfma_f32_16x16x32_bf16 v[90:93], v[192:195], v[208:211], v[90:93]
	v_mfma_f32_16x16x32_bf16 v[82:85], v[184:187], v[216:219], v[82:85]
	v_mfma_f32_16x16x32_bf16 v[74:77], v[192:195], v[216:219], v[74:77]
	v_mfma_f32_16x16x32_bf16 v[70:73], v[184:187], v[224:227], v[70:73]
	v_mfma_f32_16x16x32_bf16 v[66:69], v[192:195], v[224:227], v[66:69]
	s_barrier
	s_setprio 0
	s_add_i32 s14, s41, s24
	s_mov_b32 m0, s14
	ds_read_b128 v[196:199], v165 offset:16384
	ds_read_b128 v[200:203], v165 offset:17408
	ds_read_b128 v[204:207], v165 offset:18432
	ds_read_b128 v[208:211], v165 offset:19456
	ds_read_b128 v[212:215], v165 offset:20480
	ds_read_b128 v[216:219], v165 offset:21504
	ds_read_b128 v[220:223], v165 offset:22528
	ds_read_b128 v[224:227], v165 offset:23552
	global_load_lds_dwordx4 v132, s[18:19]
	s_add_i32 m0, s14, 0x2000
	s_add_u32 s14, s18, 0xb0000
	s_addc_u32 s15, s19, 0
	s_add_i32 s41, s42, s24
	global_load_lds_dwordx4 v154, s[18:19]
	s_mov_b32 m0, s41
	s_nop 0
	global_load_lds_dwordx4 v132, s[14:15]
	s_add_i32 m0, s41, 0x2000
	s_nop 0
	global_load_lds_dwordx4 v154, s[14:15]
	s_mov_b32 m0, s25
	s_nop 0
	global_load_lds_dwordx4 v130, s[20:21]
	s_mov_b32 m0, s26
	s_nop 0
	global_load_lds_dwordx4 v134, s[20:21]
	s_waitcnt vmcnt(8)
	s_waitcnt lgkmcnt(0)
	s_setprio 1
	s_barrier
	v_mfma_f32_16x16x32_bf16 v[62:65], v[160:163], v[196:199], v[62:65]
	v_mfma_f32_16x16x32_bf16 v[58:61], v[170:173], v[196:199], v[58:61]
	v_mfma_f32_16x16x32_bf16 v[54:57], v[160:163], v[204:207], v[54:57]
	v_mfma_f32_16x16x32_bf16 v[46:49], v[170:173], v[204:207], v[46:49]
	v_mfma_f32_16x16x32_bf16 v[38:41], v[160:163], v[212:215], v[38:41]
	v_mfma_f32_16x16x32_bf16 v[30:33], v[170:173], v[212:215], v[30:33]
	v_mfma_f32_16x16x32_bf16 v[22:25], v[160:163], v[220:223], v[22:25]
	v_mfma_f32_16x16x32_bf16 v[14:17], v[170:173], v[220:223], v[14:17]
	v_mfma_f32_16x16x32_bf16 v[62:65], v[166:169], v[200:203], v[62:65]
	v_mfma_f32_16x16x32_bf16 v[58:61], v[174:177], v[200:203], v[58:61]
	v_mfma_f32_16x16x32_bf16 v[54:57], v[166:169], v[208:211], v[54:57]
	v_mfma_f32_16x16x32_bf16 v[46:49], v[174:177], v[208:211], v[46:49]
	v_mfma_f32_16x16x32_bf16 v[38:41], v[166:169], v[216:219], v[38:41]
	v_mfma_f32_16x16x32_bf16 v[30:33], v[174:177], v[216:219], v[30:33]
	v_mfma_f32_16x16x32_bf16 v[22:25], v[166:169], v[224:227], v[22:25]
	v_mfma_f32_16x16x32_bf16 v[14:17], v[174:177], v[224:227], v[14:17]
	v_mfma_f32_16x16x32_bf16 v[50:53], v[178:181], v[196:199], v[50:53]
	v_mfma_f32_16x16x32_bf16 v[42:45], v[188:191], v[196:199], v[42:45]
	v_mfma_f32_16x16x32_bf16 v[34:37], v[178:181], v[204:207], v[34:37]
	v_mfma_f32_16x16x32_bf16 v[26:29], v[188:191], v[204:207], v[26:29]
	v_mfma_f32_16x16x32_bf16 v[18:21], v[178:181], v[212:215], v[18:21]
	v_mfma_f32_16x16x32_bf16 v[10:13], v[188:191], v[212:215], v[10:13]
	v_mfma_f32_16x16x32_bf16 v[6:9], v[178:181], v[220:223], v[6:9]
	v_mfma_f32_16x16x32_bf16 v[2:5], v[188:191], v[220:223], v[2:5]
	v_mfma_f32_16x16x32_bf16 v[50:53], v[184:187], v[200:203], v[50:53]
	v_mfma_f32_16x16x32_bf16 v[42:45], v[192:195], v[200:203], v[42:45]
	v_mfma_f32_16x16x32_bf16 v[34:37], v[184:187], v[208:211], v[34:37]
	v_mfma_f32_16x16x32_bf16 v[26:29], v[192:195], v[208:211], v[26:29]
	v_mfma_f32_16x16x32_bf16 v[18:21], v[184:187], v[216:219], v[18:21]
	v_mfma_f32_16x16x32_bf16 v[10:13], v[192:195], v[216:219], v[10:13]
	v_mfma_f32_16x16x32_bf16 v[6:9], v[184:187], v[224:227], v[6:9]
	v_mfma_f32_16x16x32_bf16 v[2:5], v[192:195], v[224:227], v[2:5]
	s_barrier
; #define PG8_STAGE(bufoff, gbase, voff) do { _Pragma("unroll") for (int _i = 0; _i < 2; ++_i) \
;         __builtin_amdgcn_global_load_lds((const unsigned*)((const char*)(gbase) + (voff)[_i]), (LAS unsigned*)(lds + (bufoff) + ldsw + _i * 8192), 16, 0, 0); } while (0)
; #define PG8_LDA(dst, b, h) do { _Pragma("unroll") for (int m = 0; m < 4; ++m) _Pragma("unroll") for (int k = 0; k < 2; ++k) dst[m][k] = *(const LAS bf16x8*)(lds + PG8_SA(b, h) + aoff + m * 2048 + k * 1024); } while (0)
; #define PG8_LDB(dst, b, h) do { _Pragma("unroll") for (int n = 0; n < 2; ++n) _Pragma("unroll") for (int k = 0; k < 2; ++k) dst[n][k] = *(const LAS bf16x8*)(lds + PG8_SB(b, h) + boff + n * 2048 + k * 1024); } while (0)
; #define PG8_MMA(ai, bj, At, Bt) do { __builtin_amdgcn_s_setprio(1); _Pragma("unroll") for (int m = 0; m < 4; ++m) _Pragma("unroll") for (int n = 0; n < 2; ++n) _Pragma("unroll") for (int k = 0; k < 2; ++k) \
;         acc[ai][bj][m][n] = __builtin_amdgcn_mfma_f32_16x16x32_bf16(Bt[n][k], At[m][k], acc[ai][bj][m][n], 0, 0, 0); __builtin_amdgcn_s_setprio(0); } while (0)
; #define PG8_WAIT_V(n) asm volatile("s_waitcnt vmcnt(" #n ")" ::: "memory")
; #define PG8_WAIT_L(n) asm volatile("s_waitcnt lgkmcnt(" #n ")" ::: "memory")
; #define PG8_BAR __builtin_amdgcn_s_barrier()
; template <class Epi, bool ALIGN_EPI = PG8_ALIGN, bool SP2 = PG8_SP2>
; __device__ __forceinline__ void gemm_phase(LAS uchar* lds, const Gemm g, const StaticOrder& S, const Epi& E) {
;     ...
;         for (int t = tb; t < tb + tblk; t += 2) {
;             const bool last = (t == nt - 2);
;             const char* a1 = cA + (size_t)(t + 1) * kstep;
;             const char* a2 = last ? nA : cA + (size_t)(t + 2) * kstep; const char* b2 = last ? nB : cB + (size_t)(t + 2) * kstep;
;             const char* a3 = a2 + kstep; const char* b3 = b2 + kstep;
;     ...
;             PG8_LDB(B0, 1, 0); PG8_LDB(B1, 1, 1); PG8_SCHED; PG8_LDA(At, 1, 0); PG8_STAGE(PG8_SA(0, 1), a2 + hstepA, voffA);
;             PG8_WAIT_V(8); PG8_WAIT_L(0); PG8_BAR; PG8_MMA(0, 0, At, B0); PG8_MMA(0, 1, At, B1); PG8_BAR; PG8_SCHED;
;             PG8_LDA(At, 1, 1); PG8_STAGE(PG8_SB(1, 0), b3, voffB); PG8_STAGE(PG8_SB(1, 1), b3 + hstepB, voffB); PG8_STAGE(PG8_SA(1, 0), a3, voffA);
;             PG8_WAIT_V(8); PG8_WAIT_L(0); PG8_BAR; PG8_MMA(1, 0, At, B0); PG8_MMA(1, 1, At, B1); PG8_BAR; PG8_SCHED;
	s_setprio 0
	s_add_i32 s41, 0, 0x18000
	v_add_u32_e32 v144, s41, v139
	s_add_i32 s42, 0, 0x1c000
	ds_read_b128 v[160:163], v144
	ds_read_b128 v[166:169], v144 offset:1024
	ds_read_b128 v[170:173], v144 offset:2048
	ds_read_b128 v[174:177], v144 offset:3072
	v_add_u32_e32 v144, s42, v139
	ds_read_b128 v[178:181], v144
	ds_read_b128 v[184:187], v144 offset:1024
	ds_read_b128 v[188:191], v144 offset:2048
	ds_read_b128 v[192:195], v144 offset:3072
	s_add_u32 s14, s20, 0xb0000
	s_addc_u32 s15, s21, 0
	s_mov_b32 m0, s27
	ds_read_b128 v[196:199], v165 offset:32768
	ds_read_b128 v[200:203], v165 offset:33792
	ds_read_b128 v[204:207], v165 offset:34816
	ds_read_b128 v[208:211], v165 offset:35840
	ds_read_b128 v[212:215], v165 offset:36864
	ds_read_b128 v[216:219], v165 offset:37888
	ds_read_b128 v[220:223], v165 offset:38912
	ds_read_b128 v[224:227], v165 offset:39936
	global_load_lds_dwordx4 v130, s[14:15]
	s_mov_b32 m0, s28
	s_nop 0
	global_load_lds_dwordx4 v134, s[14:15]
	s_waitcnt vmcnt(8)
	s_waitcnt lgkmcnt(0)
	s_setprio 1
	s_barrier
	v_mfma_f32_16x16x32_bf16 v[126:129], v[160:163], v[196:199], v[126:129]
	v_mfma_f32_16x16x32_bf16 v[122:125], v[170:173], v[196:199], v[122:125]
	v_mfma_f32_16x16x32_bf16 v[118:121], v[160:163], v[204:207], v[118:121]
	v_mfma_f32_16x16x32_bf16 v[110:113], v[170:173], v[204:207], v[110:113]
	v_mfma_f32_16x16x32_bf16 v[102:105], v[160:163], v[212:215], v[102:105]
	v_mfma_f32_16x16x32_bf16 v[94:97], v[170:173], v[212:215], v[94:97]
	v_mfma_f32_16x16x32_bf16 v[86:89], v[160:163], v[220:223], v[86:89]
	v_mfma_f32_16x16x32_bf16 v[78:81], v[170:173], v[220:223], v[78:81]
	v_mfma_f32_16x16x32_bf16 v[126:129], v[166:169], v[200:203], v[126:129]
	v_mfma_f32_16x16x32_bf16 v[122:125], v[174:177], v[200:203], v[122:125]
	v_mfma_f32_16x16x32_bf16 v[118:121], v[166:169], v[208:211], v[118:121]
	v_mfma_f32_16x16x32_bf16 v[110:113], v[174:177], v[208:211], v[110:113]
	v_mfma_f32_16x16x32_bf16 v[102:105], v[166:169], v[216:219], v[102:105]
	v_mfma_f32_16x16x32_bf16 v[94:97], v[174:177], v[216:219], v[94:97]
	v_mfma_f32_16x16x32_bf16 v[86:89], v[166:169], v[224:227], v[86:89]
	v_mfma_f32_16x16x32_bf16 v[78:81], v[174:177], v[224:227], v[78:81]
	v_mfma_f32_16x16x32_bf16 v[114:117], v[178:181], v[196:199], v[114:117]
	v_mfma_f32_16x16x32_bf16 v[106:109], v[188:191], v[196:199], v[106:109]
	v_mfma_f32_16x16x32_bf16 v[98:101], v[178:181], v[204:207], v[98:101]
	v_mfma_f32_16x16x32_bf16 v[90:93], v[188:191], v[204:207], v[90:93]
	v_mfma_f32_16x16x32_bf16 v[82:85], v[178:181], v[212:215], v[82:85]
	v_mfma_f32_16x16x32_bf16 v[74:77], v[188:191], v[212:215], v[74:77]
	v_mfma_f32_16x16x32_bf16 v[70:73], v[178:181], v[220:223], v[70:73]
	v_mfma_f32_16x16x32_bf16 v[66:69], v[188:191], v[220:223], v[66:69]
	v_mfma_f32_16x16x32_bf16 v[114:117], v[184:187], v[200:203], v[114:117]
	v_mfma_f32_16x16x32_bf16 v[106:109], v[192:195], v[200:203], v[106:109]
	v_mfma_f32_16x16x32_bf16 v[98:101], v[184:187], v[208:211], v[98:101]
	v_mfma_f32_16x16x32_bf16 v[90:93], v[192:195], v[208:211], v[90:93]
	v_mfma_f32_16x16x32_bf16 v[82:85], v[184:187], v[216:219], v[82:85]
	v_mfma_f32_16x16x32_bf16 v[74:77], v[192:195], v[216:219], v[74:77]
	v_mfma_f32_16x16x32_bf16 v[70:73], v[184:187], v[224:227], v[70:73]
	v_mfma_f32_16x16x32_bf16 v[66:69], v[192:195], v[224:227], v[66:69]
	s_barrier
	s_setprio 0
	s_add_i32 s14, s41, s24
	s_add_i32 m0, s14, 0xffffff80
	ds_read_b128 v[196:199], v165 offset:49152
	ds_read_b128 v[200:203], v165 offset:50176
	ds_read_b128 v[204:207], v165 offset:51200
	ds_read_b128 v[208:211], v165 offset:52224
	ds_read_b128 v[212:215], v165 offset:53248
	ds_read_b128 v[216:219], v165 offset:54272
	ds_read_b128 v[220:223], v165 offset:55296
	ds_read_b128 v[224:227], v165 offset:56320
	global_load_lds_dwordx4 v132, s[18:19] offset:128
	s_add_i32 m0, s14, 0x1f80
	s_add_u32 s14, s18, 0xb0080
	s_addc_u32 s15, s19, 0
	global_load_lds_dwordx4 v154, s[18:19] offset:128
	s_add_i32 s18, s42, s24
	s_mov_b32 m0, s18
	s_nop 0
	global_load_lds_dwordx4 v132, s[14:15]
	s_add_i32 m0, s18, 0x2000
	s_nop 0
	global_load_lds_dwordx4 v154, s[14:15]
	s_add_i32 m0, s29, 0xffffff80
	s_nop 0
	global_load_lds_dwordx4 v130, s[20:21] offset:128
	s_add_i32 m0, s30, 0xffffff80
	s_nop 0
	global_load_lds_dwordx4 v134, s[20:21] offset:128
	s_waitcnt vmcnt(8)
	s_waitcnt lgkmcnt(0)
	s_setprio 1
	s_barrier
	v_mfma_f32_16x16x32_bf16 v[62:65], v[160:163], v[196:199], v[62:65]
	v_mfma_f32_16x16x32_bf16 v[58:61], v[170:173], v[196:199], v[58:61]
	v_mfma_f32_16x16x32_bf16 v[54:57], v[160:163], v[204:207], v[54:57]
	v_mfma_f32_16x16x32_bf16 v[46:49], v[170:173], v[204:207], v[46:49]
	v_mfma_f32_16x16x32_bf16 v[38:41], v[160:163], v[212:215], v[38:41]
	v_mfma_f32_16x16x32_bf16 v[30:33], v[170:173], v[212:215], v[30:33]
	v_mfma_f32_16x16x32_bf16 v[22:25], v[160:163], v[220:223], v[22:25]
	v_mfma_f32_16x16x32_bf16 v[14:17], v[170:173], v[220:223], v[14:17]
	v_mfma_f32_16x16x32_bf16 v[62:65], v[166:169], v[200:203], v[62:65]
	v_mfma_f32_16x16x32_bf16 v[58:61], v[174:177], v[200:203], v[58:61]
	v_mfma_f32_16x16x32_bf16 v[54:57], v[166:169], v[208:211], v[54:57]
	v_mfma_f32_16x16x32_bf16 v[46:49], v[174:177], v[208:211], v[46:49]
	v_mfma_f32_16x16x32_bf16 v[38:41], v[166:169], v[216:219], v[38:41]
	v_mfma_f32_16x16x32_bf16 v[30:33], v[174:177], v[216:219], v[30:33]
	v_mfma_f32_16x16x32_bf16 v[22:25], v[166:169], v[224:227], v[22:25]
	v_mfma_f32_16x16x32_bf16 v[14:17], v[174:177], v[224:227], v[14:17]
	v_mfma_f32_16x16x32_bf16 v[50:53], v[178:181], v[196:199], v[50:53]
	v_mfma_f32_16x16x32_bf16 v[42:45], v[188:191], v[196:199], v[42:45]
	v_mfma_f32_16x16x32_bf16 v[34:37], v[178:181], v[204:207], v[34:37]
	v_mfma_f32_16x16x32_bf16 v[26:29], v[188:191], v[204:207], v[26:29]
	v_mfma_f32_16x16x32_bf16 v[18:21], v[178:181], v[212:215], v[18:21]
	v_mfma_f32_16x16x32_bf16 v[10:13], v[188:191], v[212:215], v[10:13]
	v_mfma_f32_16x16x32_bf16 v[6:9], v[178:181], v[220:223], v[6:9]
	v_mfma_f32_16x16x32_bf16 v[2:5], v[188:191], v[220:223], v[2:5]
	v_mfma_f32_16x16x32_bf16 v[50:53], v[184:187], v[200:203], v[50:53]
	v_mfma_f32_16x16x32_bf16 v[42:45], v[192:195], v[200:203], v[42:45]
	v_mfma_f32_16x16x32_bf16 v[34:37], v[184:187], v[208:211], v[34:37]
	v_mfma_f32_16x16x32_bf16 v[26:29], v[192:195], v[208:211], v[26:29]
	v_mfma_f32_16x16x32_bf16 v[18:21], v[184:187], v[216:219], v[18:21]
	v_mfma_f32_16x16x32_bf16 v[10:13], v[192:195], v[216:219], v[10:13]
	v_mfma_f32_16x16x32_bf16 v[6:9], v[184:187], v[224:227], v[6:9]
	v_mfma_f32_16x16x32_bf16 v[2:5], v[192:195], v[224:227], v[2:5]
	s_barrier
	s_setprio 0
	s_add_i32 s40, s40, 2
	s_add_u32 s38, s38, 0x100
	s_addc_u32 s39, s39, 0
	s_cmp_gt_u32 s40, 41
	s_mov_b64 s[14:15], s[16:17]
	s_cbranch_scc0 .LBB0_1143
	s_and_b64 vcc, exec, s[10:11]
	s_cbranch_vccz .LBB0_1146
	s_barrier
